# All GEMM-epilogue bf16 row stores (in-proj, MLP1, out-proj, MLP2) widened to dwordx4 via v_permlane16_swap pairing
# speedup vs baseline: 1.0454x; 1.0165x over previous
; DEVI int vhalf() { int t = threadIdx.x >> 8; t = __builtin_amdgcn_readfirstlane(t); return t; }
; #define LAS __attribute__((address_space(3)))
; DEVI void run_phase(const Params& p, int ph, char* lds, volatile int* nsa_cnt, float* p4s, bool rep) {
;   const int l = ph / PH_PER_LAYER, q = ph % PH_PER_LAYER;
;   char* hl = lds + vhalf() * LDS_HALF;
;   switch (q) {
;     case 0: phase1(p, l, hl); break;
;     case 1: phase2(p, l, lds); break;
;     case 2: phase3a(p, l, hl, rep, nsa_cnt); break;
;     case 3: phase3b(p, l, hl, nsa_cnt); break;
;     case 4: phase4(p, l, lds, p4s); break;
;     case 5: phase_resid_gemm(p, (const bfu*)(p.ws + OFF_MIX), LDX, 16, (const bfu*)(p.ws + OFF_WOUT), LDX,
;                              (l == 0) ? p.in[0] : nullptr, (float*)(p.ws + OFF_SSQB), nullptr, lds); break;
;     case 6: phase7(p, l, lds); break;
;     case 7: phase_resid_gemm(p, (const bfu*)(p.ws + OFF_HID), LDH, 64, (const bfu*)(p.ws + OFF_WM2), LDH, nullptr,
;                              (float*)(p.ws + OFF_SSQA), (l == 1) ? p.out : nullptr, lds); break;
;   }
; }
; __global__ void __launch_bounds__(512, 2) fwd_mega(Params p, int ph_lo, int ph_hi, int coop) {
;   extern __shared__ __attribute__((aligned(16))) char lds[];
;   __shared__ uint4 xb_words;
;   __shared__ int nsa_cnt_s[4];
;   __shared__ float p4_stage[768];
;   XcdBarrier xb;
;   if (coop) {
;     if (threadIdx.x == 0) xb_words = make_uint4(0u, 0u, 0u, 0u);
;     __syncthreads();
;     xb = xcd_barrier_post((unsigned*)(p.ws + OFF_BAR), (volatile LAS unsigned*)&xb_words);
;   }
;   for (int ph = ph_lo; ph < ph_hi; ++ph) {
;     run_phase(p, ph, lds, nsa_cnt_s, p4_stage, false);
.LBB0_9:
	s_add_u32 s6, s90, 0x4728000
	s_addc_u32 s7, s91, 0
	s_add_u32 s2, s90, 0x1c00000
	v_writelane_b32 v244, s2, 53
	s_addc_u32 s2, s91, 0
	v_writelane_b32 v244, s2, 54
	s_add_u32 s2, s90, 0xf508000
	s_addc_u32 s3, s91, 0
	v_writelane_b32 v244, s2, 55
	s_mov_b32 s31, 0
	v_and_b32_e32 v220, 0x3ff, v0
	v_writelane_b32 v244, s3, 56
	s_add_u32 s2, s90, 0x2528000
	v_readlane_b32 s5, v244, 0
	s_addc_u32 s3, s91, 0
	s_lshr_b32 s86, s5, 3
	s_add_u32 s0, s0, 0xe0
	s_addc_u32 s1, s1, 0
	v_writelane_b32 v244, s0, 57
	s_cmpk_lt_u32 s5, 0x100
	v_and_b32_e32 v221, 0xff, v0
	v_writelane_b32 v244, s1, 58
	s_cselect_b64 s[0:1], -1, 0
	v_writelane_b32 v244, s0, 59
	v_and_b32_e32 v0, 0x3fffffff, v0
	v_mbcnt_lo_u32_b32 v2, -1, 0
	v_writelane_b32 v244, s1, 60
	s_lshr_b32 s0, s5, 5
	s_and_b32 s0, s0, 4
	s_lshl_b32 s1, s0, 2
	s_sub_i32 s1, s86, s1
	s_ashr_i32 s1, s1, 2
	v_writelane_b32 v244, s1, 61
	s_lshl_b32 s1, s5, 3
	s_and_b32 s87, s1, 56
	s_bfe_u32 s1, s5, 0x20003
	s_or_b32 s1, s87, s1
	s_or_b32 s0, s1, s0
	v_writelane_b32 v244, s0, 62
	s_add_u32 s0, s90, 0x1380000
	v_writelane_b32 v244, s0, 63
	s_addc_u32 s0, s91, 0
	s_cmpk_lt_u32 s5, 0x400
	v_writelane_b32 v243, s0, 0
	s_cselect_b64 s[10:11], -1, 0
	s_lshr_b32 s0, s5, 7
	s_and_b32 s0, s0, 4
	s_lshl_b32 s4, s0, 4
	s_sub_i32 s4, s86, s4
	v_writelane_b32 v243, s10, 1
	s_ashr_i32 s4, s4, 2
	s_or_b32 s0, s1, s0
	v_writelane_b32 v243, s11, 2
	s_add_u32 s10, s90, 0xf548000
	s_addc_u32 s11, s91, 0
	s_add_u32 s96, s90, 0xc928000
	v_writelane_b32 v243, s4, 3
	s_addc_u32 s97, s91, 0
	v_writelane_b32 v243, s0, 4
	s_add_u32 s18, s90, 0x1160000
	v_writelane_b32 v243, s10, 5
	s_addc_u32 s19, s91, 0
	v_readlane_b32 s36, v244, 35
	v_writelane_b32 v243, s11, 6
	s_add_u32 s10, s90, 0xa728000
	s_addc_u32 s11, s91, 0
	s_add_u32 s33, s90, 0x660000
	s_addc_u32 s22, s91, 0
	s_add_u32 s13, s90, 0xee0000
	s_addc_u32 s24, s91, 0
	v_writelane_b32 v243, s10, 7
	s_cmpk_lt_u32 s5, 0x200
	v_readlane_b32 s37, v244, 36
	v_writelane_b32 v243, s11, 8
	s_cselect_b64 s[10:11], -1, 0
	s_lshr_b32 s0, s5, 6
	s_and_b32 s0, s0, 4
	s_lshl_b32 s4, s0, 3
	v_writelane_b32 v243, s10, 9
	s_sub_i32 s4, s86, s4
	s_ashr_i32 s4, s4, 2
	v_writelane_b32 v243, s11, 10
	v_writelane_b32 v243, s4, 11
	s_or_b32 s0, s1, s0
	v_writelane_b32 v243, s0, 12
	s_lshl_b32 s0, s5, 1
	s_add_u32 s10, s90, 0xeb28000
	v_writelane_b32 v243, s0, 13
	s_addc_u32 s11, s91, 0
	v_writelane_b32 v243, s10, 14
	s_add_u32 s0, s90, 0xeb68000
	v_readlane_b32 s38, v244, 37
	v_writelane_b32 v243, s11, 15
	v_writelane_b32 v243, s0, 16
	s_addc_u32 s0, s91, 0
	v_writelane_b32 v243, s0, 17
	s_add_u32 s0, s90, 0xeba8000
	v_writelane_b32 v243, s0, 18
	s_addc_u32 s0, s91, 0
	v_writelane_b32 v243, s0, 19
	s_add_u32 s0, s90, 0xefa8000
	v_writelane_b32 v243, s0, 20
	s_addc_u32 s0, s91, 0
	v_writelane_b32 v243, s0, 21
	s_add_u32 s0, s90, 0xf58b6b0
	v_writelane_b32 v243, s0, 22
	s_addc_u32 s0, s91, 0
	s_cmp_lt_i32 s5, 32
	v_writelane_b32 v243, s0, 23
	s_cselect_b64 s[10:11], -1, 0
	v_writelane_b32 v243, s10, 24
	s_add_u32 s0, s90, 0xf3a8000
	v_readlane_b32 s39, v244, 38
	v_writelane_b32 v243, s11, 25
	v_writelane_b32 v243, s0, 26
	s_addc_u32 s0, s91, 0
	v_writelane_b32 v243, s0, 27
	s_add_u32 s0, s90, 0xf4a8000
	v_writelane_b32 v243, s0, 28
	s_addc_u32 s0, s91, 0
	v_writelane_b32 v243, s0, 29
	s_add_u32 s0, s90, 0x2420000
	v_writelane_b32 v243, s0, 30
	s_addc_u32 s0, s91, 0
	v_writelane_b32 v243, s0, 31
	s_add_u32 s0, s90, 0x2520000
	v_writelane_b32 v243, s0, 32
	s_addc_u32 s0, s91, 0
	s_cmpk_lt_u32 s5, 0x300
	s_cselect_b64 s[10:11], -1, 0
	s_cmpk_gt_u32 s5, 0x17f
	v_writelane_b32 v243, s0, 33
	s_cselect_b32 s0, 4, 0
	s_or_b32 s1, s1, s0
	s_mul_i32 s0, s0, -12
	v_writelane_b32 v243, s10, 34
	s_add_i32 s0, s0, s86
	s_ashr_i32 s0, s0, 2
	v_writelane_b32 v243, s11, 35
	v_readlane_b32 s40, v244, 39
	v_readlane_b32 s41, v244, 40
	v_readlane_b32 s42, v244, 41
	v_readlane_b32 s43, v244, 42
	v_readlane_b32 s44, v244, 43
	v_readlane_b32 s45, v244, 44
	v_readlane_b32 s46, v244, 45
	v_readlane_b32 s47, v244, 46
	v_readlane_b32 s48, v244, 47
	v_readlane_b32 s49, v244, 48
	v_readlane_b32 s50, v244, 49
	v_readlane_b32 s51, v244, 50
	v_writelane_b32 v243, s1, 36
	s_cmp_lg_u64 s[46:47], 0
	v_readlane_b32 s36, v244, 3
	v_writelane_b32 v243, s0, 37
	s_cselect_b64 s[0:1], -1, 0
	v_readlane_b32 s38, v244, 5
	v_readlane_b32 s39, v244, 6
	v_writelane_b32 v243, s0, 38
	s_cmp_lg_u64 s[38:39], 0
	v_readlane_b32 s10, v244, 51
	v_writelane_b32 v243, s1, 39
	s_cselect_b64 s[0:1], -1, 0
	v_writelane_b32 v243, s0, 40
	s_bitcmp1_b32 s94, 1
	v_readlane_b32 s11, v244, 52
	v_writelane_b32 v243, s1, 41
	s_cselect_b64 s[0:1], -1, 0
	v_writelane_b32 v243, s0, 42
	v_mov_b32_e32 v1, 0
	v_mov_b32_e32 v222, 0x358637bd
	v_writelane_b32 v243, s1, 43
; DEVI int vhalf() { int t = threadIdx.x >> 8; t = __builtin_amdgcn_readfirstlane(t); return t; }
; #define LAS __attribute__((address_space(3)))
; DEVI void run_phase(const Params& p, int ph, char* lds, volatile int* nsa_cnt, float* p4s, bool rep) {
;   const int l = ph / PH_PER_LAYER, q = ph % PH_PER_LAYER;
;   char* hl = lds + vhalf() * LDS_HALF;
;   switch (q) {
;     case 0: phase1(p, l, hl); break;
;     case 1: phase2(p, l, lds); break;
;     case 2: phase3a(p, l, hl, rep, nsa_cnt); break;
;     case 3: phase3b(p, l, hl, nsa_cnt); break;
;     case 4: phase4(p, l, lds, p4s); break;
;     case 5: phase_resid_gemm(p, (const bfu*)(p.ws + OFF_MIX), LDX, 16, (const bfu*)(p.ws + OFF_WOUT), LDX,
;                              (l == 0) ? p.in[0] : nullptr, (float*)(p.ws + OFF_SSQB), nullptr, lds); break;
;     case 6: phase7(p, l, lds); break;
;     case 7: phase_resid_gemm(p, (const bfu*)(p.ws + OFF_HID), LDH, 64, (const bfu*)(p.ws + OFF_WM2), LDH, nullptr,
;                              (float*)(p.ws + OFF_SSQA), (l == 1) ? p.out : nullptr, lds); break;
;   }
; }
; __global__ void __launch_bounds__(512, 2) fwd_mega(Params p, int ph_lo, int ph_hi, int coop) {
;   extern __shared__ __attribute__((aligned(16))) char lds[];
;   __shared__ uint4 xb_words;
;   __shared__ int nsa_cnt_s[4];
;   __shared__ float p4_stage[768];
;   XcdBarrier xb;
;   if (coop) {
;     if (threadIdx.x == 0) xb_words = make_uint4(0u, 0u, 0u, 0u);
;     __syncthreads();
;     xb = xcd_barrier_post((unsigned*)(p.ws + OFF_BAR), (volatile LAS unsigned*)&xb_words);
;   }
;   for (int ph = ph_lo; ph < ph_hi; ++ph) {
;     run_phase(p, ph, lds, nsa_cnt_s, p4_stage, false);
	s_add_u32 s0, s10, 0x200
	s_addc_u32 s1, s11, 0
	v_writelane_b32 v243, s0, 44
	v_mov_b32_e32 v223, 0x3727c5ac
	v_mov_b32_e32 v224, 1
	v_writelane_b32 v243, s1, 45
	s_add_u32 s0, s10, 0x1000
	s_addc_u32 s1, s11, 0
	v_writelane_b32 v243, s0, 46
	v_mbcnt_hi_u32_b32 v225, -1, v2
	v_bfe_u32 v254, v225, 4, 1
	v_mov_b32_e32 v255, 0
	v_mul_u32_u24_e32 v254, 24, v254
	v_mov_b32_e32 v226, 0xc20
	v_writelane_b32 v243, s1, 47
	s_add_u32 s0, s10, 0x1100
	s_addc_u32 s1, s11, 0
	v_writelane_b32 v243, s0, 48
	v_mov_b32_e32 v227, 0xf149f2ca
	v_mov_b32_e32 v178, 0xc10
	v_writelane_b32 v243, s1, 49
	s_add_u32 s0, s10, 0x1200
	s_addc_u32 s1, s11, 0
	v_writelane_b32 v243, s0, 50
	v_mov_b32_e32 v180, 0xc14
	v_mov_b32_e32 v228, 0x3f80
	v_writelane_b32 v243, s1, 51
	s_add_u32 s0, s10, 0x1300
	s_addc_u32 s1, s11, 0
	v_writelane_b32 v243, s0, 52
	s_cmp_eq_u32 s8, 15
	v_mov_b32_e32 v182, 0xc18
	v_writelane_b32 v243, s1, 53
	s_cselect_b64 s[0:1], -1, 0
	v_writelane_b32 v243, s0, 54
	s_cmp_eq_u32 s8, 14
	v_mov_b32_e32 v229, 0x18000
	v_writelane_b32 v243, s1, 55
	s_cselect_b64 s[0:1], -1, 0
	v_writelane_b32 v243, s0, 56
	s_cmp_eq_u32 s8, 13
	v_mov_b32_e32 v230, 0xa00
	v_writelane_b32 v243, s1, 57
	s_cselect_b64 s[0:1], -1, 0
	v_writelane_b32 v243, s0, 58
	s_cmp_eq_u32 s8, 12
	v_mov_b32_e32 v231, 0x900
	v_writelane_b32 v243, s1, 59
	s_cselect_b64 s[0:1], -1, 0
	v_writelane_b32 v243, s0, 60
	s_cmp_eq_u32 s8, 11
	v_mov_b32_e32 v232, 0xefa8000
	v_writelane_b32 v243, s1, 61
	s_cselect_b64 s[0:1], -1, 0
	v_writelane_b32 v243, s0, 62
	s_cmp_eq_u32 s8, 10
	v_mov_b32_e32 v233, 0xeba8000
	v_writelane_b32 v243, s1, 63
	s_cselect_b64 s[0:1], -1, 0
	v_writelane_b32 v242, s0, 0
	s_cmp_eq_u32 s8, 9
	s_movk_i32 s94, 0x100
	v_writelane_b32 v242, s1, 1
	s_cselect_b64 s[0:1], -1, 0
	v_writelane_b32 v242, s0, 2
	s_cmp_eq_u32 s8, 8
	s_movk_i32 s95, 0x880
	v_writelane_b32 v242, s1, 3
	s_cselect_b64 s[0:1], -1, 0
	v_writelane_b32 v242, s0, 4
	s_cmp_eq_u32 s8, 7
	s_mov_b32 s12, 0x22000
	v_writelane_b32 v242, s1, 5
	s_cselect_b64 s[0:1], -1, 0
	v_writelane_b32 v242, s0, 6
	s_cmp_eq_u32 s8, 6
	s_movk_i32 s83, 0x440
	v_writelane_b32 v242, s1, 7
	s_cselect_b64 s[0:1], -1, 0
	v_writelane_b32 v242, s0, 8
	s_cmp_eq_u32 s8, 5
	s_movk_i32 s72, 0x1800
	v_writelane_b32 v242, s1, 9
	s_cselect_b64 s[0:1], -1, 0
	v_writelane_b32 v242, s0, 10
	s_cmp_eq_u32 s8, 4
	s_mov_b32 s16, 0x5040100
	v_writelane_b32 v242, s1, 11
	s_cselect_b64 s[0:1], -1, 0
	v_writelane_b32 v242, s0, 12
	s_cmp_eq_u32 s8, 3
	s_mov_b32 s17, 0xa728000
	v_writelane_b32 v242, s1, 13
	s_cselect_b64 s[0:1], -1, 0
	v_writelane_b32 v242, s0, 14
	s_cmp_eq_u32 s8, 2
	s_mov_b64 s[14:15], 0x22000
	v_writelane_b32 v242, s1, 15
	s_cselect_b64 s[0:1], -1, 0
	v_writelane_b32 v242, s0, 16
	s_cmp_eq_u32 s8, 1
	s_mov_b64 s[34:35], 0x66000
	v_writelane_b32 v242, s1, 17
	s_cselect_b64 s[0:1], -1, 0
	v_writelane_b32 v242, s0, 18
	s_cmp_eq_u32 s8, 0
	v_readlane_b32 s37, v244, 4
	v_writelane_b32 v242, s1, 19
	s_cselect_b64 s[0:1], -1, 0
	s_lshl_b32 s4, s8, 6
	v_writelane_b32 v242, s0, 20
	s_add_i32 s30, s4, 0x500
	s_mov_b64 s[8:9], 0x44000
	v_writelane_b32 v242, s1, 21
	s_lshl_b64 s[0:1], s[30:31], 2
	s_add_u32 s0, s10, s0
	s_addc_u32 s1, s11, s1
	v_writelane_b32 v242, s0, 22
	s_add_i32 s30, s4, 0x900
	v_readlane_b32 s40, v244, 7
	v_writelane_b32 v242, s1, 23
	s_lshl_b64 s[0:1], s[30:31], 2
	s_add_u32 s0, s10, s0
	s_addc_u32 s1, s11, s1
	v_writelane_b32 v242, s0, 24
	v_readlane_b32 s41, v244, 8
	v_readlane_b32 s42, v244, 9
	v_writelane_b32 v242, s1, 25
	s_add_u32 s0, s10, 0x3400
	s_addc_u32 s1, s11, 0
	v_writelane_b32 v242, s0, 26
	v_readlane_b32 s43, v244, 10
	v_readlane_b32 s44, v244, 11
	v_writelane_b32 v242, s1, 27
	s_add_u32 s0, s10, 0x3500
	s_addc_u32 s1, s11, 0
	v_writelane_b32 v242, s0, 28
	s_movk_i32 s11, 0x500
	s_movk_i32 s10, 0x140
	v_writelane_b32 v242, s1, 29
	s_add_u32 s0, s90, 0xa728400
	s_addc_u32 s1, s91, 0
	v_writelane_b32 v242, s0, 30
	v_readlane_b32 s45, v244, 12
	v_readlane_b32 s46, v244, 13
	v_writelane_b32 v242, s1, 31
	s_add_u32 s0, s90, 0x2420180
	v_writelane_b32 v242, s0, 32
	s_addc_u32 s0, s91, 0
	v_writelane_b32 v242, s0, 33
	s_mov_b32 s0, 0x20000
	s_addk_i32 s0, 0xc20
	v_writelane_b32 v242, s0, 34
	s_movk_i32 s0, 0x4400
	s_addk_i32 s0, 0xc20
	v_writelane_b32 v242, s0, 35
	s_lshl_b32 s0, s5, 13
	v_writelane_b32 v242, s0, 36
	v_cmp_eq_u32_e64 s[0:1], 0, v220
	v_readlane_b32 s47, v244, 14
	v_readlane_b32 s48, v244, 15
	v_writelane_b32 v242, s0, 37
	v_readlane_b32 s49, v244, 16
	v_readlane_b32 s50, v244, 17
	v_writelane_b32 v242, s1, 38
	v_cmp_eq_u32_e64 s[0:1], 0, v0
	v_readlane_b32 s51, v244, 18
	s_nop 0
	v_writelane_b32 v242, s0, 39
	s_nop 1
	v_writelane_b32 v242, s1, 40
	v_writelane_b32 v242, s13, 41
	v_writelane_b32 v242, s24, 42
	s_branch .LBB0_14

; DEVI float lo2f(unsigned u) { return __uint_as_float(u << 16); }
; DEVI float hi2f(unsigned u) { return __uint_as_float(u & 0xffff0000u); }
; DEVI void phase_resid_gemm(const Params& p, const bfu* A, int lda, int nkt, const bfu* wT, int ldb, const float* resid32,
;                            float* ssq_out, float* out32, char* lds) {
;     ...
; #pragma unroll
;       for (int ni = 0; ni < 4; ++ni) {
;         const int n = n0 + wn * 64 + ni * 16 + fq * 4;
;         float4 r;
;         if (resid32) r = *(const float4*)(resid32 + (long)m * 1024 + n);
;         else { const uint2 u = *(const uint2*)(xs + (long)m * LDX + n); r = make_float4(lo2f(u.x), hi2f(u.x), lo2f(u.y), hi2f(u.y)); }
;         float4 o;
;         o.x = r.x + acc[ni][mi][0]; o.y = r.y + acc[ni][mi][1]; o.z = r.z + acc[ni][mi][2]; o.w = r.w + acc[ni][mi][3];
;         if (out32) *(float4*)(out32 + (long)m * 1024 + n) = o;
;         else {
;           uint2 ob; ob.x = pack2(o.x, o.y); ob.y = pack2(o.z, o.w);
;           *(uint2*)(xs + (long)m * LDX + n) = ob;
;           const float q0 = lo2f(ob.x), q1 = hi2f(ob.x), q2 = lo2f(ob.y), q3 = hi2f(ob.y);
;           ss += q0 * q0 + q1 * q1 + q2 * q2 + q3 * q3;
.LBB0_40:
	s_andn2_b64 vcc, exec, s[36:37]
	v_mov_b32_e32 v0, 0
	s_cbranch_vccnz .LBB0_42
	v_cvt_pk_bf16_f32 v126, v126, v127
	v_cvt_pk_bf16_f32 v127, v128, v129
	v_lshlrev_b32_e32 v128, 16, v126
	v_and_b32_e32 v129, 0xffff0000, v126
	v_mov_b32_e32 v200, v126
	v_mov_b32_e32 v201, v127
	v_lshlrev_b32_e32 v139, 16, v127
	v_and_b32_e32 v138, 0xffff0000, v127
	v_pk_mul_f32 v[126:127], v[128:129], v[128:129]
	v_pk_mul_f32 v[128:129], v[138:139], v[138:139]
	v_add_f32_e32 v0, v126, v127
	v_add_f32_e32 v0, v129, v0
	v_add_f32_e32 v0, v128, v0

; DEVI float lo2f(unsigned u) { return __uint_as_float(u << 16); }
; DEVI float hi2f(unsigned u) { return __uint_as_float(u & 0xffff0000u); }
; DEVI void phase_resid_gemm(const Params& p, const bfu* A, int lda, int nkt, const bfu* wT, int ldb, const float* resid32,
;                            float* ssq_out, float* out32, char* lds) {
;     ...
; #pragma unroll
;       for (int ni = 0; ni < 4; ++ni) {
;         const int n = n0 + wn * 64 + ni * 16 + fq * 4;
;         float4 r;
;         if (resid32) r = *(const float4*)(resid32 + (long)m * 1024 + n);
;         else { const uint2 u = *(const uint2*)(xs + (long)m * LDX + n); r = make_float4(lo2f(u.x), hi2f(u.x), lo2f(u.y), hi2f(u.y)); }
;         float4 o;
;         o.x = r.x + acc[ni][mi][0]; o.y = r.y + acc[ni][mi][1]; o.z = r.z + acc[ni][mi][2]; o.w = r.w + acc[ni][mi][3];
;         if (out32) *(float4*)(out32 + (long)m * 1024 + n) = o;
;         else {
;           uint2 ob; ob.x = pack2(o.x, o.y); ob.y = pack2(o.z, o.w);
;           *(uint2*)(xs + (long)m * LDX + n) = ob;
;           const float q0 = lo2f(ob.x), q1 = hi2f(ob.x), q2 = lo2f(ob.y), q3 = hi2f(ob.y);
;           ss += q0 * q0 + q1 * q1 + q2 * q2 + q3 * q3;
.LBB0_44:
	s_andn2_b64 vcc, exec, s[36:37]
	s_cbranch_vccnz .LBB0_46
	v_cvt_pk_bf16_f32 v122, v122, v123
	v_cvt_pk_bf16_f32 v123, v124, v125
	v_lshlrev_b32_e32 v124, 16, v122
	v_and_b32_e32 v125, 0xffff0000, v122
	v_mov_b32_e32 v206, v122
	v_mov_b32_e32 v207, v123
	v_mov_b32_e32 v204, v200
	v_mov_b32_e32 v205, v201
	v_lshl_add_u64 v[212:213], v[134:135], 0, v[254:255]
	s_nop 0
	v_permlane16_swap_b32_e32 v204, v206
	v_permlane16_swap_b32_e32 v205, v207
	s_nop 1
	global_store_dwordx4 v[212:213], v[204:207], off
	v_lshlrev_b32_e32 v127, 16, v123
	v_and_b32_e32 v126, 0xffff0000, v123
	v_pk_mul_f32 v[122:123], v[124:125], v[124:125]
	v_pk_mul_f32 v[124:125], v[126:127], v[126:127]
	v_add_f32_e32 v122, v122, v123
	v_add_f32_e32 v122, v125, v122
	v_add_f32_e32 v122, v124, v122
	v_add_f32_e32 v0, v0, v122

; DEVI float lo2f(unsigned u) { return __uint_as_float(u << 16); }
; DEVI float hi2f(unsigned u) { return __uint_as_float(u & 0xffff0000u); }
; DEVI void phase_resid_gemm(const Params& p, const bfu* A, int lda, int nkt, const bfu* wT, int ldb, const float* resid32,
;                            float* ssq_out, float* out32, char* lds) {
;     ...
; #pragma unroll
;       for (int ni = 0; ni < 4; ++ni) {
;         const int n = n0 + wn * 64 + ni * 16 + fq * 4;
;         float4 r;
;         if (resid32) r = *(const float4*)(resid32 + (long)m * 1024 + n);
;         else { const uint2 u = *(const uint2*)(xs + (long)m * LDX + n); r = make_float4(lo2f(u.x), hi2f(u.x), lo2f(u.y), hi2f(u.y)); }
;         float4 o;
;         o.x = r.x + acc[ni][mi][0]; o.y = r.y + acc[ni][mi][1]; o.z = r.z + acc[ni][mi][2]; o.w = r.w + acc[ni][mi][3];
;         if (out32) *(float4*)(out32 + (long)m * 1024 + n) = o;
;         else {
;           uint2 ob; ob.x = pack2(o.x, o.y); ob.y = pack2(o.z, o.w);
;           *(uint2*)(xs + (long)m * LDX + n) = ob;
;           const float q0 = lo2f(ob.x), q1 = hi2f(ob.x), q2 = lo2f(ob.y), q3 = hi2f(ob.y);
;           ss += q0 * q0 + q1 * q1 + q2 * q2 + q3 * q3;
.LBB0_48:
	s_andn2_b64 vcc, exec, s[36:37]
	s_cbranch_vccnz .LBB0_50
	v_cvt_pk_bf16_f32 v114, v114, v115
	v_cvt_pk_bf16_f32 v115, v116, v117
	v_lshlrev_b32_e32 v116, 16, v114
	v_and_b32_e32 v117, 0xffff0000, v114
	v_mov_b32_e32 v200, v114
	v_mov_b32_e32 v201, v115
	v_lshlrev_b32_e32 v123, 16, v115
	v_and_b32_e32 v122, 0xffff0000, v115
	v_pk_mul_f32 v[114:115], v[116:117], v[116:117]
	v_pk_mul_f32 v[116:117], v[122:123], v[122:123]
	v_add_f32_e32 v114, v114, v115
	v_add_f32_e32 v114, v117, v114
	v_add_f32_e32 v114, v116, v114
	v_add_f32_e32 v0, v0, v114

; DEVI float lo2f(unsigned u) { return __uint_as_float(u << 16); }
; DEVI float hi2f(unsigned u) { return __uint_as_float(u & 0xffff0000u); }
; DEVI void phase_resid_gemm(const Params& p, const bfu* A, int lda, int nkt, const bfu* wT, int ldb, const float* resid32,
;                            float* ssq_out, float* out32, char* lds) {
;     ...
; #pragma unroll
;       for (int ni = 0; ni < 4; ++ni) {
;         const int n = n0 + wn * 64 + ni * 16 + fq * 4;
;         float4 r;
;         if (resid32) r = *(const float4*)(resid32 + (long)m * 1024 + n);
;         else { const uint2 u = *(const uint2*)(xs + (long)m * LDX + n); r = make_float4(lo2f(u.x), hi2f(u.x), lo2f(u.y), hi2f(u.y)); }
;         float4 o;
;         o.x = r.x + acc[ni][mi][0]; o.y = r.y + acc[ni][mi][1]; o.z = r.z + acc[ni][mi][2]; o.w = r.w + acc[ni][mi][3];
;         if (out32) *(float4*)(out32 + (long)m * 1024 + n) = o;
;         else {
;           uint2 ob; ob.x = pack2(o.x, o.y); ob.y = pack2(o.z, o.w);
;           *(uint2*)(xs + (long)m * LDX + n) = ob;
;           const float q0 = lo2f(ob.x), q1 = hi2f(ob.x), q2 = lo2f(ob.y), q3 = hi2f(ob.y);
;           ss += q0 * q0 + q1 * q1 + q2 * q2 + q3 * q3;
.LBB0_54:
	s_nop 0
	v_cvt_pk_bf16_f32 v110, v110, v111
	v_cvt_pk_bf16_f32 v111, v112, v113
	v_lshlrev_b32_e32 v112, 16, v110
	v_and_b32_e32 v113, 0xffff0000, v110
	v_mov_b32_e32 v210, v110
	v_mov_b32_e32 v211, v111
	v_mov_b32_e32 v208, v200
	v_mov_b32_e32 v209, v201
	v_lshl_add_u64 v[212:213], v[134:135], 0, v[254:255]
	s_nop 0
	v_permlane16_swap_b32_e32 v208, v210
	v_permlane16_swap_b32_e32 v209, v211
	s_nop 1
	global_store_dwordx4 v[212:213], v[208:211], off offset:64
	v_lshlrev_b32_e32 v115, 16, v111
	v_and_b32_e32 v114, 0xffff0000, v111
	v_pk_mul_f32 v[110:111], v[112:113], v[112:113]
	v_pk_mul_f32 v[112:113], v[114:115], v[114:115]
	v_add_f32_e32 v110, v110, v111
	v_add_f32_e32 v110, v113, v110
	v_add_f32_e32 v110, v112, v110
	v_add_f32_e32 v0, v0, v110
	v_cndmask_b32_e64 v110, 0, 1, s[4:5]
	v_cmp_ne_u32_e64 s[44:45], 1, v110
	s_andn2_b64 vcc, exec, s[4:5]
	s_cbranch_vccnz .LBB0_58

; DEVI float lo2f(unsigned u) { return __uint_as_float(u << 16); }
; DEVI float hi2f(unsigned u) { return __uint_as_float(u & 0xffff0000u); }
; DEVI void phase_resid_gemm(const Params& p, const bfu* A, int lda, int nkt, const bfu* wT, int ldb, const float* resid32,
;                            float* ssq_out, float* out32, char* lds) {
;     ...
; #pragma unroll
;       for (int ni = 0; ni < 4; ++ni) {
;         const int n = n0 + wn * 64 + ni * 16 + fq * 4;
;         float4 r;
;         if (resid32) r = *(const float4*)(resid32 + (long)m * 1024 + n);
;         else { const uint2 u = *(const uint2*)(xs + (long)m * LDX + n); r = make_float4(lo2f(u.x), hi2f(u.x), lo2f(u.y), hi2f(u.y)); }
;         float4 o;
;         o.x = r.x + acc[ni][mi][0]; o.y = r.y + acc[ni][mi][1]; o.z = r.z + acc[ni][mi][2]; o.w = r.w + acc[ni][mi][3];
;         if (out32) *(float4*)(out32 + (long)m * 1024 + n) = o;
;         else {
;           uint2 ob; ob.x = pack2(o.x, o.y); ob.y = pack2(o.z, o.w);
;           *(uint2*)(xs + (long)m * LDX + n) = ob;
;           const float q0 = lo2f(ob.x), q1 = hi2f(ob.x), q2 = lo2f(ob.y), q3 = hi2f(ob.y);
;           ss += q0 * q0 + q1 * q1 + q2 * q2 + q3 * q3;
.LBB0_60:
	s_andn2_b64 vcc, exec, s[36:37]
	v_mov_b32_e32 v0, 0
	s_cbranch_vccnz .LBB0_62
	v_cvt_pk_bf16_f32 v110, v110, v111
	v_cvt_pk_bf16_f32 v111, v112, v113
	v_lshlrev_b32_e32 v112, 16, v110
	v_and_b32_e32 v113, 0xffff0000, v110
	v_mov_b32_e32 v200, v110
	v_mov_b32_e32 v201, v111
	v_lshlrev_b32_e32 v119, 16, v111
	v_and_b32_e32 v118, 0xffff0000, v111
	v_pk_mul_f32 v[110:111], v[112:113], v[112:113]
	v_pk_mul_f32 v[112:113], v[118:119], v[118:119]
	v_add_f32_e32 v0, v110, v111
	v_add_f32_e32 v0, v113, v0
	v_add_f32_e32 v0, v112, v0

; DEVI float lo2f(unsigned u) { return __uint_as_float(u << 16); }
; DEVI float hi2f(unsigned u) { return __uint_as_float(u & 0xffff0000u); }
; DEVI void phase_resid_gemm(const Params& p, const bfu* A, int lda, int nkt, const bfu* wT, int ldb, const float* resid32,
;                            float* ssq_out, float* out32, char* lds) {
;     ...
; #pragma unroll
;       for (int ni = 0; ni < 4; ++ni) {
;         const int n = n0 + wn * 64 + ni * 16 + fq * 4;
;         float4 r;
;         if (resid32) r = *(const float4*)(resid32 + (long)m * 1024 + n);
;         else { const uint2 u = *(const uint2*)(xs + (long)m * LDX + n); r = make_float4(lo2f(u.x), hi2f(u.x), lo2f(u.y), hi2f(u.y)); }
;         float4 o;
;         o.x = r.x + acc[ni][mi][0]; o.y = r.y + acc[ni][mi][1]; o.z = r.z + acc[ni][mi][2]; o.w = r.w + acc[ni][mi][3];
;         if (out32) *(float4*)(out32 + (long)m * 1024 + n) = o;
;         else {
;           uint2 ob; ob.x = pack2(o.x, o.y); ob.y = pack2(o.z, o.w);
;           *(uint2*)(xs + (long)m * LDX + n) = ob;
;           const float q0 = lo2f(ob.x), q1 = hi2f(ob.x), q2 = lo2f(ob.y), q3 = hi2f(ob.y);
;           ss += q0 * q0 + q1 * q1 + q2 * q2 + q3 * q3;
.LBB0_64:
	s_andn2_b64 vcc, exec, s[36:37]
	s_cbranch_vccnz .LBB0_66
	v_cvt_pk_bf16_f32 v106, v106, v107
	v_cvt_pk_bf16_f32 v107, v108, v109
	v_lshlrev_b32_e32 v108, 16, v106
	v_and_b32_e32 v109, 0xffff0000, v106
	v_mov_b32_e32 v206, v106
	v_mov_b32_e32 v207, v107
	v_mov_b32_e32 v204, v200
	v_mov_b32_e32 v205, v201
	v_lshl_add_u64 v[212:213], v[114:115], 0, v[254:255]
	s_nop 0
	v_permlane16_swap_b32_e32 v204, v206
	v_permlane16_swap_b32_e32 v205, v207
	s_nop 1
	global_store_dwordx4 v[212:213], v[204:207], off
	v_lshlrev_b32_e32 v111, 16, v107
	v_and_b32_e32 v110, 0xffff0000, v107
	v_pk_mul_f32 v[106:107], v[108:109], v[108:109]
	v_pk_mul_f32 v[108:109], v[110:111], v[110:111]
	v_add_f32_e32 v106, v106, v107
	v_add_f32_e32 v106, v109, v106
	v_add_f32_e32 v106, v108, v106
	v_add_f32_e32 v0, v0, v106

; DEVI float lo2f(unsigned u) { return __uint_as_float(u << 16); }
; DEVI float hi2f(unsigned u) { return __uint_as_float(u & 0xffff0000u); }
; DEVI void phase_resid_gemm(const Params& p, const bfu* A, int lda, int nkt, const bfu* wT, int ldb, const float* resid32,
;                            float* ssq_out, float* out32, char* lds) {
;     ...
; #pragma unroll
;       for (int ni = 0; ni < 4; ++ni) {
;         const int n = n0 + wn * 64 + ni * 16 + fq * 4;
;         float4 r;
;         if (resid32) r = *(const float4*)(resid32 + (long)m * 1024 + n);
;         else { const uint2 u = *(const uint2*)(xs + (long)m * LDX + n); r = make_float4(lo2f(u.x), hi2f(u.x), lo2f(u.y), hi2f(u.y)); }
;         float4 o;
;         o.x = r.x + acc[ni][mi][0]; o.y = r.y + acc[ni][mi][1]; o.z = r.z + acc[ni][mi][2]; o.w = r.w + acc[ni][mi][3];
;         if (out32) *(float4*)(out32 + (long)m * 1024 + n) = o;
;         else {
;           uint2 ob; ob.x = pack2(o.x, o.y); ob.y = pack2(o.z, o.w);
;           *(uint2*)(xs + (long)m * LDX + n) = ob;
;           const float q0 = lo2f(ob.x), q1 = hi2f(ob.x), q2 = lo2f(ob.y), q3 = hi2f(ob.y);
;           ss += q0 * q0 + q1 * q1 + q2 * q2 + q3 * q3;
.LBB0_68:
	s_andn2_b64 vcc, exec, s[36:37]
	s_cbranch_vccnz .LBB0_70
	v_cvt_pk_bf16_f32 v102, v102, v103
	v_cvt_pk_bf16_f32 v103, v104, v105
	v_lshlrev_b32_e32 v104, 16, v102
	v_and_b32_e32 v105, 0xffff0000, v102
	v_mov_b32_e32 v200, v102
	v_mov_b32_e32 v201, v103
	v_lshlrev_b32_e32 v107, 16, v103
	v_and_b32_e32 v106, 0xffff0000, v103
	v_pk_mul_f32 v[102:103], v[104:105], v[104:105]
	v_pk_mul_f32 v[104:105], v[106:107], v[106:107]
	v_add_f32_e32 v102, v102, v103
	v_add_f32_e32 v102, v105, v102
	v_add_f32_e32 v102, v104, v102
	v_add_f32_e32 v0, v0, v102

; DEVI float lo2f(unsigned u) { return __uint_as_float(u << 16); }
; DEVI float hi2f(unsigned u) { return __uint_as_float(u & 0xffff0000u); }
; DEVI void phase_resid_gemm(const Params& p, const bfu* A, int lda, int nkt, const bfu* wT, int ldb, const float* resid32,
;                            float* ssq_out, float* out32, char* lds) {
;     ...
; #pragma unroll
;       for (int ni = 0; ni < 4; ++ni) {
;         const int n = n0 + wn * 64 + ni * 16 + fq * 4;
;         float4 r;
;         if (resid32) r = *(const float4*)(resid32 + (long)m * 1024 + n);
;         else { const uint2 u = *(const uint2*)(xs + (long)m * LDX + n); r = make_float4(lo2f(u.x), hi2f(u.x), lo2f(u.y), hi2f(u.y)); }
;         float4 o;
;         o.x = r.x + acc[ni][mi][0]; o.y = r.y + acc[ni][mi][1]; o.z = r.z + acc[ni][mi][2]; o.w = r.w + acc[ni][mi][3];
;         if (out32) *(float4*)(out32 + (long)m * 1024 + n) = o;
;         else {
;           uint2 ob; ob.x = pack2(o.x, o.y); ob.y = pack2(o.z, o.w);
;           *(uint2*)(xs + (long)m * LDX + n) = ob;
;           const float q0 = lo2f(ob.x), q1 = hi2f(ob.x), q2 = lo2f(ob.y), q3 = hi2f(ob.y);
;           ss += q0 * q0 + q1 * q1 + q2 * q2 + q3 * q3;
.LBB0_74:
	s_nop 0
	v_cvt_pk_bf16_f32 v94, v94, v95
	v_cvt_pk_bf16_f32 v95, v96, v97
	v_lshlrev_b32_e32 v96, 16, v94
	v_and_b32_e32 v97, 0xffff0000, v94
	v_mov_b32_e32 v210, v94
	v_mov_b32_e32 v211, v95
	v_mov_b32_e32 v208, v200
	v_mov_b32_e32 v209, v201
	v_lshl_add_u64 v[212:213], v[114:115], 0, v[254:255]
	s_nop 0
	v_permlane16_swap_b32_e32 v208, v210
	v_permlane16_swap_b32_e32 v209, v211
	s_nop 1
	global_store_dwordx4 v[212:213], v[208:211], off offset:64
	v_lshlrev_b32_e32 v103, 16, v95
	v_and_b32_e32 v102, 0xffff0000, v95
	v_pk_mul_f32 v[94:95], v[96:97], v[96:97]
	v_pk_mul_f32 v[96:97], v[102:103], v[102:103]
	v_add_f32_e32 v94, v94, v95
	v_add_f32_e32 v94, v97, v94
	v_add_f32_e32 v94, v96, v94
	v_add_f32_e32 v0, v0, v94
	s_and_b64 vcc, exec, s[44:45]
	s_cbranch_vccnz .LBB0_78

; DEVI float lo2f(unsigned u) { return __uint_as_float(u << 16); }
; DEVI float hi2f(unsigned u) { return __uint_as_float(u & 0xffff0000u); }
; DEVI void phase_resid_gemm(const Params& p, const bfu* A, int lda, int nkt, const bfu* wT, int ldb, const float* resid32,
;                            float* ssq_out, float* out32, char* lds) {
;     ...
; #pragma unroll
;       for (int ni = 0; ni < 4; ++ni) {
;         const int n = n0 + wn * 64 + ni * 16 + fq * 4;
;         float4 r;
;         if (resid32) r = *(const float4*)(resid32 + (long)m * 1024 + n);
;         else { const uint2 u = *(const uint2*)(xs + (long)m * LDX + n); r = make_float4(lo2f(u.x), hi2f(u.x), lo2f(u.y), hi2f(u.y)); }
;         float4 o;
;         o.x = r.x + acc[ni][mi][0]; o.y = r.y + acc[ni][mi][1]; o.z = r.z + acc[ni][mi][2]; o.w = r.w + acc[ni][mi][3];
;         if (out32) *(float4*)(out32 + (long)m * 1024 + n) = o;
;         else {
;           uint2 ob; ob.x = pack2(o.x, o.y); ob.y = pack2(o.z, o.w);
;           *(uint2*)(xs + (long)m * LDX + n) = ob;
;           const float q0 = lo2f(ob.x), q1 = hi2f(ob.x), q2 = lo2f(ob.y), q3 = hi2f(ob.y);
;           ss += q0 * q0 + q1 * q1 + q2 * q2 + q3 * q3;
.LBB0_80:
	s_andn2_b64 vcc, exec, s[36:37]
	v_mov_b32_e32 v0, 0
	s_cbranch_vccnz .LBB0_82
	v_cvt_pk_bf16_f32 v94, v94, v95
	v_cvt_pk_bf16_f32 v95, v96, v97
	v_lshlrev_b32_e32 v96, 16, v94
	v_and_b32_e32 v97, 0xffff0000, v94
	v_mov_b32_e32 v200, v94
	v_mov_b32_e32 v201, v95
	v_lshlrev_b32_e32 v101, 16, v95
	v_and_b32_e32 v100, 0xffff0000, v95
	v_pk_mul_f32 v[94:95], v[96:97], v[96:97]
	v_pk_mul_f32 v[96:97], v[100:101], v[100:101]
	v_add_f32_e32 v0, v94, v95
	v_add_f32_e32 v0, v97, v0
	v_add_f32_e32 v0, v96, v0

; DEVI float lo2f(unsigned u) { return __uint_as_float(u << 16); }
; DEVI float hi2f(unsigned u) { return __uint_as_float(u & 0xffff0000u); }
; DEVI void phase_resid_gemm(const Params& p, const bfu* A, int lda, int nkt, const bfu* wT, int ldb, const float* resid32,
;                            float* ssq_out, float* out32, char* lds) {
;     ...
; #pragma unroll
;       for (int ni = 0; ni < 4; ++ni) {
;         const int n = n0 + wn * 64 + ni * 16 + fq * 4;
;         float4 r;
;         if (resid32) r = *(const float4*)(resid32 + (long)m * 1024 + n);
;         else { const uint2 u = *(const uint2*)(xs + (long)m * LDX + n); r = make_float4(lo2f(u.x), hi2f(u.x), lo2f(u.y), hi2f(u.y)); }
;         float4 o;
;         o.x = r.x + acc[ni][mi][0]; o.y = r.y + acc[ni][mi][1]; o.z = r.z + acc[ni][mi][2]; o.w = r.w + acc[ni][mi][3];
;         if (out32) *(float4*)(out32 + (long)m * 1024 + n) = o;
;         else {
;           uint2 ob; ob.x = pack2(o.x, o.y); ob.y = pack2(o.z, o.w);
;           *(uint2*)(xs + (long)m * LDX + n) = ob;
;           const float q0 = lo2f(ob.x), q1 = hi2f(ob.x), q2 = lo2f(ob.y), q3 = hi2f(ob.y);
;           ss += q0 * q0 + q1 * q1 + q2 * q2 + q3 * q3;
.LBB0_84:
	s_andn2_b64 vcc, exec, s[36:37]
	s_cbranch_vccnz .LBB0_86
	v_cvt_pk_bf16_f32 v90, v90, v91
	v_cvt_pk_bf16_f32 v91, v92, v93
	v_lshlrev_b32_e32 v92, 16, v90
	v_and_b32_e32 v93, 0xffff0000, v90
	v_mov_b32_e32 v206, v90
	v_mov_b32_e32 v207, v91
	v_mov_b32_e32 v204, v200
	v_mov_b32_e32 v205, v201
	v_lshl_add_u64 v[212:213], v[102:103], 0, v[254:255]
	s_nop 0
	v_permlane16_swap_b32_e32 v204, v206
	v_permlane16_swap_b32_e32 v205, v207
	s_nop 1
	global_store_dwordx4 v[212:213], v[204:207], off
	v_lshlrev_b32_e32 v95, 16, v91
	v_and_b32_e32 v94, 0xffff0000, v91
	v_pk_mul_f32 v[90:91], v[92:93], v[92:93]
	v_pk_mul_f32 v[92:93], v[94:95], v[94:95]
	v_add_f32_e32 v90, v90, v91
	v_add_f32_e32 v90, v93, v90
	v_add_f32_e32 v90, v92, v90
	v_add_f32_e32 v0, v0, v90

; DEVI float lo2f(unsigned u) { return __uint_as_float(u << 16); }
; DEVI float hi2f(unsigned u) { return __uint_as_float(u & 0xffff0000u); }
; DEVI void phase_resid_gemm(const Params& p, const bfu* A, int lda, int nkt, const bfu* wT, int ldb, const float* resid32,
;                            float* ssq_out, float* out32, char* lds) {
;     ...
; #pragma unroll
;       for (int ni = 0; ni < 4; ++ni) {
;         const int n = n0 + wn * 64 + ni * 16 + fq * 4;
;         float4 r;
;         if (resid32) r = *(const float4*)(resid32 + (long)m * 1024 + n);
;         else { const uint2 u = *(const uint2*)(xs + (long)m * LDX + n); r = make_float4(lo2f(u.x), hi2f(u.x), lo2f(u.y), hi2f(u.y)); }
;         float4 o;
;         o.x = r.x + acc[ni][mi][0]; o.y = r.y + acc[ni][mi][1]; o.z = r.z + acc[ni][mi][2]; o.w = r.w + acc[ni][mi][3];
;         if (out32) *(float4*)(out32 + (long)m * 1024 + n) = o;
;         else {
;           uint2 ob; ob.x = pack2(o.x, o.y); ob.y = pack2(o.z, o.w);
;           *(uint2*)(xs + (long)m * LDX + n) = ob;
;           const float q0 = lo2f(ob.x), q1 = hi2f(ob.x), q2 = lo2f(ob.y), q3 = hi2f(ob.y);
;           ss += q0 * q0 + q1 * q1 + q2 * q2 + q3 * q3;
.LBB0_88:
	s_andn2_b64 vcc, exec, s[36:37]
	s_cbranch_vccnz .LBB0_90
	v_cvt_pk_bf16_f32 v86, v86, v87
	v_cvt_pk_bf16_f32 v87, v88, v89
	v_lshlrev_b32_e32 v88, 16, v86
	v_and_b32_e32 v89, 0xffff0000, v86
	v_mov_b32_e32 v200, v86
	v_mov_b32_e32 v201, v87
	v_lshlrev_b32_e32 v91, 16, v87
	v_and_b32_e32 v90, 0xffff0000, v87
	v_pk_mul_f32 v[86:87], v[88:89], v[88:89]
	v_pk_mul_f32 v[88:89], v[90:91], v[90:91]
	v_add_f32_e32 v86, v86, v87
	v_add_f32_e32 v86, v89, v86
	v_add_f32_e32 v86, v88, v86
	v_add_f32_e32 v0, v0, v86

; DEVI float lo2f(unsigned u) { return __uint_as_float(u << 16); }
; DEVI float hi2f(unsigned u) { return __uint_as_float(u & 0xffff0000u); }
; DEVI void phase_resid_gemm(const Params& p, const bfu* A, int lda, int nkt, const bfu* wT, int ldb, const float* resid32,
;                            float* ssq_out, float* out32, char* lds) {
;     ...
; #pragma unroll
;       for (int ni = 0; ni < 4; ++ni) {
;         const int n = n0 + wn * 64 + ni * 16 + fq * 4;
;         float4 r;
;         if (resid32) r = *(const float4*)(resid32 + (long)m * 1024 + n);
;         else { const uint2 u = *(const uint2*)(xs + (long)m * LDX + n); r = make_float4(lo2f(u.x), hi2f(u.x), lo2f(u.y), hi2f(u.y)); }
;         float4 o;
;         o.x = r.x + acc[ni][mi][0]; o.y = r.y + acc[ni][mi][1]; o.z = r.z + acc[ni][mi][2]; o.w = r.w + acc[ni][mi][3];
;         if (out32) *(float4*)(out32 + (long)m * 1024 + n) = o;
;         else {
;           uint2 ob; ob.x = pack2(o.x, o.y); ob.y = pack2(o.z, o.w);
;           *(uint2*)(xs + (long)m * LDX + n) = ob;
;           const float q0 = lo2f(ob.x), q1 = hi2f(ob.x), q2 = lo2f(ob.y), q3 = hi2f(ob.y);
;           ss += q0 * q0 + q1 * q1 + q2 * q2 + q3 * q3;
.LBB0_94:
	s_nop 0
	v_cvt_pk_bf16_f32 v78, v78, v79
	v_cvt_pk_bf16_f32 v79, v80, v81
	v_lshlrev_b32_e32 v80, 16, v78
	v_and_b32_e32 v81, 0xffff0000, v78
	v_mov_b32_e32 v210, v78
	v_mov_b32_e32 v211, v79
	v_mov_b32_e32 v208, v200
	v_mov_b32_e32 v209, v201
	v_lshl_add_u64 v[212:213], v[102:103], 0, v[254:255]
	s_nop 0
	v_permlane16_swap_b32_e32 v208, v210
	v_permlane16_swap_b32_e32 v209, v211
	s_nop 1
	global_store_dwordx4 v[212:213], v[208:211], off offset:64
	v_lshlrev_b32_e32 v87, 16, v79
	v_and_b32_e32 v86, 0xffff0000, v79
	v_pk_mul_f32 v[78:79], v[80:81], v[80:81]
	v_pk_mul_f32 v[80:81], v[86:87], v[86:87]
	v_add_f32_e32 v78, v78, v79
	v_add_f32_e32 v78, v81, v78
	v_add_f32_e32 v78, v80, v78
	v_add_f32_e32 v0, v0, v78
	s_and_b64 vcc, exec, s[44:45]
	s_cbranch_vccnz .LBB0_98

; DEVI float lo2f(unsigned u) { return __uint_as_float(u << 16); }
; DEVI float hi2f(unsigned u) { return __uint_as_float(u & 0xffff0000u); }
; DEVI void phase_resid_gemm(const Params& p, const bfu* A, int lda, int nkt, const bfu* wT, int ldb, const float* resid32,
;                            float* ssq_out, float* out32, char* lds) {
;     ...
; #pragma unroll
;       for (int ni = 0; ni < 4; ++ni) {
;         const int n = n0 + wn * 64 + ni * 16 + fq * 4;
;         float4 r;
;         if (resid32) r = *(const float4*)(resid32 + (long)m * 1024 + n);
;         else { const uint2 u = *(const uint2*)(xs + (long)m * LDX + n); r = make_float4(lo2f(u.x), hi2f(u.x), lo2f(u.y), hi2f(u.y)); }
;         float4 o;
;         o.x = r.x + acc[ni][mi][0]; o.y = r.y + acc[ni][mi][1]; o.z = r.z + acc[ni][mi][2]; o.w = r.w + acc[ni][mi][3];
;         if (out32) *(float4*)(out32 + (long)m * 1024 + n) = o;
;         else {
;           uint2 ob; ob.x = pack2(o.x, o.y); ob.y = pack2(o.z, o.w);
;           *(uint2*)(xs + (long)m * LDX + n) = ob;
;           const float q0 = lo2f(ob.x), q1 = hi2f(ob.x), q2 = lo2f(ob.y), q3 = hi2f(ob.y);
;           ss += q0 * q0 + q1 * q1 + q2 * q2 + q3 * q3;
.LBB0_100:
	s_andn2_b64 vcc, exec, s[36:37]
	v_mov_b32_e32 v0, 0
	s_cbranch_vccnz .LBB0_102
	v_cvt_pk_bf16_f32 v78, v78, v79
	v_cvt_pk_bf16_f32 v79, v80, v81
	v_lshlrev_b32_e32 v80, 16, v78
	v_and_b32_e32 v81, 0xffff0000, v78
	v_mov_b32_e32 v200, v78
	v_mov_b32_e32 v201, v79
	v_lshlrev_b32_e32 v85, 16, v79
	v_and_b32_e32 v84, 0xffff0000, v79
	v_pk_mul_f32 v[78:79], v[80:81], v[80:81]
	v_pk_mul_f32 v[80:81], v[84:85], v[84:85]
	v_add_f32_e32 v0, v78, v79
	v_add_f32_e32 v0, v81, v0
	v_add_f32_e32 v0, v80, v0

; DEVI float lo2f(unsigned u) { return __uint_as_float(u << 16); }
; DEVI float hi2f(unsigned u) { return __uint_as_float(u & 0xffff0000u); }
; DEVI void phase_resid_gemm(const Params& p, const bfu* A, int lda, int nkt, const bfu* wT, int ldb, const float* resid32,
;                            float* ssq_out, float* out32, char* lds) {
;     ...
; #pragma unroll
;       for (int ni = 0; ni < 4; ++ni) {
;         const int n = n0 + wn * 64 + ni * 16 + fq * 4;
;         float4 r;
;         if (resid32) r = *(const float4*)(resid32 + (long)m * 1024 + n);
;         else { const uint2 u = *(const uint2*)(xs + (long)m * LDX + n); r = make_float4(lo2f(u.x), hi2f(u.x), lo2f(u.y), hi2f(u.y)); }
;         float4 o;
;         o.x = r.x + acc[ni][mi][0]; o.y = r.y + acc[ni][mi][1]; o.z = r.z + acc[ni][mi][2]; o.w = r.w + acc[ni][mi][3];
;         if (out32) *(float4*)(out32 + (long)m * 1024 + n) = o;
;         else {
;           uint2 ob; ob.x = pack2(o.x, o.y); ob.y = pack2(o.z, o.w);
;           *(uint2*)(xs + (long)m * LDX + n) = ob;
;           const float q0 = lo2f(ob.x), q1 = hi2f(ob.x), q2 = lo2f(ob.y), q3 = hi2f(ob.y);
;           ss += q0 * q0 + q1 * q1 + q2 * q2 + q3 * q3;
.LBB0_104:
	s_andn2_b64 vcc, exec, s[36:37]
	s_cbranch_vccnz .LBB0_106
	v_cvt_pk_bf16_f32 v74, v74, v75
	v_cvt_pk_bf16_f32 v75, v76, v77
	v_lshlrev_b32_e32 v76, 16, v74
	v_and_b32_e32 v77, 0xffff0000, v74
	v_mov_b32_e32 v206, v74
	v_mov_b32_e32 v207, v75
	v_mov_b32_e32 v204, v200
	v_mov_b32_e32 v205, v201
	v_lshl_add_u64 v[212:213], v[86:87], 0, v[254:255]
	s_nop 0
	v_permlane16_swap_b32_e32 v204, v206
	v_permlane16_swap_b32_e32 v205, v207
	s_nop 1
	global_store_dwordx4 v[212:213], v[204:207], off
	v_lshlrev_b32_e32 v79, 16, v75
	v_and_b32_e32 v78, 0xffff0000, v75
	v_pk_mul_f32 v[74:75], v[76:77], v[76:77]
	v_pk_mul_f32 v[76:77], v[78:79], v[78:79]
	v_add_f32_e32 v74, v74, v75
	v_add_f32_e32 v74, v77, v74
	v_add_f32_e32 v74, v76, v74
	v_add_f32_e32 v0, v0, v74

; DEVI float lo2f(unsigned u) { return __uint_as_float(u << 16); }
; DEVI float hi2f(unsigned u) { return __uint_as_float(u & 0xffff0000u); }
; DEVI void phase_resid_gemm(const Params& p, const bfu* A, int lda, int nkt, const bfu* wT, int ldb, const float* resid32,
;                            float* ssq_out, float* out32, char* lds) {
;     ...
; #pragma unroll
;       for (int ni = 0; ni < 4; ++ni) {
;         const int n = n0 + wn * 64 + ni * 16 + fq * 4;
;         float4 r;
;         if (resid32) r = *(const float4*)(resid32 + (long)m * 1024 + n);
;         else { const uint2 u = *(const uint2*)(xs + (long)m * LDX + n); r = make_float4(lo2f(u.x), hi2f(u.x), lo2f(u.y), hi2f(u.y)); }
;         float4 o;
;         o.x = r.x + acc[ni][mi][0]; o.y = r.y + acc[ni][mi][1]; o.z = r.z + acc[ni][mi][2]; o.w = r.w + acc[ni][mi][3];
;         if (out32) *(float4*)(out32 + (long)m * 1024 + n) = o;
;         else {
;           uint2 ob; ob.x = pack2(o.x, o.y); ob.y = pack2(o.z, o.w);
;           *(uint2*)(xs + (long)m * LDX + n) = ob;
;           const float q0 = lo2f(ob.x), q1 = hi2f(ob.x), q2 = lo2f(ob.y), q3 = hi2f(ob.y);
;           ss += q0 * q0 + q1 * q1 + q2 * q2 + q3 * q3;
.LBB0_108:
	s_andn2_b64 vcc, exec, s[36:37]
	s_cbranch_vccnz .LBB0_110
	v_cvt_pk_bf16_f32 v70, v70, v71
	v_cvt_pk_bf16_f32 v71, v72, v73
	v_lshlrev_b32_e32 v72, 16, v70
	v_and_b32_e32 v73, 0xffff0000, v70
	v_mov_b32_e32 v200, v70
	v_mov_b32_e32 v201, v71
	v_lshlrev_b32_e32 v75, 16, v71
	v_and_b32_e32 v74, 0xffff0000, v71
	v_pk_mul_f32 v[70:71], v[72:73], v[72:73]
	v_pk_mul_f32 v[72:73], v[74:75], v[74:75]
	v_add_f32_e32 v70, v70, v71
	v_add_f32_e32 v70, v73, v70
	v_add_f32_e32 v70, v72, v70
	v_add_f32_e32 v0, v0, v70

; DEVI float lo2f(unsigned u) { return __uint_as_float(u << 16); }
; DEVI float hi2f(unsigned u) { return __uint_as_float(u & 0xffff0000u); }
; DEVI void phase_resid_gemm(const Params& p, const bfu* A, int lda, int nkt, const bfu* wT, int ldb, const float* resid32,
;                            float* ssq_out, float* out32, char* lds) {
;     ...
; #pragma unroll
;       for (int ni = 0; ni < 4; ++ni) {
;         const int n = n0 + wn * 64 + ni * 16 + fq * 4;
;         float4 r;
;         if (resid32) r = *(const float4*)(resid32 + (long)m * 1024 + n);
;         else { const uint2 u = *(const uint2*)(xs + (long)m * LDX + n); r = make_float4(lo2f(u.x), hi2f(u.x), lo2f(u.y), hi2f(u.y)); }
;         float4 o;
;         o.x = r.x + acc[ni][mi][0]; o.y = r.y + acc[ni][mi][1]; o.z = r.z + acc[ni][mi][2]; o.w = r.w + acc[ni][mi][3];
;         if (out32) *(float4*)(out32 + (long)m * 1024 + n) = o;
;         else {
;           uint2 ob; ob.x = pack2(o.x, o.y); ob.y = pack2(o.z, o.w);
;           *(uint2*)(xs + (long)m * LDX + n) = ob;
;           const float q0 = lo2f(ob.x), q1 = hi2f(ob.x), q2 = lo2f(ob.y), q3 = hi2f(ob.y);
;           ss += q0 * q0 + q1 * q1 + q2 * q2 + q3 * q3;
.LBB0_114:
	s_nop 0
	v_cvt_pk_bf16_f32 v62, v62, v63
	v_cvt_pk_bf16_f32 v63, v64, v65
	v_lshlrev_b32_e32 v64, 16, v62
	v_and_b32_e32 v65, 0xffff0000, v62
	v_mov_b32_e32 v210, v62
	v_mov_b32_e32 v211, v63
	v_mov_b32_e32 v208, v200
	v_mov_b32_e32 v209, v201
	v_lshl_add_u64 v[212:213], v[86:87], 0, v[254:255]
	s_nop 0
	v_permlane16_swap_b32_e32 v208, v210
	v_permlane16_swap_b32_e32 v209, v211
	s_nop 1
	global_store_dwordx4 v[212:213], v[208:211], off offset:64
	v_lshlrev_b32_e32 v71, 16, v63
	v_and_b32_e32 v70, 0xffff0000, v63
	v_pk_mul_f32 v[62:63], v[64:65], v[64:65]
	v_pk_mul_f32 v[64:65], v[70:71], v[70:71]
	v_add_f32_e32 v62, v62, v63
	v_add_f32_e32 v62, v65, v62
	v_add_f32_e32 v62, v64, v62
	v_add_f32_e32 v0, v0, v62
	s_and_b64 vcc, exec, s[44:45]
	s_cbranch_vccnz .LBB0_118

; DEVI float lo2f(unsigned u) { return __uint_as_float(u << 16); }
; DEVI float hi2f(unsigned u) { return __uint_as_float(u & 0xffff0000u); }
; DEVI void phase_resid_gemm(const Params& p, const bfu* A, int lda, int nkt, const bfu* wT, int ldb, const float* resid32,
;                            float* ssq_out, float* out32, char* lds) {
;     ...
; #pragma unroll
;       for (int ni = 0; ni < 4; ++ni) {
;         const int n = n0 + wn * 64 + ni * 16 + fq * 4;
;         float4 r;
;         if (resid32) r = *(const float4*)(resid32 + (long)m * 1024 + n);
;         else { const uint2 u = *(const uint2*)(xs + (long)m * LDX + n); r = make_float4(lo2f(u.x), hi2f(u.x), lo2f(u.y), hi2f(u.y)); }
;         float4 o;
;         o.x = r.x + acc[ni][mi][0]; o.y = r.y + acc[ni][mi][1]; o.z = r.z + acc[ni][mi][2]; o.w = r.w + acc[ni][mi][3];
;         if (out32) *(float4*)(out32 + (long)m * 1024 + n) = o;
;         else {
;           uint2 ob; ob.x = pack2(o.x, o.y); ob.y = pack2(o.z, o.w);
;           *(uint2*)(xs + (long)m * LDX + n) = ob;
;           const float q0 = lo2f(ob.x), q1 = hi2f(ob.x), q2 = lo2f(ob.y), q3 = hi2f(ob.y);
;           ss += q0 * q0 + q1 * q1 + q2 * q2 + q3 * q3;
.LBB0_120:
	s_andn2_b64 vcc, exec, s[36:37]
	v_mov_b32_e32 v0, 0
	s_cbranch_vccnz .LBB0_122
	v_cvt_pk_bf16_f32 v62, v62, v63
	v_cvt_pk_bf16_f32 v63, v64, v65
	v_lshlrev_b32_e32 v64, 16, v62
	v_and_b32_e32 v65, 0xffff0000, v62
	v_mov_b32_e32 v200, v62
	v_mov_b32_e32 v201, v63
	v_lshlrev_b32_e32 v69, 16, v63
	v_and_b32_e32 v68, 0xffff0000, v63
	v_pk_mul_f32 v[62:63], v[64:65], v[64:65]
	v_pk_mul_f32 v[64:65], v[68:69], v[68:69]
	v_add_f32_e32 v0, v62, v63
	v_add_f32_e32 v0, v65, v0
	v_add_f32_e32 v0, v64, v0

; DEVI float lo2f(unsigned u) { return __uint_as_float(u << 16); }
; DEVI float hi2f(unsigned u) { return __uint_as_float(u & 0xffff0000u); }
; DEVI void phase_resid_gemm(const Params& p, const bfu* A, int lda, int nkt, const bfu* wT, int ldb, const float* resid32,
;                            float* ssq_out, float* out32, char* lds) {
;     ...
; #pragma unroll
;       for (int ni = 0; ni < 4; ++ni) {
;         const int n = n0 + wn * 64 + ni * 16 + fq * 4;
;         float4 r;
;         if (resid32) r = *(const float4*)(resid32 + (long)m * 1024 + n);
;         else { const uint2 u = *(const uint2*)(xs + (long)m * LDX + n); r = make_float4(lo2f(u.x), hi2f(u.x), lo2f(u.y), hi2f(u.y)); }
;         float4 o;
;         o.x = r.x + acc[ni][mi][0]; o.y = r.y + acc[ni][mi][1]; o.z = r.z + acc[ni][mi][2]; o.w = r.w + acc[ni][mi][3];
;         if (out32) *(float4*)(out32 + (long)m * 1024 + n) = o;
;         else {
;           uint2 ob; ob.x = pack2(o.x, o.y); ob.y = pack2(o.z, o.w);
;           *(uint2*)(xs + (long)m * LDX + n) = ob;
;           const float q0 = lo2f(ob.x), q1 = hi2f(ob.x), q2 = lo2f(ob.y), q3 = hi2f(ob.y);
;           ss += q0 * q0 + q1 * q1 + q2 * q2 + q3 * q3;
.LBB0_124:
	s_andn2_b64 vcc, exec, s[36:37]
	s_cbranch_vccnz .LBB0_126
	v_cvt_pk_bf16_f32 v58, v58, v59
	v_cvt_pk_bf16_f32 v59, v60, v61
	v_lshlrev_b32_e32 v60, 16, v58
	v_and_b32_e32 v61, 0xffff0000, v58
	v_mov_b32_e32 v206, v58
	v_mov_b32_e32 v207, v59
	v_mov_b32_e32 v204, v200
	v_mov_b32_e32 v205, v201
	v_lshl_add_u64 v[212:213], v[70:71], 0, v[254:255]
	s_nop 0
	v_permlane16_swap_b32_e32 v204, v206
	v_permlane16_swap_b32_e32 v205, v207
	s_nop 1
	global_store_dwordx4 v[212:213], v[204:207], off
	v_lshlrev_b32_e32 v63, 16, v59
	v_and_b32_e32 v62, 0xffff0000, v59
	v_pk_mul_f32 v[58:59], v[60:61], v[60:61]
	v_pk_mul_f32 v[60:61], v[62:63], v[62:63]
	v_add_f32_e32 v58, v58, v59
	v_add_f32_e32 v58, v61, v58
	v_add_f32_e32 v58, v60, v58
	v_add_f32_e32 v0, v0, v58

; DEVI float lo2f(unsigned u) { return __uint_as_float(u << 16); }
; DEVI float hi2f(unsigned u) { return __uint_as_float(u & 0xffff0000u); }
; DEVI void phase_resid_gemm(const Params& p, const bfu* A, int lda, int nkt, const bfu* wT, int ldb, const float* resid32,
;                            float* ssq_out, float* out32, char* lds) {
;     ...
; #pragma unroll
;       for (int ni = 0; ni < 4; ++ni) {
;         const int n = n0 + wn * 64 + ni * 16 + fq * 4;
;         float4 r;
;         if (resid32) r = *(const float4*)(resid32 + (long)m * 1024 + n);
;         else { const uint2 u = *(const uint2*)(xs + (long)m * LDX + n); r = make_float4(lo2f(u.x), hi2f(u.x), lo2f(u.y), hi2f(u.y)); }
;         float4 o;
;         o.x = r.x + acc[ni][mi][0]; o.y = r.y + acc[ni][mi][1]; o.z = r.z + acc[ni][mi][2]; o.w = r.w + acc[ni][mi][3];
;         if (out32) *(float4*)(out32 + (long)m * 1024 + n) = o;
;         else {
;           uint2 ob; ob.x = pack2(o.x, o.y); ob.y = pack2(o.z, o.w);
;           *(uint2*)(xs + (long)m * LDX + n) = ob;
;           const float q0 = lo2f(ob.x), q1 = hi2f(ob.x), q2 = lo2f(ob.y), q3 = hi2f(ob.y);
;           ss += q0 * q0 + q1 * q1 + q2 * q2 + q3 * q3;
.LBB0_128:
	s_andn2_b64 vcc, exec, s[36:37]
	s_cbranch_vccnz .LBB0_130
	v_cvt_pk_bf16_f32 v54, v54, v55
	v_cvt_pk_bf16_f32 v55, v56, v57
	v_lshlrev_b32_e32 v56, 16, v54
	v_and_b32_e32 v57, 0xffff0000, v54
	v_mov_b32_e32 v200, v54
	v_mov_b32_e32 v201, v55
	v_lshlrev_b32_e32 v59, 16, v55
	v_and_b32_e32 v58, 0xffff0000, v55
	v_pk_mul_f32 v[54:55], v[56:57], v[56:57]
	v_pk_mul_f32 v[56:57], v[58:59], v[58:59]
	v_add_f32_e32 v54, v54, v55
	v_add_f32_e32 v54, v57, v54
	v_add_f32_e32 v54, v56, v54
	v_add_f32_e32 v0, v0, v54

; DEVI float lo2f(unsigned u) { return __uint_as_float(u << 16); }
; DEVI float hi2f(unsigned u) { return __uint_as_float(u & 0xffff0000u); }
; DEVI void phase_resid_gemm(const Params& p, const bfu* A, int lda, int nkt, const bfu* wT, int ldb, const float* resid32,
;                            float* ssq_out, float* out32, char* lds) {
;     ...
; #pragma unroll
;       for (int ni = 0; ni < 4; ++ni) {
;         const int n = n0 + wn * 64 + ni * 16 + fq * 4;
;         float4 r;
;         if (resid32) r = *(const float4*)(resid32 + (long)m * 1024 + n);
;         else { const uint2 u = *(const uint2*)(xs + (long)m * LDX + n); r = make_float4(lo2f(u.x), hi2f(u.x), lo2f(u.y), hi2f(u.y)); }
;         float4 o;
;         o.x = r.x + acc[ni][mi][0]; o.y = r.y + acc[ni][mi][1]; o.z = r.z + acc[ni][mi][2]; o.w = r.w + acc[ni][mi][3];
;         if (out32) *(float4*)(out32 + (long)m * 1024 + n) = o;
;         else {
;           uint2 ob; ob.x = pack2(o.x, o.y); ob.y = pack2(o.z, o.w);
;           *(uint2*)(xs + (long)m * LDX + n) = ob;
;           const float q0 = lo2f(ob.x), q1 = hi2f(ob.x), q2 = lo2f(ob.y), q3 = hi2f(ob.y);
;           ss += q0 * q0 + q1 * q1 + q2 * q2 + q3 * q3;
.LBB0_134:
	s_nop 0
	v_cvt_pk_bf16_f32 v46, v46, v47
	v_cvt_pk_bf16_f32 v47, v48, v49
	v_lshlrev_b32_e32 v48, 16, v46
	v_and_b32_e32 v49, 0xffff0000, v46
	v_mov_b32_e32 v210, v46
	v_mov_b32_e32 v211, v47
	v_mov_b32_e32 v208, v200
	v_mov_b32_e32 v209, v201
	v_lshl_add_u64 v[212:213], v[70:71], 0, v[254:255]
	s_nop 0
	v_permlane16_swap_b32_e32 v208, v210
	v_permlane16_swap_b32_e32 v209, v211
	s_nop 1
	global_store_dwordx4 v[212:213], v[208:211], off offset:64
	v_lshlrev_b32_e32 v55, 16, v47
	v_and_b32_e32 v54, 0xffff0000, v47
	v_pk_mul_f32 v[46:47], v[48:49], v[48:49]
	v_pk_mul_f32 v[48:49], v[54:55], v[54:55]
	v_add_f32_e32 v46, v46, v47
	v_add_f32_e32 v46, v49, v46
	v_add_f32_e32 v46, v48, v46
	v_add_f32_e32 v0, v0, v46
	s_and_b64 vcc, exec, s[44:45]
	s_cbranch_vccnz .LBB0_138

; DEVI float lo2f(unsigned u) { return __uint_as_float(u << 16); }
; DEVI float hi2f(unsigned u) { return __uint_as_float(u & 0xffff0000u); }
; DEVI void phase_resid_gemm(const Params& p, const bfu* A, int lda, int nkt, const bfu* wT, int ldb, const float* resid32,
;                            float* ssq_out, float* out32, char* lds) {
;     ...
; #pragma unroll
;       for (int ni = 0; ni < 4; ++ni) {
;         const int n = n0 + wn * 64 + ni * 16 + fq * 4;
;         float4 r;
;         if (resid32) r = *(const float4*)(resid32 + (long)m * 1024 + n);
;         else { const uint2 u = *(const uint2*)(xs + (long)m * LDX + n); r = make_float4(lo2f(u.x), hi2f(u.x), lo2f(u.y), hi2f(u.y)); }
;         float4 o;
;         o.x = r.x + acc[ni][mi][0]; o.y = r.y + acc[ni][mi][1]; o.z = r.z + acc[ni][mi][2]; o.w = r.w + acc[ni][mi][3];
;         if (out32) *(float4*)(out32 + (long)m * 1024 + n) = o;
;         else {
;           uint2 ob; ob.x = pack2(o.x, o.y); ob.y = pack2(o.z, o.w);
;           *(uint2*)(xs + (long)m * LDX + n) = ob;
;           const float q0 = lo2f(ob.x), q1 = hi2f(ob.x), q2 = lo2f(ob.y), q3 = hi2f(ob.y);
;           ss += q0 * q0 + q1 * q1 + q2 * q2 + q3 * q3;
.LBB0_140:
	s_andn2_b64 vcc, exec, s[36:37]
	v_mov_b32_e32 v0, 0
	s_cbranch_vccnz .LBB0_142
	v_cvt_pk_bf16_f32 v46, v46, v47
	v_cvt_pk_bf16_f32 v47, v48, v49
	v_lshlrev_b32_e32 v48, 16, v46
	v_and_b32_e32 v49, 0xffff0000, v46
	v_mov_b32_e32 v200, v46
	v_mov_b32_e32 v201, v47
	v_lshlrev_b32_e32 v53, 16, v47
	v_and_b32_e32 v52, 0xffff0000, v47
	v_pk_mul_f32 v[46:47], v[48:49], v[48:49]
	v_pk_mul_f32 v[48:49], v[52:53], v[52:53]
	v_add_f32_e32 v0, v46, v47
	v_add_f32_e32 v0, v49, v0
	v_add_f32_e32 v0, v48, v0

; DEVI float lo2f(unsigned u) { return __uint_as_float(u << 16); }
; DEVI float hi2f(unsigned u) { return __uint_as_float(u & 0xffff0000u); }
; DEVI void phase_resid_gemm(const Params& p, const bfu* A, int lda, int nkt, const bfu* wT, int ldb, const float* resid32,
;                            float* ssq_out, float* out32, char* lds) {
;     ...
; #pragma unroll
;       for (int ni = 0; ni < 4; ++ni) {
;         const int n = n0 + wn * 64 + ni * 16 + fq * 4;
;         float4 r;
;         if (resid32) r = *(const float4*)(resid32 + (long)m * 1024 + n);
;         else { const uint2 u = *(const uint2*)(xs + (long)m * LDX + n); r = make_float4(lo2f(u.x), hi2f(u.x), lo2f(u.y), hi2f(u.y)); }
;         float4 o;
;         o.x = r.x + acc[ni][mi][0]; o.y = r.y + acc[ni][mi][1]; o.z = r.z + acc[ni][mi][2]; o.w = r.w + acc[ni][mi][3];
;         if (out32) *(float4*)(out32 + (long)m * 1024 + n) = o;
;         else {
;           uint2 ob; ob.x = pack2(o.x, o.y); ob.y = pack2(o.z, o.w);
;           *(uint2*)(xs + (long)m * LDX + n) = ob;
;           const float q0 = lo2f(ob.x), q1 = hi2f(ob.x), q2 = lo2f(ob.y), q3 = hi2f(ob.y);
;           ss += q0 * q0 + q1 * q1 + q2 * q2 + q3 * q3;
.LBB0_144:
	s_andn2_b64 vcc, exec, s[36:37]
	s_cbranch_vccnz .LBB0_146
	v_cvt_pk_bf16_f32 v42, v42, v43
	v_cvt_pk_bf16_f32 v43, v44, v45
	v_lshlrev_b32_e32 v44, 16, v42
	v_and_b32_e32 v45, 0xffff0000, v42
	v_mov_b32_e32 v206, v42
	v_mov_b32_e32 v207, v43
	v_mov_b32_e32 v204, v200
	v_mov_b32_e32 v205, v201
	v_lshl_add_u64 v[212:213], v[54:55], 0, v[254:255]
	s_nop 0
	v_permlane16_swap_b32_e32 v204, v206
	v_permlane16_swap_b32_e32 v205, v207
	s_nop 1
	global_store_dwordx4 v[212:213], v[204:207], off
	v_lshlrev_b32_e32 v47, 16, v43
	v_and_b32_e32 v46, 0xffff0000, v43
	v_pk_mul_f32 v[42:43], v[44:45], v[44:45]
	v_pk_mul_f32 v[44:45], v[46:47], v[46:47]
	v_add_f32_e32 v42, v42, v43
	v_add_f32_e32 v42, v45, v42
	v_add_f32_e32 v42, v44, v42
	v_add_f32_e32 v0, v0, v42

; DEVI float lo2f(unsigned u) { return __uint_as_float(u << 16); }
; DEVI float hi2f(unsigned u) { return __uint_as_float(u & 0xffff0000u); }
; DEVI void phase_resid_gemm(const Params& p, const bfu* A, int lda, int nkt, const bfu* wT, int ldb, const float* resid32,
;                            float* ssq_out, float* out32, char* lds) {
;     ...
; #pragma unroll
;       for (int ni = 0; ni < 4; ++ni) {
;         const int n = n0 + wn * 64 + ni * 16 + fq * 4;
;         float4 r;
;         if (resid32) r = *(const float4*)(resid32 + (long)m * 1024 + n);
;         else { const uint2 u = *(const uint2*)(xs + (long)m * LDX + n); r = make_float4(lo2f(u.x), hi2f(u.x), lo2f(u.y), hi2f(u.y)); }
;         float4 o;
;         o.x = r.x + acc[ni][mi][0]; o.y = r.y + acc[ni][mi][1]; o.z = r.z + acc[ni][mi][2]; o.w = r.w + acc[ni][mi][3];
;         if (out32) *(float4*)(out32 + (long)m * 1024 + n) = o;
;         else {
;           uint2 ob; ob.x = pack2(o.x, o.y); ob.y = pack2(o.z, o.w);
;           *(uint2*)(xs + (long)m * LDX + n) = ob;
;           const float q0 = lo2f(ob.x), q1 = hi2f(ob.x), q2 = lo2f(ob.y), q3 = hi2f(ob.y);
;           ss += q0 * q0 + q1 * q1 + q2 * q2 + q3 * q3;
.LBB0_148:
	s_andn2_b64 vcc, exec, s[36:37]
	s_cbranch_vccnz .LBB0_150
	v_cvt_pk_bf16_f32 v38, v38, v39
	v_cvt_pk_bf16_f32 v39, v40, v41
	v_lshlrev_b32_e32 v40, 16, v38
	v_and_b32_e32 v41, 0xffff0000, v38
	v_mov_b32_e32 v200, v38
	v_mov_b32_e32 v201, v39
	v_lshlrev_b32_e32 v43, 16, v39
	v_and_b32_e32 v42, 0xffff0000, v39
	v_pk_mul_f32 v[38:39], v[40:41], v[40:41]
	v_pk_mul_f32 v[40:41], v[42:43], v[42:43]
	v_add_f32_e32 v38, v38, v39
	v_add_f32_e32 v38, v41, v38
	v_add_f32_e32 v38, v40, v38
	v_add_f32_e32 v0, v0, v38

; DEVI float lo2f(unsigned u) { return __uint_as_float(u << 16); }
; DEVI float hi2f(unsigned u) { return __uint_as_float(u & 0xffff0000u); }
; DEVI void phase_resid_gemm(const Params& p, const bfu* A, int lda, int nkt, const bfu* wT, int ldb, const float* resid32,
;                            float* ssq_out, float* out32, char* lds) {
;     ...
; #pragma unroll
;       for (int ni = 0; ni < 4; ++ni) {
;         const int n = n0 + wn * 64 + ni * 16 + fq * 4;
;         float4 r;
;         if (resid32) r = *(const float4*)(resid32 + (long)m * 1024 + n);
;         else { const uint2 u = *(const uint2*)(xs + (long)m * LDX + n); r = make_float4(lo2f(u.x), hi2f(u.x), lo2f(u.y), hi2f(u.y)); }
;         float4 o;
;         o.x = r.x + acc[ni][mi][0]; o.y = r.y + acc[ni][mi][1]; o.z = r.z + acc[ni][mi][2]; o.w = r.w + acc[ni][mi][3];
;         if (out32) *(float4*)(out32 + (long)m * 1024 + n) = o;
;         else {
;           uint2 ob; ob.x = pack2(o.x, o.y); ob.y = pack2(o.z, o.w);
;           *(uint2*)(xs + (long)m * LDX + n) = ob;
;           const float q0 = lo2f(ob.x), q1 = hi2f(ob.x), q2 = lo2f(ob.y), q3 = hi2f(ob.y);
;           ss += q0 * q0 + q1 * q1 + q2 * q2 + q3 * q3;
.LBB0_154:
	s_nop 0
	v_cvt_pk_bf16_f32 v30, v30, v31
	v_cvt_pk_bf16_f32 v31, v32, v33
	v_lshlrev_b32_e32 v32, 16, v30
	v_and_b32_e32 v33, 0xffff0000, v30
	v_mov_b32_e32 v210, v30
	v_mov_b32_e32 v211, v31
	v_mov_b32_e32 v208, v200
	v_mov_b32_e32 v209, v201
	v_lshl_add_u64 v[212:213], v[54:55], 0, v[254:255]
	s_nop 0
	v_permlane16_swap_b32_e32 v208, v210
	v_permlane16_swap_b32_e32 v209, v211
	s_nop 1
	global_store_dwordx4 v[212:213], v[208:211], off offset:64
	v_lshlrev_b32_e32 v39, 16, v31
	v_and_b32_e32 v38, 0xffff0000, v31
	v_pk_mul_f32 v[30:31], v[32:33], v[32:33]
	v_pk_mul_f32 v[32:33], v[38:39], v[38:39]
	v_add_f32_e32 v30, v30, v31
	v_add_f32_e32 v30, v33, v30
	v_add_f32_e32 v30, v32, v30
	v_add_f32_e32 v0, v0, v30
	s_and_b64 vcc, exec, s[44:45]
	s_cbranch_vccnz .LBB0_158

; DEVI float lo2f(unsigned u) { return __uint_as_float(u << 16); }
; DEVI float hi2f(unsigned u) { return __uint_as_float(u & 0xffff0000u); }
; DEVI void phase_resid_gemm(const Params& p, const bfu* A, int lda, int nkt, const bfu* wT, int ldb, const float* resid32,
;                            float* ssq_out, float* out32, char* lds) {
;     ...
; #pragma unroll
;       for (int ni = 0; ni < 4; ++ni) {
;         const int n = n0 + wn * 64 + ni * 16 + fq * 4;
;         float4 r;
;         if (resid32) r = *(const float4*)(resid32 + (long)m * 1024 + n);
;         else { const uint2 u = *(const uint2*)(xs + (long)m * LDX + n); r = make_float4(lo2f(u.x), hi2f(u.x), lo2f(u.y), hi2f(u.y)); }
;         float4 o;
;         o.x = r.x + acc[ni][mi][0]; o.y = r.y + acc[ni][mi][1]; o.z = r.z + acc[ni][mi][2]; o.w = r.w + acc[ni][mi][3];
;         if (out32) *(float4*)(out32 + (long)m * 1024 + n) = o;
;         else {
;           uint2 ob; ob.x = pack2(o.x, o.y); ob.y = pack2(o.z, o.w);
;           *(uint2*)(xs + (long)m * LDX + n) = ob;
;           const float q0 = lo2f(ob.x), q1 = hi2f(ob.x), q2 = lo2f(ob.y), q3 = hi2f(ob.y);
;           ss += q0 * q0 + q1 * q1 + q2 * q2 + q3 * q3;
.LBB0_160:
	v_mov_b32_e32 v0, 0
	s_andn2_b64 vcc, exec, s[36:37]
	s_cbranch_vccnz .LBB0_162
	v_cvt_pk_bf16_f32 v30, v30, v31
	v_cvt_pk_bf16_f32 v31, v32, v33
	v_lshlrev_b32_e32 v32, 16, v30
	v_and_b32_e32 v33, 0xffff0000, v30
	v_mov_b32_e32 v200, v30
	v_mov_b32_e32 v201, v31
	v_lshlrev_b32_e32 v37, 16, v31
	v_and_b32_e32 v36, 0xffff0000, v31
	v_pk_mul_f32 v[30:31], v[32:33], v[32:33]
	v_pk_mul_f32 v[32:33], v[36:37], v[36:37]
	v_add_f32_e32 v0, v30, v31
	v_add_f32_e32 v0, v33, v0
	v_add_f32_e32 v0, v32, v0

; DEVI float lo2f(unsigned u) { return __uint_as_float(u << 16); }
; DEVI float hi2f(unsigned u) { return __uint_as_float(u & 0xffff0000u); }
; DEVI void phase_resid_gemm(const Params& p, const bfu* A, int lda, int nkt, const bfu* wT, int ldb, const float* resid32,
;                            float* ssq_out, float* out32, char* lds) {
;     ...
; #pragma unroll
;       for (int ni = 0; ni < 4; ++ni) {
;         const int n = n0 + wn * 64 + ni * 16 + fq * 4;
;         float4 r;
;         if (resid32) r = *(const float4*)(resid32 + (long)m * 1024 + n);
;         else { const uint2 u = *(const uint2*)(xs + (long)m * LDX + n); r = make_float4(lo2f(u.x), hi2f(u.x), lo2f(u.y), hi2f(u.y)); }
;         float4 o;
;         o.x = r.x + acc[ni][mi][0]; o.y = r.y + acc[ni][mi][1]; o.z = r.z + acc[ni][mi][2]; o.w = r.w + acc[ni][mi][3];
;         if (out32) *(float4*)(out32 + (long)m * 1024 + n) = o;
;         else {
;           uint2 ob; ob.x = pack2(o.x, o.y); ob.y = pack2(o.z, o.w);
;           *(uint2*)(xs + (long)m * LDX + n) = ob;
;           const float q0 = lo2f(ob.x), q1 = hi2f(ob.x), q2 = lo2f(ob.y), q3 = hi2f(ob.y);
;           ss += q0 * q0 + q1 * q1 + q2 * q2 + q3 * q3;
.LBB0_164:
	s_andn2_b64 vcc, exec, s[36:37]
	s_cbranch_vccnz .LBB0_166
	v_cvt_pk_bf16_f32 v26, v26, v27
	v_cvt_pk_bf16_f32 v27, v28, v29
	v_lshlrev_b32_e32 v28, 16, v26
	v_and_b32_e32 v29, 0xffff0000, v26
	v_mov_b32_e32 v206, v26
	v_mov_b32_e32 v207, v27
	v_mov_b32_e32 v204, v200
	v_mov_b32_e32 v205, v201
	v_lshl_add_u64 v[212:213], v[38:39], 0, v[254:255]
	s_nop 0
	v_permlane16_swap_b32_e32 v204, v206
	v_permlane16_swap_b32_e32 v205, v207
	s_nop 1
	global_store_dwordx4 v[212:213], v[204:207], off
	v_lshlrev_b32_e32 v31, 16, v27
	v_and_b32_e32 v30, 0xffff0000, v27
	v_pk_mul_f32 v[26:27], v[28:29], v[28:29]
	v_pk_mul_f32 v[28:29], v[30:31], v[30:31]
	v_add_f32_e32 v26, v26, v27
	v_add_f32_e32 v26, v29, v26
	v_add_f32_e32 v26, v28, v26
	v_add_f32_e32 v0, v0, v26

; DEVI float lo2f(unsigned u) { return __uint_as_float(u << 16); }
; DEVI float hi2f(unsigned u) { return __uint_as_float(u & 0xffff0000u); }
; DEVI void phase_resid_gemm(const Params& p, const bfu* A, int lda, int nkt, const bfu* wT, int ldb, const float* resid32,
;                            float* ssq_out, float* out32, char* lds) {
;     ...
; #pragma unroll
;       for (int ni = 0; ni < 4; ++ni) {
;         const int n = n0 + wn * 64 + ni * 16 + fq * 4;
;         float4 r;
;         if (resid32) r = *(const float4*)(resid32 + (long)m * 1024 + n);
;         else { const uint2 u = *(const uint2*)(xs + (long)m * LDX + n); r = make_float4(lo2f(u.x), hi2f(u.x), lo2f(u.y), hi2f(u.y)); }
;         float4 o;
;         o.x = r.x + acc[ni][mi][0]; o.y = r.y + acc[ni][mi][1]; o.z = r.z + acc[ni][mi][2]; o.w = r.w + acc[ni][mi][3];
;         if (out32) *(float4*)(out32 + (long)m * 1024 + n) = o;
;         else {
;           uint2 ob; ob.x = pack2(o.x, o.y); ob.y = pack2(o.z, o.w);
;           *(uint2*)(xs + (long)m * LDX + n) = ob;
;           const float q0 = lo2f(ob.x), q1 = hi2f(ob.x), q2 = lo2f(ob.y), q3 = hi2f(ob.y);
;           ss += q0 * q0 + q1 * q1 + q2 * q2 + q3 * q3;
.LBB0_168:
	s_andn2_b64 vcc, exec, s[36:37]
	s_cbranch_vccnz .LBB0_170
	v_cvt_pk_bf16_f32 v22, v22, v23
	v_cvt_pk_bf16_f32 v23, v24, v25
	v_lshlrev_b32_e32 v24, 16, v22
	v_and_b32_e32 v25, 0xffff0000, v22
	v_mov_b32_e32 v200, v22
	v_mov_b32_e32 v201, v23
	v_lshlrev_b32_e32 v27, 16, v23
	v_and_b32_e32 v26, 0xffff0000, v23
	v_pk_mul_f32 v[22:23], v[24:25], v[24:25]
	v_pk_mul_f32 v[24:25], v[26:27], v[26:27]
	v_add_f32_e32 v22, v22, v23
	v_add_f32_e32 v22, v25, v22
	v_add_f32_e32 v22, v24, v22
	v_add_f32_e32 v0, v0, v22

; DEVI float lo2f(unsigned u) { return __uint_as_float(u << 16); }
; DEVI float hi2f(unsigned u) { return __uint_as_float(u & 0xffff0000u); }
; DEVI void phase_resid_gemm(const Params& p, const bfu* A, int lda, int nkt, const bfu* wT, int ldb, const float* resid32,
;                            float* ssq_out, float* out32, char* lds) {
;     ...
; #pragma unroll
;       for (int ni = 0; ni < 4; ++ni) {
;         const int n = n0 + wn * 64 + ni * 16 + fq * 4;
;         float4 r;
;         if (resid32) r = *(const float4*)(resid32 + (long)m * 1024 + n);
;         else { const uint2 u = *(const uint2*)(xs + (long)m * LDX + n); r = make_float4(lo2f(u.x), hi2f(u.x), lo2f(u.y), hi2f(u.y)); }
;         float4 o;
;         o.x = r.x + acc[ni][mi][0]; o.y = r.y + acc[ni][mi][1]; o.z = r.z + acc[ni][mi][2]; o.w = r.w + acc[ni][mi][3];
;         if (out32) *(float4*)(out32 + (long)m * 1024 + n) = o;
;         else {
;           uint2 ob; ob.x = pack2(o.x, o.y); ob.y = pack2(o.z, o.w);
;           *(uint2*)(xs + (long)m * LDX + n) = ob;
;           const float q0 = lo2f(ob.x), q1 = hi2f(ob.x), q2 = lo2f(ob.y), q3 = hi2f(ob.y);
;           ss += q0 * q0 + q1 * q1 + q2 * q2 + q3 * q3;
.LBB0_174:
	s_nop 0
	v_cvt_pk_bf16_f32 v18, v18, v19
	v_cvt_pk_bf16_f32 v19, v20, v21
	v_lshlrev_b32_e32 v20, 16, v18
	v_and_b32_e32 v21, 0xffff0000, v18
	v_mov_b32_e32 v210, v18
	v_mov_b32_e32 v211, v19
	v_mov_b32_e32 v208, v200
	v_mov_b32_e32 v209, v201
	v_lshl_add_u64 v[212:213], v[38:39], 0, v[254:255]
	s_nop 0
	v_permlane16_swap_b32_e32 v208, v210
	v_permlane16_swap_b32_e32 v209, v211
	s_nop 1
	global_store_dwordx4 v[212:213], v[208:211], off offset:64
	v_lshlrev_b32_e32 v23, 16, v19
	v_and_b32_e32 v22, 0xffff0000, v19
	v_pk_mul_f32 v[18:19], v[20:21], v[20:21]
	v_pk_mul_f32 v[20:21], v[22:23], v[22:23]
	v_add_f32_e32 v18, v18, v19
	v_add_f32_e32 v18, v21, v18
	v_add_f32_e32 v18, v20, v18
	v_add_f32_e32 v0, v0, v18
	s_and_b64 vcc, exec, s[44:45]
	s_cbranch_vccnz .LBB0_178

; DEVI float lo2f(unsigned u) { return __uint_as_float(u << 16); }
; DEVI float hi2f(unsigned u) { return __uint_as_float(u & 0xffff0000u); }
; DEVI void phase_resid_gemm(const Params& p, const bfu* A, int lda, int nkt, const bfu* wT, int ldb, const float* resid32,
;                            float* ssq_out, float* out32, char* lds) {
;     ...
; #pragma unroll
;       for (int ni = 0; ni < 4; ++ni) {
;         const int n = n0 + wn * 64 + ni * 16 + fq * 4;
;         float4 r;
;         if (resid32) r = *(const float4*)(resid32 + (long)m * 1024 + n);
;         else { const uint2 u = *(const uint2*)(xs + (long)m * LDX + n); r = make_float4(lo2f(u.x), hi2f(u.x), lo2f(u.y), hi2f(u.y)); }
;         float4 o;
;         o.x = r.x + acc[ni][mi][0]; o.y = r.y + acc[ni][mi][1]; o.z = r.z + acc[ni][mi][2]; o.w = r.w + acc[ni][mi][3];
;         if (out32) *(float4*)(out32 + (long)m * 1024 + n) = o;
;         else {
;           uint2 ob; ob.x = pack2(o.x, o.y); ob.y = pack2(o.z, o.w);
;           *(uint2*)(xs + (long)m * LDX + n) = ob;
;           const float q0 = lo2f(ob.x), q1 = hi2f(ob.x), q2 = lo2f(ob.y), q3 = hi2f(ob.y);
;           ss += q0 * q0 + q1 * q1 + q2 * q2 + q3 * q3;
.LBB0_180:
	v_mov_b32_e32 v0, 0
	s_andn2_b64 vcc, exec, s[36:37]
	s_cbranch_vccnz .LBB0_182
	v_cvt_pk_bf16_f32 v14, v14, v15
	v_cvt_pk_bf16_f32 v15, v16, v17
	v_lshlrev_b32_e32 v16, 16, v14
	v_and_b32_e32 v17, 0xffff0000, v14
	v_mov_b32_e32 v200, v14
	v_mov_b32_e32 v201, v15
	v_lshlrev_b32_e32 v23, 16, v15
	v_and_b32_e32 v22, 0xffff0000, v15
	v_pk_mul_f32 v[14:15], v[16:17], v[16:17]
	v_pk_mul_f32 v[16:17], v[22:23], v[22:23]
	v_add_f32_e32 v0, v14, v15
	v_add_f32_e32 v0, v17, v0
	v_add_f32_e32 v0, v16, v0

; DEVI float lo2f(unsigned u) { return __uint_as_float(u << 16); }
; DEVI float hi2f(unsigned u) { return __uint_as_float(u & 0xffff0000u); }
; DEVI void phase_resid_gemm(const Params& p, const bfu* A, int lda, int nkt, const bfu* wT, int ldb, const float* resid32,
;                            float* ssq_out, float* out32, char* lds) {
;     ...
; #pragma unroll
;       for (int ni = 0; ni < 4; ++ni) {
;         const int n = n0 + wn * 64 + ni * 16 + fq * 4;
;         float4 r;
;         if (resid32) r = *(const float4*)(resid32 + (long)m * 1024 + n);
;         else { const uint2 u = *(const uint2*)(xs + (long)m * LDX + n); r = make_float4(lo2f(u.x), hi2f(u.x), lo2f(u.y), hi2f(u.y)); }
;         float4 o;
;         o.x = r.x + acc[ni][mi][0]; o.y = r.y + acc[ni][mi][1]; o.z = r.z + acc[ni][mi][2]; o.w = r.w + acc[ni][mi][3];
;         if (out32) *(float4*)(out32 + (long)m * 1024 + n) = o;
;         else {
;           uint2 ob; ob.x = pack2(o.x, o.y); ob.y = pack2(o.z, o.w);
;           *(uint2*)(xs + (long)m * LDX + n) = ob;
;           const float q0 = lo2f(ob.x), q1 = hi2f(ob.x), q2 = lo2f(ob.y), q3 = hi2f(ob.y);
;           ss += q0 * q0 + q1 * q1 + q2 * q2 + q3 * q3;
.LBB0_184:
	s_andn2_b64 vcc, exec, s[36:37]
	s_cbranch_vccnz .LBB0_186
	v_cvt_pk_bf16_f32 v10, v10, v11
	v_cvt_pk_bf16_f32 v11, v12, v13
	v_lshlrev_b32_e32 v12, 16, v10
	v_and_b32_e32 v13, 0xffff0000, v10
	v_mov_b32_e32 v206, v10
	v_mov_b32_e32 v207, v11
	v_mov_b32_e32 v204, v200
	v_mov_b32_e32 v205, v201
	v_lshl_add_u64 v[212:213], v[18:19], 0, v[254:255]
	s_nop 0
	v_permlane16_swap_b32_e32 v204, v206
	v_permlane16_swap_b32_e32 v205, v207
	s_nop 1
	global_store_dwordx4 v[212:213], v[204:207], off
	v_lshlrev_b32_e32 v15, 16, v11
	v_and_b32_e32 v14, 0xffff0000, v11
	v_pk_mul_f32 v[10:11], v[12:13], v[12:13]
	v_pk_mul_f32 v[12:13], v[14:15], v[14:15]
	v_add_f32_e32 v10, v10, v11
	v_add_f32_e32 v10, v13, v10
	v_add_f32_e32 v10, v12, v10
	v_add_f32_e32 v0, v0, v10

; DEVI float lo2f(unsigned u) { return __uint_as_float(u << 16); }
; DEVI float hi2f(unsigned u) { return __uint_as_float(u & 0xffff0000u); }
; DEVI void phase_resid_gemm(const Params& p, const bfu* A, int lda, int nkt, const bfu* wT, int ldb, const float* resid32,
;                            float* ssq_out, float* out32, char* lds) {
;     ...
; #pragma unroll
;       for (int ni = 0; ni < 4; ++ni) {
;         const int n = n0 + wn * 64 + ni * 16 + fq * 4;
;         float4 r;
;         if (resid32) r = *(const float4*)(resid32 + (long)m * 1024 + n);
;         else { const uint2 u = *(const uint2*)(xs + (long)m * LDX + n); r = make_float4(lo2f(u.x), hi2f(u.x), lo2f(u.y), hi2f(u.y)); }
;         float4 o;
;         o.x = r.x + acc[ni][mi][0]; o.y = r.y + acc[ni][mi][1]; o.z = r.z + acc[ni][mi][2]; o.w = r.w + acc[ni][mi][3];
;         if (out32) *(float4*)(out32 + (long)m * 1024 + n) = o;
;         else {
;           uint2 ob; ob.x = pack2(o.x, o.y); ob.y = pack2(o.z, o.w);
;           *(uint2*)(xs + (long)m * LDX + n) = ob;
;           const float q0 = lo2f(ob.x), q1 = hi2f(ob.x), q2 = lo2f(ob.y), q3 = hi2f(ob.y);
;           ss += q0 * q0 + q1 * q1 + q2 * q2 + q3 * q3;
.LBB0_188:
	s_andn2_b64 vcc, exec, s[36:37]
	s_cbranch_vccnz .LBB0_190
	v_cvt_pk_bf16_f32 v6, v6, v7
	v_cvt_pk_bf16_f32 v7, v8, v9
	v_lshlrev_b32_e32 v8, 16, v6
	v_and_b32_e32 v9, 0xffff0000, v6
	v_mov_b32_e32 v200, v6
	v_mov_b32_e32 v201, v7
	v_lshlrev_b32_e32 v11, 16, v7
	v_and_b32_e32 v10, 0xffff0000, v7
	v_pk_mul_f32 v[6:7], v[8:9], v[8:9]
	v_pk_mul_f32 v[8:9], v[10:11], v[10:11]
	v_add_f32_e32 v6, v6, v7
	v_add_f32_e32 v6, v9, v6
	v_add_f32_e32 v6, v8, v6
	v_add_f32_e32 v0, v0, v6

; DEVI float lo2f(unsigned u) { return __uint_as_float(u << 16); }
; DEVI float hi2f(unsigned u) { return __uint_as_float(u & 0xffff0000u); }
; DEVI void phase_resid_gemm(const Params& p, const bfu* A, int lda, int nkt, const bfu* wT, int ldb, const float* resid32,
;                            float* ssq_out, float* out32, char* lds) {
;     ...
; #pragma unroll
;       for (int ni = 0; ni < 4; ++ni) {
;         const int n = n0 + wn * 64 + ni * 16 + fq * 4;
;         float4 r;
;         if (resid32) r = *(const float4*)(resid32 + (long)m * 1024 + n);
;         else { const uint2 u = *(const uint2*)(xs + (long)m * LDX + n); r = make_float4(lo2f(u.x), hi2f(u.x), lo2f(u.y), hi2f(u.y)); }
;         float4 o;
;         o.x = r.x + acc[ni][mi][0]; o.y = r.y + acc[ni][mi][1]; o.z = r.z + acc[ni][mi][2]; o.w = r.w + acc[ni][mi][3];
;         if (out32) *(float4*)(out32 + (long)m * 1024 + n) = o;
;         else {
;           uint2 ob; ob.x = pack2(o.x, o.y); ob.y = pack2(o.z, o.w);
;           *(uint2*)(xs + (long)m * LDX + n) = ob;
;           const float q0 = lo2f(ob.x), q1 = hi2f(ob.x), q2 = lo2f(ob.y), q3 = hi2f(ob.y);
;           ss += q0 * q0 + q1 * q1 + q2 * q2 + q3 * q3;
.LBB0_194:
	s_nop 0
	v_cvt_pk_bf16_f32 v2, v2, v3
	v_cvt_pk_bf16_f32 v3, v4, v5
	v_lshlrev_b32_e32 v4, 16, v2
	v_and_b32_e32 v5, 0xffff0000, v2
	v_mov_b32_e32 v210, v2
	v_mov_b32_e32 v211, v3
	v_mov_b32_e32 v208, v200
	v_mov_b32_e32 v209, v201
	v_lshl_add_u64 v[212:213], v[18:19], 0, v[254:255]
	s_nop 0
	v_permlane16_swap_b32_e32 v208, v210
	v_permlane16_swap_b32_e32 v209, v211
	s_nop 1
	global_store_dwordx4 v[212:213], v[208:211], off offset:64
	v_lshlrev_b32_e32 v7, 16, v3
	v_and_b32_e32 v6, 0xffff0000, v3
	v_pk_mul_f32 v[2:3], v[4:5], v[4:5]
	v_pk_mul_f32 v[4:5], v[6:7], v[6:7]
	v_add_f32_e32 v2, v2, v3
	v_add_f32_e32 v2, v5, v2
	v_add_f32_e32 v2, v4, v2
	v_add_f32_e32 v0, v0, v2
	s_and_b64 vcc, exec, s[44:45]
	s_cbranch_vccnz .LBB0_21

; DEVI void phase7(const Params& p, int l, char* lds) {
;     ...
;     float rs8[8];
; #pragma unroll
;     for (int mi = 0; mi < 8; ++mi) rs8[mi] = rsS[wm * 128 + mi * 16 + fr];
; #pragma unroll
;     for (int ni = 0; ni < 4; ++ni)
; #pragma unroll
;       for (int mi = 0; mi < 8; ++mi) {
;         f32x4 v = acc[ni][mi];
; #pragma unroll
;         for (int j = 0; j < 4; ++j) { float r = fmaxf(v[j] * rs8[mi], 0.f); v[j] = r * r; }
;         int n = n0 + wn * 64 + ni * 16 + fq * 4;
;         int m = m0 + wm * 128 + mi * 16 + fr;
;         store_bf4(hid + (long)m * LDH + n, v);
;       }
.LBB0_204:
	v_lshlrev_b32_e32 v0, 2, v179
	v_add3_u32 v0, s44, v181, v0
	ds_read2_b32 v[120:121], v0 offset1:16
	ds_read2_b32 v[118:119], v0 offset0:32 offset1:48
	ds_read2_b32 v[116:117], v0 offset0:64 offset1:80
	ds_read2_b32 v[114:115], v0 offset0:96 offset1:112
	v_or_b32_e32 v122, s45, v183
	v_ashrrev_i32_e32 v123, 31, v122
	v_lshl_add_u64 v[134:135], v[122:123], 1, s[6:7]
	s_waitcnt lgkmcnt(0)
	v_mul_f32_e32 v122, v162, v120
	v_mul_f32_e32 v123, v163, v120
	v_max_f32_e32 v122, 0, v122
	v_max_f32_e32 v123, 0, v123
	v_pk_mul_f32 v[124:125], v[122:123], v[122:123]
	v_mul_f32_e32 v122, v164, v120
	v_mul_f32_e32 v123, v165, v120
	v_max_f32_e32 v122, 0, v122
	v_max_f32_e32 v123, 0, v123
	v_add_u32_e32 v0, s28, v184
	v_pk_mul_f32 v[126:127], v[122:123], v[122:123]
	s_movk_i32 s20, 0x2080
	v_mad_i64_i32 v[122:123], s[4:5], v0, s20, v[134:135]
	v_cvt_pk_bf16_f32 v124, v124, v125
	v_cvt_pk_bf16_f32 v125, v126, v127
	v_mov_b32_e32 v234, v124
	v_mov_b32_e32 v235, v125
	v_mul_f32_e32 v124, v158, v121
	v_mul_f32_e32 v125, v159, v121
	v_max_f32_e32 v124, 0, v124
	v_max_f32_e32 v125, 0, v125
	v_pk_mul_f32 v[126:127], v[124:125], v[124:125]
	v_mul_f32_e32 v124, v160, v121
	v_mul_f32_e32 v125, v161, v121
	v_max_f32_e32 v124, 0, v124
	v_max_f32_e32 v125, 0, v125
	v_pk_mul_f32 v[128:129], v[124:125], v[124:125]
	v_or_b32_e32 v124, 16, v0
	v_mad_i64_i32 v[124:125], s[4:5], v124, s20, v[134:135]
	v_cvt_pk_bf16_f32 v126, v126, v127
	v_cvt_pk_bf16_f32 v127, v128, v129
	v_mov_b32_e32 v236, v126
	v_mov_b32_e32 v237, v127
	v_mul_f32_e32 v126, v150, v118
	v_mul_f32_e32 v127, v151, v118
	v_max_f32_e32 v126, 0, v126
	v_max_f32_e32 v127, 0, v127
	v_pk_mul_f32 v[128:129], v[126:127], v[126:127]
	v_mul_f32_e32 v126, v152, v118
	v_mul_f32_e32 v127, v153, v118
	v_max_f32_e32 v126, 0, v126
	v_max_f32_e32 v127, 0, v127
	v_pk_mul_f32 v[136:137], v[126:127], v[126:127]
	v_or_b32_e32 v126, 32, v0
	v_mad_i64_i32 v[126:127], s[4:5], v126, s20, v[134:135]
	v_cvt_pk_bf16_f32 v128, v128, v129
	v_cvt_pk_bf16_f32 v129, v136, v137
	v_mov_b32_e32 v238, v128
	v_mov_b32_e32 v239, v129
	v_mul_f32_e32 v128, v130, v119
	v_mul_f32_e32 v129, v131, v119
	v_max_f32_e32 v128, 0, v128
	v_max_f32_e32 v129, 0, v129
	v_pk_mul_f32 v[130:131], v[128:129], v[128:129]
	v_mul_f32_e32 v128, v132, v119
	v_mul_f32_e32 v129, v133, v119
	v_max_f32_e32 v128, 0, v128
	v_max_f32_e32 v129, 0, v129
	v_pk_mul_f32 v[132:133], v[128:129], v[128:129]
	v_or_b32_e32 v128, 48, v0
	v_mul_f32_e32 v110, v110, v116
	v_mul_f32_e32 v111, v111, v116
	v_mad_i64_i32 v[128:129], s[4:5], v128, s20, v[134:135]
	v_cvt_pk_bf16_f32 v130, v130, v131
	v_cvt_pk_bf16_f32 v131, v132, v133
	v_max_f32_e32 v110, 0, v110
	v_max_f32_e32 v111, 0, v111
	v_mov_b32_e32 v240, v130
	v_mov_b32_e32 v241, v131
	v_pk_mul_f32 v[130:131], v[110:111], v[110:111]
	v_mul_f32_e32 v110, v112, v116
	v_mul_f32_e32 v111, v113, v116
	v_max_f32_e32 v110, 0, v110
	v_max_f32_e32 v111, 0, v111
	v_mul_f32_e32 v106, v106, v117
	v_mul_f32_e32 v107, v107, v117
	v_pk_mul_f32 v[112:113], v[110:111], v[110:111]
	v_max_f32_e32 v106, 0, v106
	v_max_f32_e32 v107, 0, v107
	v_cvt_pk_bf16_f32 v130, v130, v131
	v_cvt_pk_bf16_f32 v131, v112, v113
	v_pk_mul_f32 v[112:113], v[106:107], v[106:107]
	v_mul_f32_e32 v106, v108, v117
	v_mul_f32_e32 v107, v109, v117
	v_max_f32_e32 v106, 0, v106
	v_max_f32_e32 v107, 0, v107
	v_mul_f32_e32 v102, v102, v114
	v_mul_f32_e32 v103, v103, v114
	v_pk_mul_f32 v[108:109], v[106:107], v[106:107]
	v_max_f32_e32 v102, 0, v102
	v_max_f32_e32 v103, 0, v103
	v_cvt_pk_bf16_f32 v112, v112, v113
	v_cvt_pk_bf16_f32 v113, v108, v109
	v_pk_mul_f32 v[108:109], v[102:103], v[102:103]
	v_mul_f32_e32 v102, v104, v114
	v_mul_f32_e32 v103, v105, v114
	v_max_f32_e32 v102, 0, v102
	v_max_f32_e32 v103, 0, v103
	v_mul_f32_e32 v98, v98, v115
	v_mul_f32_e32 v99, v99, v115
	v_pk_mul_f32 v[104:105], v[102:103], v[102:103]
	v_max_f32_e32 v98, 0, v98
	v_max_f32_e32 v99, 0, v99
	v_cvt_pk_bf16_f32 v108, v108, v109
	v_cvt_pk_bf16_f32 v109, v104, v105
	v_pk_mul_f32 v[104:105], v[98:99], v[98:99]
	v_mul_f32_e32 v98, v100, v115
	v_mul_f32_e32 v99, v101, v115
	v_or_b32_e32 v110, 64, v0
	v_or_b32_e32 v106, 0x50, v0
	v_or_b32_e32 v102, 0x60, v0
	v_max_f32_e32 v98, 0, v98
	v_max_f32_e32 v99, 0, v99
	v_or_b32_e32 v0, 0x70, v0
	v_pk_mul_f32 v[100:101], v[98:99], v[98:99]
	v_mad_i64_i32 v[98:99], s[4:5], v0, s20, v[134:135]
	v_mul_f32_e32 v0, v94, v120
	v_max_f32_e32 v94, 0, v0
	v_mul_f32_e32 v0, v95, v120
	v_max_f32_e32 v95, 0, v0
	v_mul_f32_e32 v0, v96, v120
	v_max_f32_e32 v96, 0, v0
	v_mul_f32_e32 v0, v97, v120
	v_max_f32_e32 v97, 0, v0
	v_mul_f32_e32 v0, v90, v121
	v_max_f32_e32 v90, 0, v0
	v_mul_f32_e32 v0, v91, v121
	v_max_f32_e32 v91, 0, v0
	v_mul_f32_e32 v0, v92, v121
	v_max_f32_e32 v92, 0, v0
	v_mul_f32_e32 v0, v93, v121
	v_max_f32_e32 v93, 0, v0
	v_mul_f32_e32 v0, v86, v118
	v_max_f32_e32 v86, 0, v0
	v_mul_f32_e32 v0, v87, v118
	v_max_f32_e32 v87, 0, v0
	v_mul_f32_e32 v0, v88, v118
	v_max_f32_e32 v88, 0, v0
	v_mul_f32_e32 v0, v89, v118
	v_max_f32_e32 v89, 0, v0
	v_mul_f32_e32 v0, v82, v119
	v_max_f32_e32 v82, 0, v0
	v_mul_f32_e32 v0, v83, v119
	v_max_f32_e32 v83, 0, v0
	v_mul_f32_e32 v0, v84, v119
	v_max_f32_e32 v84, 0, v0
	v_mul_f32_e32 v0, v85, v119
	v_max_f32_e32 v85, 0, v0
	v_mul_f32_e32 v0, v78, v116
	v_max_f32_e32 v78, 0, v0
	v_mul_f32_e32 v0, v79, v116
	v_max_f32_e32 v79, 0, v0
	v_mul_f32_e32 v0, v80, v116
	v_max_f32_e32 v80, 0, v0
	v_mul_f32_e32 v0, v81, v116
	v_max_f32_e32 v81, 0, v0
	v_mul_f32_e32 v0, v74, v117
	v_max_f32_e32 v74, 0, v0
	v_mul_f32_e32 v0, v75, v117
	v_max_f32_e32 v75, 0, v0
	v_mul_f32_e32 v0, v76, v117
	v_max_f32_e32 v76, 0, v0
	v_mul_f32_e32 v0, v77, v117
; DEVI void phase7(const Params& p, int l, char* lds) {
;     ...
; #pragma unroll
;     for (int ni = 0; ni < 4; ++ni)
; #pragma unroll
;       for (int mi = 0; mi < 8; ++mi) {
;         f32x4 v = acc[ni][mi];
; #pragma unroll
;         for (int j = 0; j < 4; ++j) { float r = fmaxf(v[j] * rs8[mi], 0.f); v[j] = r * r; }
	v_max_f32_e32 v77, 0, v0
	v_mul_f32_e32 v0, v70, v114
	v_max_f32_e32 v70, 0, v0
	v_mul_f32_e32 v0, v71, v114
	v_max_f32_e32 v71, 0, v0
	v_mul_f32_e32 v0, v72, v114
	v_max_f32_e32 v72, 0, v0
	v_mul_f32_e32 v0, v73, v114
	v_max_f32_e32 v73, 0, v0
	v_mul_f32_e32 v0, v66, v115
	v_max_f32_e32 v66, 0, v0
	v_mul_f32_e32 v0, v67, v115
	v_max_f32_e32 v67, 0, v0
	v_mul_f32_e32 v0, v68, v115
	v_max_f32_e32 v68, 0, v0
	v_mul_f32_e32 v0, v69, v115
	v_max_f32_e32 v69, 0, v0
	v_mul_f32_e32 v0, v62, v120
	v_max_f32_e32 v62, 0, v0
	v_mul_f32_e32 v0, v63, v120
	v_max_f32_e32 v63, 0, v0
	v_mul_f32_e32 v0, v64, v120
	v_max_f32_e32 v64, 0, v0
	v_mul_f32_e32 v0, v65, v120
	v_max_f32_e32 v65, 0, v0
	v_mul_f32_e32 v0, v58, v121
	v_max_f32_e32 v58, 0, v0
	v_mul_f32_e32 v0, v59, v121
	v_max_f32_e32 v59, 0, v0
	v_mul_f32_e32 v0, v60, v121
	v_max_f32_e32 v60, 0, v0
	v_mul_f32_e32 v0, v61, v121
	v_max_f32_e32 v61, 0, v0
	v_mul_f32_e32 v0, v54, v118
	v_max_f32_e32 v54, 0, v0
	v_mul_f32_e32 v0, v55, v118
	v_max_f32_e32 v55, 0, v0
	v_mul_f32_e32 v0, v56, v118
	v_max_f32_e32 v56, 0, v0
	v_mul_f32_e32 v0, v57, v118
	v_max_f32_e32 v57, 0, v0
	v_mul_f32_e32 v0, v50, v119
	v_max_f32_e32 v50, 0, v0
	v_mul_f32_e32 v0, v51, v119
	v_max_f32_e32 v51, 0, v0
	v_mul_f32_e32 v0, v52, v119
	v_max_f32_e32 v52, 0, v0
	v_mul_f32_e32 v0, v53, v119
	v_max_f32_e32 v53, 0, v0
	v_mul_f32_e32 v0, v46, v116
	v_max_f32_e32 v46, 0, v0
	v_mul_f32_e32 v0, v47, v116
	v_max_f32_e32 v47, 0, v0
	v_mul_f32_e32 v0, v48, v116
	v_max_f32_e32 v48, 0, v0
	v_mul_f32_e32 v0, v49, v116
	v_max_f32_e32 v49, 0, v0
	v_mul_f32_e32 v0, v42, v117
	v_max_f32_e32 v42, 0, v0
	v_mul_f32_e32 v0, v43, v117
	v_max_f32_e32 v43, 0, v0
	v_mul_f32_e32 v0, v44, v117
	v_max_f32_e32 v44, 0, v0
	v_mul_f32_e32 v0, v45, v117
	v_max_f32_e32 v45, 0, v0
	v_mul_f32_e32 v0, v38, v114
	v_max_f32_e32 v38, 0, v0
	v_mul_f32_e32 v0, v39, v114
	v_max_f32_e32 v39, 0, v0
	v_mul_f32_e32 v0, v40, v114
	v_max_f32_e32 v40, 0, v0
	v_mul_f32_e32 v0, v41, v114
	v_max_f32_e32 v41, 0, v0
	v_mul_f32_e32 v0, v34, v115
	v_max_f32_e32 v34, 0, v0
	v_mul_f32_e32 v0, v35, v115
	v_max_f32_e32 v35, 0, v0
	v_mul_f32_e32 v0, v36, v115
	v_max_f32_e32 v36, 0, v0
	v_mul_f32_e32 v0, v37, v115
	v_max_f32_e32 v37, 0, v0
	v_mul_f32_e32 v0, v30, v120
	v_max_f32_e32 v30, 0, v0
	v_mul_f32_e32 v0, v31, v120
	v_max_f32_e32 v31, 0, v0
	v_mul_f32_e32 v0, v32, v120
	v_max_f32_e32 v32, 0, v0
	v_mul_f32_e32 v0, v33, v120
	v_max_f32_e32 v33, 0, v0
	v_mul_f32_e32 v0, v26, v121
	v_max_f32_e32 v26, 0, v0
	v_mul_f32_e32 v0, v27, v121
	v_max_f32_e32 v27, 0, v0
	v_mul_f32_e32 v0, v28, v121
	v_max_f32_e32 v28, 0, v0
	v_mul_f32_e32 v0, v29, v121
	v_max_f32_e32 v29, 0, v0
	v_mul_f32_e32 v0, v22, v118
	v_max_f32_e32 v22, 0, v0
	v_mul_f32_e32 v0, v23, v118
	v_max_f32_e32 v23, 0, v0
	v_mul_f32_e32 v0, v24, v118
	v_max_f32_e32 v24, 0, v0
	v_mul_f32_e32 v0, v25, v118
	v_max_f32_e32 v25, 0, v0
	v_mul_f32_e32 v0, v18, v119
	v_max_f32_e32 v18, 0, v0
	v_mul_f32_e32 v0, v19, v119
	v_max_f32_e32 v19, 0, v0
	v_mul_f32_e32 v0, v20, v119
	v_max_f32_e32 v20, 0, v0
	v_mul_f32_e32 v0, v21, v119
	v_max_f32_e32 v21, 0, v0
	v_mul_f32_e32 v0, v14, v116
	v_max_f32_e32 v14, 0, v0
	v_mul_f32_e32 v0, v15, v116
	v_max_f32_e32 v15, 0, v0
	v_mul_f32_e32 v0, v16, v116
	v_max_f32_e32 v16, 0, v0
	v_mul_f32_e32 v0, v17, v116
	v_max_f32_e32 v17, 0, v0
	v_mul_f32_e32 v0, v10, v117
	v_max_f32_e32 v10, 0, v0
	v_mul_f32_e32 v0, v11, v117
	v_max_f32_e32 v11, 0, v0
	v_mul_f32_e32 v0, v12, v117
	v_max_f32_e32 v12, 0, v0
	v_mul_f32_e32 v0, v13, v117
	v_max_f32_e32 v13, 0, v0
	v_mul_f32_e32 v0, v6, v114
	v_max_f32_e32 v6, 0, v0
	v_mul_f32_e32 v0, v7, v114
	v_max_f32_e32 v7, 0, v0
	v_mul_f32_e32 v0, v8, v114
	v_max_f32_e32 v8, 0, v0
	v_mul_f32_e32 v0, v9, v114
	v_max_f32_e32 v9, 0, v0
	v_mul_f32_e32 v0, v2, v115
	v_max_f32_e32 v2, 0, v0
	v_mul_f32_e32 v0, v3, v115
	v_max_f32_e32 v3, 0, v0
	v_mul_f32_e32 v0, v4, v115
	v_max_f32_e32 v4, 0, v0
	v_mul_f32_e32 v0, v5, v115
	v_max_f32_e32 v5, 0, v0
	v_pk_mul_f32 v[94:95], v[94:95], v[94:95]
	v_pk_mul_f32 v[96:97], v[96:97], v[96:97]
	v_pk_mul_f32 v[90:91], v[90:91], v[90:91]
	v_pk_mul_f32 v[92:93], v[92:93], v[92:93]
	v_pk_mul_f32 v[86:87], v[86:87], v[86:87]
	v_pk_mul_f32 v[88:89], v[88:89], v[88:89]
	v_pk_mul_f32 v[82:83], v[82:83], v[82:83]
	v_pk_mul_f32 v[84:85], v[84:85], v[84:85]
	v_pk_mul_f32 v[78:79], v[78:79], v[78:79]
	v_pk_mul_f32 v[80:81], v[80:81], v[80:81]
	v_pk_mul_f32 v[74:75], v[74:75], v[74:75]
	v_pk_mul_f32 v[76:77], v[76:77], v[76:77]
	v_pk_mul_f32 v[70:71], v[70:71], v[70:71]
	v_pk_mul_f32 v[72:73], v[72:73], v[72:73]
	v_pk_mul_f32 v[66:67], v[66:67], v[66:67]
	v_pk_mul_f32 v[68:69], v[68:69], v[68:69]
	v_pk_mul_f32 v[62:63], v[62:63], v[62:63]
	v_pk_mul_f32 v[64:65], v[64:65], v[64:65]
	v_pk_mul_f32 v[58:59], v[58:59], v[58:59]
	v_pk_mul_f32 v[60:61], v[60:61], v[60:61]
	v_pk_mul_f32 v[54:55], v[54:55], v[54:55]
	v_pk_mul_f32 v[56:57], v[56:57], v[56:57]
	v_pk_mul_f32 v[50:51], v[50:51], v[50:51]
	v_pk_mul_f32 v[52:53], v[52:53], v[52:53]
	v_pk_mul_f32 v[46:47], v[46:47], v[46:47]
	v_pk_mul_f32 v[48:49], v[48:49], v[48:49]
	v_pk_mul_f32 v[42:43], v[42:43], v[42:43]
	v_pk_mul_f32 v[44:45], v[44:45], v[44:45]
	v_pk_mul_f32 v[38:39], v[38:39], v[38:39]
	v_pk_mul_f32 v[40:41], v[40:41], v[40:41]
	v_pk_mul_f32 v[34:35], v[34:35], v[34:35]
	v_pk_mul_f32 v[36:37], v[36:37], v[36:37]
	v_pk_mul_f32 v[30:31], v[30:31], v[30:31]
	v_pk_mul_f32 v[32:33], v[32:33], v[32:33]
	v_pk_mul_f32 v[26:27], v[26:27], v[26:27]
	v_pk_mul_f32 v[28:29], v[28:29], v[28:29]
	v_pk_mul_f32 v[22:23], v[22:23], v[22:23]
	v_pk_mul_f32 v[24:25], v[24:25], v[24:25]
	v_pk_mul_f32 v[18:19], v[18:19], v[18:19]
; DEVI void store_bf4(bfu* p, f32x4 v) {
;   uint2 u; u.x = pack2(v[0], v[1]); u.y = pack2(v[2], v[3]);
;   *(uint2*)p = u;
; }
; DEVI void phase7(const Params& p, int l, char* lds) {
;     ...
; #pragma unroll
;     for (int ni = 0; ni < 4; ++ni)
; #pragma unroll
;       for (int mi = 0; mi < 8; ++mi) {
;         f32x4 v = acc[ni][mi];
; #pragma unroll
;         for (int j = 0; j < 4; ++j) { float r = fmaxf(v[j] * rs8[mi], 0.f); v[j] = r * r; }
;         int n = n0 + wn * 64 + ni * 16 + fq * 4;
;         int m = m0 + wm * 128 + mi * 16 + fr;
;         store_bf4(hid + (long)m * LDH + n, v);
;       }
	v_pk_mul_f32 v[20:21], v[20:21], v[20:21]
	v_pk_mul_f32 v[14:15], v[14:15], v[14:15]
	v_pk_mul_f32 v[16:17], v[16:17], v[16:17]
	v_pk_mul_f32 v[10:11], v[10:11], v[10:11]
	v_pk_mul_f32 v[12:13], v[12:13], v[12:13]
	v_pk_mul_f32 v[6:7], v[6:7], v[6:7]
	v_pk_mul_f32 v[8:9], v[8:9], v[8:9]
	v_pk_mul_f32 v[2:3], v[2:3], v[2:3]
	v_pk_mul_f32 v[4:5], v[4:5], v[4:5]
	v_mad_i64_i32 v[110:111], s[4:5], v110, s20, v[134:135]
	v_mad_i64_i32 v[106:107], s[4:5], v106, s20, v[134:135]
	v_mad_i64_i32 v[102:103], s[4:5], v102, s20, v[134:135]
	v_cvt_pk_bf16_f32 v104, v104, v105
	v_cvt_pk_bf16_f32 v105, v100, v101
	v_cvt_pk_bf16_f32 v94, v94, v95
	v_cvt_pk_bf16_f32 v95, v96, v97
	v_cvt_pk_bf16_f32 v90, v90, v91
	v_cvt_pk_bf16_f32 v91, v92, v93
	v_cvt_pk_bf16_f32 v86, v86, v87
	v_cvt_pk_bf16_f32 v87, v88, v89
	v_cvt_pk_bf16_f32 v82, v82, v83
	v_cvt_pk_bf16_f32 v83, v84, v85
	v_cvt_pk_bf16_f32 v78, v78, v79
	v_cvt_pk_bf16_f32 v79, v80, v81
	v_cvt_pk_bf16_f32 v74, v74, v75
	v_cvt_pk_bf16_f32 v75, v76, v77
	v_cvt_pk_bf16_f32 v70, v70, v71
	v_cvt_pk_bf16_f32 v71, v72, v73
	v_cvt_pk_bf16_f32 v66, v66, v67
	v_cvt_pk_bf16_f32 v67, v68, v69
	v_cvt_pk_bf16_f32 v62, v62, v63
	v_cvt_pk_bf16_f32 v63, v64, v65
	v_cvt_pk_bf16_f32 v58, v58, v59
	v_cvt_pk_bf16_f32 v59, v60, v61
	v_cvt_pk_bf16_f32 v54, v54, v55
	v_cvt_pk_bf16_f32 v55, v56, v57
	v_cvt_pk_bf16_f32 v50, v50, v51
	v_cvt_pk_bf16_f32 v51, v52, v53
	v_cvt_pk_bf16_f32 v46, v46, v47
	v_cvt_pk_bf16_f32 v47, v48, v49
	v_cvt_pk_bf16_f32 v42, v42, v43
	v_cvt_pk_bf16_f32 v43, v44, v45
	v_cvt_pk_bf16_f32 v38, v38, v39
	v_cvt_pk_bf16_f32 v39, v40, v41
	v_cvt_pk_bf16_f32 v34, v34, v35
	v_cvt_pk_bf16_f32 v35, v36, v37
	v_cvt_pk_bf16_f32 v30, v30, v31
	v_cvt_pk_bf16_f32 v31, v32, v33
	v_cvt_pk_bf16_f32 v26, v26, v27
	v_cvt_pk_bf16_f32 v27, v28, v29
	v_cvt_pk_bf16_f32 v22, v22, v23
	v_cvt_pk_bf16_f32 v23, v24, v25
	v_cvt_pk_bf16_f32 v18, v18, v19
	v_cvt_pk_bf16_f32 v19, v20, v21
	v_cvt_pk_bf16_f32 v14, v14, v15
	v_cvt_pk_bf16_f32 v15, v16, v17
	v_cvt_pk_bf16_f32 v10, v10, v11
	v_cvt_pk_bf16_f32 v11, v12, v13
	v_cvt_pk_bf16_f32 v6, v6, v7
	v_cvt_pk_bf16_f32 v7, v8, v9
	v_cvt_pk_bf16_f32 v2, v2, v3
	v_cvt_pk_bf16_f32 v3, v4, v5
	s_and_b64 vcc, exec, s[0:1]
	s_mov_b32 s20, s27
	s_mov_b32 s30, s42
	s_mov_b32 s23, s29
	v_bfe_u32 v216, v225, 4, 1
	v_mov_b32_e32 v217, 0
	v_mul_u32_u24_e32 v216, 24, v216
	v_lshl_add_u64 v[194:195], v[122:123], 0, v[216:217]
	v_lshl_add_u64 v[196:197], v[124:125], 0, v[216:217]
	v_lshl_add_u64 v[198:199], v[126:127], 0, v[216:217]
	v_lshl_add_u64 v[200:201], v[128:129], 0, v[216:217]
	v_lshl_add_u64 v[202:203], v[110:111], 0, v[216:217]
	v_lshl_add_u64 v[204:205], v[106:107], 0, v[216:217]
	v_lshl_add_u64 v[206:207], v[102:103], 0, v[216:217]
	v_lshl_add_u64 v[208:209], v[98:99], 0, v[216:217]
	v_mov_b32_e32 v64, v30
	v_mov_b32_e32 v65, v31
	v_mov_b32_e32 v60, v26
	v_mov_b32_e32 v61, v27
	v_mov_b32_e32 v56, v22
	v_mov_b32_e32 v57, v23
	v_mov_b32_e32 v52, v18
	v_mov_b32_e32 v53, v19
	v_mov_b32_e32 v48, v14
	v_mov_b32_e32 v49, v15
	v_mov_b32_e32 v44, v10
	v_mov_b32_e32 v45, v11
	v_mov_b32_e32 v40, v6
	v_mov_b32_e32 v41, v7
	v_mov_b32_e32 v36, v2
	v_mov_b32_e32 v37, v3
	v_mov_b32_e32 v96, v94
	v_mov_b32_e32 v97, v95
	v_mov_b32_e32 v94, v234
	v_mov_b32_e32 v95, v235
	v_mov_b32_e32 v92, v90
	v_mov_b32_e32 v93, v91
	v_mov_b32_e32 v90, v236
	v_mov_b32_e32 v91, v237
	v_mov_b32_e32 v88, v86
	v_mov_b32_e32 v89, v87
	v_mov_b32_e32 v86, v238
	v_mov_b32_e32 v87, v239
	v_mov_b32_e32 v84, v82
	v_mov_b32_e32 v85, v83
	v_mov_b32_e32 v82, v240
	v_mov_b32_e32 v83, v241
	v_mov_b32_e32 v80, v78
	v_mov_b32_e32 v81, v79
	v_mov_b32_e32 v78, v130
	v_mov_b32_e32 v79, v131
	v_mov_b32_e32 v76, v74
	v_mov_b32_e32 v77, v75
	v_mov_b32_e32 v74, v112
	v_mov_b32_e32 v75, v113
	v_mov_b32_e32 v72, v70
	v_mov_b32_e32 v73, v71
	v_mov_b32_e32 v70, v108
	v_mov_b32_e32 v71, v109
	v_mov_b32_e32 v68, v66
	v_mov_b32_e32 v69, v67
	v_mov_b32_e32 v66, v104
	v_mov_b32_e32 v67, v105
	s_nop 1
	v_permlane16_swap_b32_e32 v62, v64
	v_permlane16_swap_b32_e32 v63, v65
	v_permlane16_swap_b32_e32 v58, v60
	v_permlane16_swap_b32_e32 v59, v61
	v_permlane16_swap_b32_e32 v54, v56
	v_permlane16_swap_b32_e32 v55, v57
	v_permlane16_swap_b32_e32 v50, v52
	v_permlane16_swap_b32_e32 v51, v53
	v_permlane16_swap_b32_e32 v46, v48
	v_permlane16_swap_b32_e32 v47, v49
	v_permlane16_swap_b32_e32 v42, v44
	v_permlane16_swap_b32_e32 v43, v45
	v_permlane16_swap_b32_e32 v38, v40
	v_permlane16_swap_b32_e32 v39, v41
	v_permlane16_swap_b32_e32 v34, v36
	v_permlane16_swap_b32_e32 v35, v37
	v_permlane16_swap_b32_e32 v94, v96
	v_permlane16_swap_b32_e32 v95, v97
	v_permlane16_swap_b32_e32 v90, v92
	v_permlane16_swap_b32_e32 v91, v93
	v_permlane16_swap_b32_e32 v86, v88
	v_permlane16_swap_b32_e32 v87, v89
	v_permlane16_swap_b32_e32 v82, v84
	v_permlane16_swap_b32_e32 v83, v85
	v_permlane16_swap_b32_e32 v78, v80
	v_permlane16_swap_b32_e32 v79, v81
	v_permlane16_swap_b32_e32 v74, v76
	v_permlane16_swap_b32_e32 v75, v77
	v_permlane16_swap_b32_e32 v70, v72
	v_permlane16_swap_b32_e32 v71, v73
	v_permlane16_swap_b32_e32 v66, v68
	v_permlane16_swap_b32_e32 v67, v69
	s_nop 1
	global_store_dwordx4 v[194:195], v[94:97], off
	global_store_dwordx4 v[196:197], v[90:93], off
	global_store_dwordx4 v[198:199], v[86:89], off
	global_store_dwordx4 v[200:201], v[82:85], off
	global_store_dwordx4 v[202:203], v[78:81], off
	global_store_dwordx4 v[204:205], v[74:77], off
	global_store_dwordx4 v[206:207], v[70:73], off
	global_store_dwordx4 v[208:209], v[66:69], off
	global_store_dwordx4 v[194:195], v[62:65], off offset:64
	global_store_dwordx4 v[196:197], v[58:61], off offset:64
	global_store_dwordx4 v[198:199], v[54:57], off offset:64
	global_store_dwordx4 v[200:201], v[50:53], off offset:64
	global_store_dwordx4 v[202:203], v[46:49], off offset:64
	global_store_dwordx4 v[204:205], v[42:45], off offset:64
	global_store_dwordx4 v[206:207], v[38:41], off offset:64
	global_store_dwordx4 v[208:209], v[34:37], off offset:64
	s_nop 1
	s_cbranch_vccnz .LBB0_223

; DEVI float lo2f(unsigned u) { return __uint_as_float(u << 16); }
; DEVI float hi2f(unsigned u) { return __uint_as_float(u & 0xffff0000u); }
; DEVI void phase_resid_gemm(const Params& p, const bfu* A, int lda, int nkt, const bfu* wT, int ldb, const float* resid32,
;                            float* ssq_out, float* out32, char* lds) {
;     ...
; #pragma unroll
;       for (int ni = 0; ni < 4; ++ni) {
;         const int n = n0 + wn * 64 + ni * 16 + fq * 4;
;         float4 r;
;         if (resid32) r = *(const float4*)(resid32 + (long)m * 1024 + n);
;         else { const uint2 u = *(const uint2*)(xs + (long)m * LDX + n); r = make_float4(lo2f(u.x), hi2f(u.x), lo2f(u.y), hi2f(u.y)); }
;         float4 o;
;         o.x = r.x + acc[ni][mi][0]; o.y = r.y + acc[ni][mi][1]; o.z = r.z + acc[ni][mi][2]; o.w = r.w + acc[ni][mi][3];
;         if (out32) *(float4*)(out32 + (long)m * 1024 + n) = o;
;         else {
;           uint2 ob; ob.x = pack2(o.x, o.y); ob.y = pack2(o.z, o.w);
;           *(uint2*)(xs + (long)m * LDX + n) = ob;
;           const float q0 = lo2f(ob.x), q1 = hi2f(ob.x), q2 = lo2f(ob.y), q3 = hi2f(ob.y);
;           ss += q0 * q0 + q1 * q1 + q2 * q2 + q3 * q3;
.LBB0_250:
	s_waitcnt vmcnt(0)
	v_pk_add_f32 v[126:127], v[162:163], v[126:127]
	v_pk_add_f32 v[128:129], v[164:165], v[128:129]
	v_cvt_pk_bf16_f32 v138, v126, v127
	v_cvt_pk_bf16_f32 v139, v128, v129
	s_and_b64 vcc, exec, s[40:41]
	v_mov_b32_e32 v200, v138
	v_mov_b32_e32 v201, v139
	s_cbranch_vccnz .LBB0_263
	global_load_dwordx4 v[126:129], v[136:137], off offset:64
	s_cbranch_execnz .LBB0_253

; DEVI float lo2f(unsigned u) { return __uint_as_float(u << 16); }
; DEVI float hi2f(unsigned u) { return __uint_as_float(u & 0xffff0000u); }
; DEVI void phase_resid_gemm(const Params& p, const bfu* A, int lda, int nkt, const bfu* wT, int ldb, const float* resid32,
;                            float* ssq_out, float* out32, char* lds) {
;     ...
; #pragma unroll
;       for (int ni = 0; ni < 4; ++ni) {
;         const int n = n0 + wn * 64 + ni * 16 + fq * 4;
;         float4 r;
;         if (resid32) r = *(const float4*)(resid32 + (long)m * 1024 + n);
;         else { const uint2 u = *(const uint2*)(xs + (long)m * LDX + n); r = make_float4(lo2f(u.x), hi2f(u.x), lo2f(u.y), hi2f(u.y)); }
;         float4 o;
;         o.x = r.x + acc[ni][mi][0]; o.y = r.y + acc[ni][mi][1]; o.z = r.z + acc[ni][mi][2]; o.w = r.w + acc[ni][mi][3];
;         if (out32) *(float4*)(out32 + (long)m * 1024 + n) = o;
;         else {
;           uint2 ob; ob.x = pack2(o.x, o.y); ob.y = pack2(o.z, o.w);
;           *(uint2*)(xs + (long)m * LDX + n) = ob;
;           const float q0 = lo2f(ob.x), q1 = hi2f(ob.x), q2 = lo2f(ob.y), q3 = hi2f(ob.y);
;           ss += q0 * q0 + q1 * q1 + q2 * q2 + q3 * q3;
.LBB0_253:
	s_waitcnt vmcnt(0)
	v_pk_add_f32 v[122:123], v[122:123], v[126:127]
	v_pk_add_f32 v[124:125], v[124:125], v[128:129]
	v_cvt_pk_bf16_f32 v126, v122, v123
	v_cvt_pk_bf16_f32 v127, v124, v125
	s_and_b64 vcc, exec, s[40:41]
	v_mov_b32_e32 v206, v126
	v_mov_b32_e32 v207, v127
	v_mov_b32_e32 v204, v200
	v_mov_b32_e32 v205, v201
	v_lshl_add_u64 v[212:213], v[134:135], 0, v[254:255]
	s_nop 0
	v_permlane16_swap_b32_e32 v204, v206
	v_permlane16_swap_b32_e32 v205, v207
	s_nop 1
	global_store_dwordx4 v[212:213], v[204:207], off
	s_cbranch_vccnz .LBB0_264
	global_load_dwordx4 v[122:125], v[136:137], off offset:128
	s_cbranch_execnz .LBB0_256

; DEVI float lo2f(unsigned u) { return __uint_as_float(u << 16); }
; DEVI float hi2f(unsigned u) { return __uint_as_float(u & 0xffff0000u); }
; DEVI void phase_resid_gemm(const Params& p, const bfu* A, int lda, int nkt, const bfu* wT, int ldb, const float* resid32,
;                            float* ssq_out, float* out32, char* lds) {
;     ...
; #pragma unroll
;       for (int ni = 0; ni < 4; ++ni) {
;         const int n = n0 + wn * 64 + ni * 16 + fq * 4;
;         float4 r;
;         if (resid32) r = *(const float4*)(resid32 + (long)m * 1024 + n);
;         else { const uint2 u = *(const uint2*)(xs + (long)m * LDX + n); r = make_float4(lo2f(u.x), hi2f(u.x), lo2f(u.y), hi2f(u.y)); }
;         float4 o;
;         o.x = r.x + acc[ni][mi][0]; o.y = r.y + acc[ni][mi][1]; o.z = r.z + acc[ni][mi][2]; o.w = r.w + acc[ni][mi][3];
;         if (out32) *(float4*)(out32 + (long)m * 1024 + n) = o;
;         else {
;           uint2 ob; ob.x = pack2(o.x, o.y); ob.y = pack2(o.z, o.w);
;           *(uint2*)(xs + (long)m * LDX + n) = ob;
;           const float q0 = lo2f(ob.x), q1 = hi2f(ob.x), q2 = lo2f(ob.y), q3 = hi2f(ob.y);
;           ss += q0 * q0 + q1 * q1 + q2 * q2 + q3 * q3;
.LBB0_256:
	s_waitcnt vmcnt(0)
	v_pk_add_f32 v[118:119], v[118:119], v[122:123]
	v_pk_add_f32 v[120:121], v[120:121], v[124:125]
	v_cvt_pk_bf16_f32 v122, v118, v119
	v_cvt_pk_bf16_f32 v123, v120, v121
	s_and_b64 vcc, exec, s[40:41]
	v_mov_b32_e32 v200, v122
	v_mov_b32_e32 v201, v123
	s_cbranch_vccnz .LBB0_265
	global_load_dwordx4 v[118:121], v[136:137], off offset:192
	s_cbranch_execnz .LBB0_259

; DEVI float lo2f(unsigned u) { return __uint_as_float(u << 16); }
; DEVI float hi2f(unsigned u) { return __uint_as_float(u & 0xffff0000u); }
; DEVI void phase_resid_gemm(const Params& p, const bfu* A, int lda, int nkt, const bfu* wT, int ldb, const float* resid32,
;                            float* ssq_out, float* out32, char* lds) {
;     ...
; #pragma unroll
;       for (int ni = 0; ni < 4; ++ni) {
;         const int n = n0 + wn * 64 + ni * 16 + fq * 4;
;         float4 r;
;         if (resid32) r = *(const float4*)(resid32 + (long)m * 1024 + n);
;         else { const uint2 u = *(const uint2*)(xs + (long)m * LDX + n); r = make_float4(lo2f(u.x), hi2f(u.x), lo2f(u.y), hi2f(u.y)); }
;         float4 o;
;         o.x = r.x + acc[ni][mi][0]; o.y = r.y + acc[ni][mi][1]; o.z = r.z + acc[ni][mi][2]; o.w = r.w + acc[ni][mi][3];
;         if (out32) *(float4*)(out32 + (long)m * 1024 + n) = o;
;         else {
;           uint2 ob; ob.x = pack2(o.x, o.y); ob.y = pack2(o.z, o.w);
;           *(uint2*)(xs + (long)m * LDX + n) = ob;
;           const float q0 = lo2f(ob.x), q1 = hi2f(ob.x), q2 = lo2f(ob.y), q3 = hi2f(ob.y);
;           ss += q0 * q0 + q1 * q1 + q2 * q2 + q3 * q3;
;         }
;       }
;       if (!out32) {
;         ss += __shfl_xor(ss, 16);
;         ss += __shfl_xor(ss, 32);
;         if (fq == 0) part[(wm * 128 + mi * 16 + fr) * 4 + wn] = ss;
.LBB0_259:
	v_and_b32_e32 v124, 0xffff0000, v138
	v_lshlrev_b32_e32 v0, 16, v138
	v_mul_f32_e32 v124, v124, v124
	v_lshlrev_b32_e32 v125, 16, v139
	v_fmac_f32_e32 v124, v0, v0
	v_fmac_f32_e32 v124, v125, v125
	v_and_b32_e32 v125, 0xffff0000, v126
	v_lshlrev_b32_e32 v0, 16, v126
	v_mul_f32_e32 v125, v125, v125
	v_lshlrev_b32_e32 v126, 16, v127
	v_fmac_f32_e32 v125, v0, v0
	v_and_b32_e32 v128, 0xffff0000, v139
	v_and_b32_e32 v127, 0xffff0000, v127
	v_fmac_f32_e32 v125, v126, v126
	v_fmac_f32_e32 v124, v128, v128
	v_fmac_f32_e32 v125, v127, v127
	s_waitcnt vmcnt(0)
	v_pk_add_f32 v[110:111], v[110:111], v[118:119]
	v_add_f32_e32 v0, v124, v125
	v_lshlrev_b32_e32 v124, 16, v122
	v_and_b32_e32 v122, 0xffff0000, v122
	v_cvt_pk_bf16_f32 v118, v110, v111
	v_mul_f32_e32 v122, v122, v122
	v_pk_add_f32 v[112:113], v[112:113], v[120:121]
	v_and_b32_e32 v111, 0xffff0000, v118
	v_lshlrev_b32_e32 v125, 16, v123
	v_fmac_f32_e32 v122, v124, v124
	v_cvt_pk_bf16_f32 v119, v112, v113
	v_lshlrev_b32_e32 v110, 16, v118
	v_mul_f32_e32 v111, v111, v111
	v_and_b32_e32 v123, 0xffff0000, v123
	v_fmac_f32_e32 v122, v125, v125
	v_lshlrev_b32_e32 v112, 16, v119
	v_fmac_f32_e32 v111, v110, v110
	v_fmac_f32_e32 v122, v123, v123
	v_and_b32_e32 v113, 0xffff0000, v119
	v_fmac_f32_e32 v111, v112, v112
	v_add_f32_e32 v0, v0, v122
	v_fmac_f32_e32 v111, v113, v113
	v_add_f32_e32 v110, v0, v111
	v_and_b32_e32 v111, 64, v225
	v_xor_b32_e32 v0, 16, v225
	v_add_u32_e32 v111, 64, v111
	v_cmp_lt_i32_e32 vcc, v0, v111
	v_mov_b32_e32 v210, v118
	v_mov_b32_e32 v211, v119
	v_mov_b32_e32 v208, v200
	v_mov_b32_e32 v209, v201
	v_lshl_add_u64 v[212:213], v[134:135], 0, v[254:255]
	s_nop 0
	v_permlane16_swap_b32_e32 v208, v210
	v_permlane16_swap_b32_e32 v209, v211
	s_nop 1
	global_store_dwordx4 v[212:213], v[208:211], off offset:64
	s_nop 0
	v_cndmask_b32_e32 v0, v225, v0, vcc
	v_lshlrev_b32_e32 v0, 2, v0
	ds_bpermute_b32 v112, v0, v110
	s_waitcnt lgkmcnt(0)
	v_add_f32_e32 v110, v110, v112
	v_xor_b32_e32 v112, 32, v225
	v_cmp_lt_i32_e32 vcc, v112, v111
	s_nop 1
	v_cndmask_b32_e32 v111, v225, v112, vcc
	v_lshlrev_b32_e32 v122, 2, v111
	ds_bpermute_b32 v111, v122, v110
	s_and_saveexec_b64 s[36:37], s[38:39]
	s_cbranch_execz .LBB0_261
	s_waitcnt lgkmcnt(0)
	v_add_f32_e32 v110, v110, v111
	ds_write_b32 v183, v110

; DEVI float lo2f(unsigned u) { return __uint_as_float(u << 16); }
; DEVI float hi2f(unsigned u) { return __uint_as_float(u & 0xffff0000u); }
; DEVI void phase_resid_gemm(const Params& p, const bfu* A, int lda, int nkt, const bfu* wT, int ldb, const float* resid32,
;                            float* ssq_out, float* out32, char* lds) {
;     ...
; #pragma unroll
;       for (int ni = 0; ni < 4; ++ni) {
;         const int n = n0 + wn * 64 + ni * 16 + fq * 4;
;         float4 r;
;         if (resid32) r = *(const float4*)(resid32 + (long)m * 1024 + n);
;         else { const uint2 u = *(const uint2*)(xs + (long)m * LDX + n); r = make_float4(lo2f(u.x), hi2f(u.x), lo2f(u.y), hi2f(u.y)); }
;         float4 o;
;         o.x = r.x + acc[ni][mi][0]; o.y = r.y + acc[ni][mi][1]; o.z = r.z + acc[ni][mi][2]; o.w = r.w + acc[ni][mi][3];
;         if (out32) *(float4*)(out32 + (long)m * 1024 + n) = o;
;         else {
;           uint2 ob; ob.x = pack2(o.x, o.y); ob.y = pack2(o.z, o.w);
;           *(uint2*)(xs + (long)m * LDX + n) = ob;
;           const float q0 = lo2f(ob.x), q1 = hi2f(ob.x), q2 = lo2f(ob.y), q3 = hi2f(ob.y);
;           ss += q0 * q0 + q1 * q1 + q2 * q2 + q3 * q3;
.LBB0_269:
	s_waitcnt vmcnt(0)
	v_pk_add_f32 v[110:111], v[114:115], v[110:111]
	v_pk_add_f32 v[112:113], v[116:117], v[112:113]
	v_cvt_pk_bf16_f32 v114, v110, v111
	v_cvt_pk_bf16_f32 v115, v112, v113
	s_and_b64 vcc, exec, s[40:41]
	v_mov_b32_e32 v200, v114
	v_mov_b32_e32 v201, v115
	s_cbranch_vccnz .LBB0_282
	global_load_dwordx4 v[110:113], v[120:121], off offset:64
	s_cbranch_execnz .LBB0_272

; DEVI float lo2f(unsigned u) { return __uint_as_float(u << 16); }
; DEVI float hi2f(unsigned u) { return __uint_as_float(u & 0xffff0000u); }
; DEVI void phase_resid_gemm(const Params& p, const bfu* A, int lda, int nkt, const bfu* wT, int ldb, const float* resid32,
;                            float* ssq_out, float* out32, char* lds) {
;     ...
;       for (int ni = 0; ni < 4; ++ni) {
;         const int n = n0 + wn * 64 + ni * 16 + fq * 4;
;         float4 r;
;         if (resid32) r = *(const float4*)(resid32 + (long)m * 1024 + n);
;         else { const uint2 u = *(const uint2*)(xs + (long)m * LDX + n); r = make_float4(lo2f(u.x), hi2f(u.x), lo2f(u.y), hi2f(u.y)); }
;         float4 o;
;         o.x = r.x + acc[ni][mi][0]; o.y = r.y + acc[ni][mi][1]; o.z = r.z + acc[ni][mi][2]; o.w = r.w + acc[ni][mi][3];
;         if (out32) *(float4*)(out32 + (long)m * 1024 + n) = o;
;         else {
;           uint2 ob; ob.x = pack2(o.x, o.y); ob.y = pack2(o.z, o.w);
;           *(uint2*)(xs + (long)m * LDX + n) = ob;
.LBB0_272:
	s_waitcnt vmcnt(0)
	v_pk_add_f32 v[106:107], v[106:107], v[110:111]
	v_pk_add_f32 v[108:109], v[108:109], v[112:113]
	v_cvt_pk_bf16_f32 v110, v106, v107
	v_cvt_pk_bf16_f32 v111, v108, v109
	s_and_b64 vcc, exec, s[40:41]
	v_mov_b32_e32 v206, v110
	v_mov_b32_e32 v207, v111
	v_mov_b32_e32 v204, v200
	v_mov_b32_e32 v205, v201
	v_lshl_add_u64 v[212:213], v[118:119], 0, v[254:255]
	s_nop 0
	v_permlane16_swap_b32_e32 v204, v206
	v_permlane16_swap_b32_e32 v205, v207
	s_nop 1
	global_store_dwordx4 v[212:213], v[204:207], off
	s_cbranch_vccnz .LBB0_283
	global_load_dwordx4 v[106:109], v[120:121], off offset:128
	s_cbranch_execnz .LBB0_275

; DEVI float lo2f(unsigned u) { return __uint_as_float(u << 16); }
; DEVI float hi2f(unsigned u) { return __uint_as_float(u & 0xffff0000u); }
; DEVI void phase_resid_gemm(const Params& p, const bfu* A, int lda, int nkt, const bfu* wT, int ldb, const float* resid32,
;                            float* ssq_out, float* out32, char* lds) {
;     ...
;       for (int ni = 0; ni < 4; ++ni) {
;         const int n = n0 + wn * 64 + ni * 16 + fq * 4;
;         float4 r;
;         if (resid32) r = *(const float4*)(resid32 + (long)m * 1024 + n);
;         else { const uint2 u = *(const uint2*)(xs + (long)m * LDX + n); r = make_float4(lo2f(u.x), hi2f(u.x), lo2f(u.y), hi2f(u.y)); }
;         float4 o;
;         o.x = r.x + acc[ni][mi][0]; o.y = r.y + acc[ni][mi][1]; o.z = r.z + acc[ni][mi][2]; o.w = r.w + acc[ni][mi][3];
;         if (out32) *(float4*)(out32 + (long)m * 1024 + n) = o;
;         else {
;           uint2 ob; ob.x = pack2(o.x, o.y); ob.y = pack2(o.z, o.w);
;           *(uint2*)(xs + (long)m * LDX + n) = ob;
.LBB0_275:
	s_waitcnt vmcnt(0)
	v_pk_add_f32 v[102:103], v[102:103], v[106:107]
	v_pk_add_f32 v[104:105], v[104:105], v[108:109]
	v_cvt_pk_bf16_f32 v106, v102, v103
	v_cvt_pk_bf16_f32 v107, v104, v105
	s_and_b64 vcc, exec, s[40:41]
	v_mov_b32_e32 v200, v106
	v_mov_b32_e32 v201, v107
	s_cbranch_vccnz .LBB0_284
	global_load_dwordx4 v[102:105], v[120:121], off offset:192
	s_cbranch_execnz .LBB0_278

; DEVI float lo2f(unsigned u) { return __uint_as_float(u << 16); }
; DEVI float hi2f(unsigned u) { return __uint_as_float(u & 0xffff0000u); }
; DEVI void phase_resid_gemm(const Params& p, const bfu* A, int lda, int nkt, const bfu* wT, int ldb, const float* resid32,
;                            float* ssq_out, float* out32, char* lds) {
;     ...
; #pragma unroll
;       for (int ni = 0; ni < 4; ++ni) {
;         const int n = n0 + wn * 64 + ni * 16 + fq * 4;
;         float4 r;
;         if (resid32) r = *(const float4*)(resid32 + (long)m * 1024 + n);
;         else { const uint2 u = *(const uint2*)(xs + (long)m * LDX + n); r = make_float4(lo2f(u.x), hi2f(u.x), lo2f(u.y), hi2f(u.y)); }
;         float4 o;
;         o.x = r.x + acc[ni][mi][0]; o.y = r.y + acc[ni][mi][1]; o.z = r.z + acc[ni][mi][2]; o.w = r.w + acc[ni][mi][3];
;         if (out32) *(float4*)(out32 + (long)m * 1024 + n) = o;
;         else {
;           uint2 ob; ob.x = pack2(o.x, o.y); ob.y = pack2(o.z, o.w);
;           *(uint2*)(xs + (long)m * LDX + n) = ob;
;           const float q0 = lo2f(ob.x), q1 = hi2f(ob.x), q2 = lo2f(ob.y), q3 = hi2f(ob.y);
;           ss += q0 * q0 + q1 * q1 + q2 * q2 + q3 * q3;
;         }
;       }
;       if (!out32) {
;         ss += __shfl_xor(ss, 16);
;         ss += __shfl_xor(ss, 32);
;         if (fq == 0) part[(wm * 128 + mi * 16 + fr) * 4 + wn] = ss;
;       }
.LBB0_278:
	v_and_b32_e32 v109, 0xffff0000, v114
	v_lshlrev_b32_e32 v108, 16, v114
	v_mul_f32_e32 v109, v109, v109
	v_fmac_f32_e32 v109, v108, v108
	v_lshlrev_b32_e32 v108, 16, v110
	v_and_b32_e32 v110, 0xffff0000, v110
	v_lshlrev_b32_e32 v112, 16, v115
	v_mul_f32_e32 v110, v110, v110
	v_fmac_f32_e32 v109, v112, v112
	v_lshlrev_b32_e32 v112, 16, v111
	v_fmac_f32_e32 v110, v108, v108
	v_and_b32_e32 v113, 0xffff0000, v115
	v_and_b32_e32 v111, 0xffff0000, v111
	v_fmac_f32_e32 v110, v112, v112
	v_fmac_f32_e32 v109, v113, v113
	v_fmac_f32_e32 v110, v111, v111
	s_waitcnt vmcnt(0)
	v_pk_add_f32 v[94:95], v[94:95], v[102:103]
	v_add_f32_e32 v108, v109, v110
	v_lshlrev_b32_e32 v109, 16, v106
	v_and_b32_e32 v106, 0xffff0000, v106
	v_cvt_pk_bf16_f32 v102, v94, v95
	v_mul_f32_e32 v106, v106, v106
	v_pk_add_f32 v[96:97], v[96:97], v[104:105]
	v_and_b32_e32 v95, 0xffff0000, v102
	v_lshlrev_b32_e32 v110, 16, v107
	v_fmac_f32_e32 v106, v109, v109
	v_cvt_pk_bf16_f32 v103, v96, v97
	v_lshlrev_b32_e32 v94, 16, v102
	v_mul_f32_e32 v95, v95, v95
	v_and_b32_e32 v107, 0xffff0000, v107
	v_fmac_f32_e32 v106, v110, v110
	v_lshlrev_b32_e32 v96, 16, v103
	v_fmac_f32_e32 v95, v94, v94
	v_fmac_f32_e32 v106, v107, v107
	v_and_b32_e32 v97, 0xffff0000, v103
	v_fmac_f32_e32 v95, v96, v96
	v_add_f32_e32 v106, v108, v106
	v_fmac_f32_e32 v95, v97, v97
	v_add_f32_e32 v94, v106, v95
	ds_bpermute_b32 v95, v0, v94
	v_mov_b32_e32 v210, v102
	v_mov_b32_e32 v211, v103
	v_mov_b32_e32 v208, v200
	v_mov_b32_e32 v209, v201
	v_lshl_add_u64 v[212:213], v[118:119], 0, v[254:255]
	s_nop 0
	v_permlane16_swap_b32_e32 v208, v210
	v_permlane16_swap_b32_e32 v209, v211
	s_nop 1
	global_store_dwordx4 v[212:213], v[208:211], off offset:64
	s_waitcnt lgkmcnt(0)
	v_add_f32_e32 v94, v94, v95
	ds_bpermute_b32 v95, v122, v94
	s_and_saveexec_b64 s[36:37], s[38:39]
	s_cbranch_execz .LBB0_280
	s_waitcnt lgkmcnt(0)
	v_add_f32_e32 v94, v94, v95
	ds_write_b32 v183, v94 offset:256

; DEVI float lo2f(unsigned u) { return __uint_as_float(u << 16); }
; DEVI float hi2f(unsigned u) { return __uint_as_float(u & 0xffff0000u); }
; DEVI void phase_resid_gemm(const Params& p, const bfu* A, int lda, int nkt, const bfu* wT, int ldb, const float* resid32,
;                            float* ssq_out, float* out32, char* lds) {
;     ...
;       for (int ni = 0; ni < 4; ++ni) {
;         const int n = n0 + wn * 64 + ni * 16 + fq * 4;
;         float4 r;
;         if (resid32) r = *(const float4*)(resid32 + (long)m * 1024 + n);
;         else { const uint2 u = *(const uint2*)(xs + (long)m * LDX + n); r = make_float4(lo2f(u.x), hi2f(u.x), lo2f(u.y), hi2f(u.y)); }
;         float4 o;
;         o.x = r.x + acc[ni][mi][0]; o.y = r.y + acc[ni][mi][1]; o.z = r.z + acc[ni][mi][2]; o.w = r.w + acc[ni][mi][3];
;         if (out32) *(float4*)(out32 + (long)m * 1024 + n) = o;
;         else {
;           uint2 ob; ob.x = pack2(o.x, o.y); ob.y = pack2(o.z, o.w);
;           *(uint2*)(xs + (long)m * LDX + n) = ob;
.LBB0_288:
	s_waitcnt vmcnt(0)
	v_pk_add_f32 v[94:95], v[98:99], v[94:95]
	v_pk_add_f32 v[96:97], v[100:101], v[96:97]
	v_cvt_pk_bf16_f32 v98, v94, v95
	v_cvt_pk_bf16_f32 v99, v96, v97
	s_and_b64 vcc, exec, s[40:41]
	v_mov_b32_e32 v200, v98
	v_mov_b32_e32 v201, v99
	s_cbranch_vccnz .LBB0_301
	global_load_dwordx4 v[94:97], v[104:105], off offset:64
	s_cbranch_execnz .LBB0_291

; DEVI float lo2f(unsigned u) { return __uint_as_float(u << 16); }
; DEVI float hi2f(unsigned u) { return __uint_as_float(u & 0xffff0000u); }
; DEVI void phase_resid_gemm(const Params& p, const bfu* A, int lda, int nkt, const bfu* wT, int ldb, const float* resid32,
;                            float* ssq_out, float* out32, char* lds) {
;     ...
;       for (int ni = 0; ni < 4; ++ni) {
;         const int n = n0 + wn * 64 + ni * 16 + fq * 4;
;         float4 r;
;         if (resid32) r = *(const float4*)(resid32 + (long)m * 1024 + n);
;         else { const uint2 u = *(const uint2*)(xs + (long)m * LDX + n); r = make_float4(lo2f(u.x), hi2f(u.x), lo2f(u.y), hi2f(u.y)); }
;         float4 o;
;         o.x = r.x + acc[ni][mi][0]; o.y = r.y + acc[ni][mi][1]; o.z = r.z + acc[ni][mi][2]; o.w = r.w + acc[ni][mi][3];
;         if (out32) *(float4*)(out32 + (long)m * 1024 + n) = o;
;         else {
;           uint2 ob; ob.x = pack2(o.x, o.y); ob.y = pack2(o.z, o.w);
;           *(uint2*)(xs + (long)m * LDX + n) = ob;
.LBB0_291:
	s_waitcnt vmcnt(0)
	v_pk_add_f32 v[90:91], v[90:91], v[94:95]
	v_pk_add_f32 v[92:93], v[92:93], v[96:97]
	v_cvt_pk_bf16_f32 v94, v90, v91
	v_cvt_pk_bf16_f32 v95, v92, v93
	s_and_b64 vcc, exec, s[40:41]
	v_mov_b32_e32 v206, v94
	v_mov_b32_e32 v207, v95
	v_mov_b32_e32 v204, v200
	v_mov_b32_e32 v205, v201
	v_lshl_add_u64 v[212:213], v[102:103], 0, v[254:255]
	s_nop 0
	v_permlane16_swap_b32_e32 v204, v206
	v_permlane16_swap_b32_e32 v205, v207
	s_nop 1
	global_store_dwordx4 v[212:213], v[204:207], off
	s_cbranch_vccnz .LBB0_302
	global_load_dwordx4 v[90:93], v[104:105], off offset:128
	s_cbranch_execnz .LBB0_294

; DEVI float lo2f(unsigned u) { return __uint_as_float(u << 16); }
; DEVI float hi2f(unsigned u) { return __uint_as_float(u & 0xffff0000u); }
; DEVI void phase_resid_gemm(const Params& p, const bfu* A, int lda, int nkt, const bfu* wT, int ldb, const float* resid32,
;                            float* ssq_out, float* out32, char* lds) {
;     ...
;       for (int ni = 0; ni < 4; ++ni) {
;         const int n = n0 + wn * 64 + ni * 16 + fq * 4;
;         float4 r;
;         if (resid32) r = *(const float4*)(resid32 + (long)m * 1024 + n);
;         else { const uint2 u = *(const uint2*)(xs + (long)m * LDX + n); r = make_float4(lo2f(u.x), hi2f(u.x), lo2f(u.y), hi2f(u.y)); }
;         float4 o;
;         o.x = r.x + acc[ni][mi][0]; o.y = r.y + acc[ni][mi][1]; o.z = r.z + acc[ni][mi][2]; o.w = r.w + acc[ni][mi][3];
;         if (out32) *(float4*)(out32 + (long)m * 1024 + n) = o;
;         else {
;           uint2 ob; ob.x = pack2(o.x, o.y); ob.y = pack2(o.z, o.w);
;           *(uint2*)(xs + (long)m * LDX + n) = ob;
.LBB0_294:
	s_waitcnt vmcnt(0)
	v_pk_add_f32 v[86:87], v[86:87], v[90:91]
	v_pk_add_f32 v[88:89], v[88:89], v[92:93]
	v_cvt_pk_bf16_f32 v90, v86, v87
	v_cvt_pk_bf16_f32 v91, v88, v89
	s_and_b64 vcc, exec, s[40:41]
	v_mov_b32_e32 v200, v90
	v_mov_b32_e32 v201, v91
	s_cbranch_vccnz .LBB0_303
	global_load_dwordx4 v[86:89], v[104:105], off offset:192
	s_cbranch_execnz .LBB0_297

; DEVI float lo2f(unsigned u) { return __uint_as_float(u << 16); }
; DEVI float hi2f(unsigned u) { return __uint_as_float(u & 0xffff0000u); }
; DEVI void phase_resid_gemm(const Params& p, const bfu* A, int lda, int nkt, const bfu* wT, int ldb, const float* resid32,
;                            float* ssq_out, float* out32, char* lds) {
;     ...
; #pragma unroll
;       for (int ni = 0; ni < 4; ++ni) {
;         const int n = n0 + wn * 64 + ni * 16 + fq * 4;
;         float4 r;
;         if (resid32) r = *(const float4*)(resid32 + (long)m * 1024 + n);
;         else { const uint2 u = *(const uint2*)(xs + (long)m * LDX + n); r = make_float4(lo2f(u.x), hi2f(u.x), lo2f(u.y), hi2f(u.y)); }
;         float4 o;
;         o.x = r.x + acc[ni][mi][0]; o.y = r.y + acc[ni][mi][1]; o.z = r.z + acc[ni][mi][2]; o.w = r.w + acc[ni][mi][3];
;         if (out32) *(float4*)(out32 + (long)m * 1024 + n) = o;
;         else {
;           uint2 ob; ob.x = pack2(o.x, o.y); ob.y = pack2(o.z, o.w);
;           *(uint2*)(xs + (long)m * LDX + n) = ob;
;           const float q0 = lo2f(ob.x), q1 = hi2f(ob.x), q2 = lo2f(ob.y), q3 = hi2f(ob.y);
;           ss += q0 * q0 + q1 * q1 + q2 * q2 + q3 * q3;
;         }
;       }
;       if (!out32) {
;         ss += __shfl_xor(ss, 16);
;         ss += __shfl_xor(ss, 32);
;         if (fq == 0) part[(wm * 128 + mi * 16 + fr) * 4 + wn] = ss;
;       }
.LBB0_297:
	v_and_b32_e32 v93, 0xffff0000, v98
	v_lshlrev_b32_e32 v92, 16, v98
	v_mul_f32_e32 v93, v93, v93
	v_fmac_f32_e32 v93, v92, v92
	v_lshlrev_b32_e32 v92, 16, v94
	v_and_b32_e32 v94, 0xffff0000, v94
	v_lshlrev_b32_e32 v96, 16, v99
	v_mul_f32_e32 v94, v94, v94
	v_fmac_f32_e32 v93, v96, v96
	v_lshlrev_b32_e32 v96, 16, v95
	v_fmac_f32_e32 v94, v92, v92
	v_and_b32_e32 v97, 0xffff0000, v99
	v_and_b32_e32 v95, 0xffff0000, v95
	v_fmac_f32_e32 v94, v96, v96
	v_fmac_f32_e32 v93, v97, v97
	v_fmac_f32_e32 v94, v95, v95
	s_waitcnt vmcnt(0)
	v_pk_add_f32 v[78:79], v[78:79], v[86:87]
	v_add_f32_e32 v92, v93, v94
	v_lshlrev_b32_e32 v93, 16, v90
	v_and_b32_e32 v90, 0xffff0000, v90
	v_cvt_pk_bf16_f32 v86, v78, v79
	v_mul_f32_e32 v90, v90, v90
	v_pk_add_f32 v[80:81], v[80:81], v[88:89]
	v_and_b32_e32 v79, 0xffff0000, v86
	v_lshlrev_b32_e32 v94, 16, v91
	v_fmac_f32_e32 v90, v93, v93
	v_cvt_pk_bf16_f32 v87, v80, v81
	v_lshlrev_b32_e32 v78, 16, v86
	v_mul_f32_e32 v79, v79, v79
	v_and_b32_e32 v91, 0xffff0000, v91
	v_fmac_f32_e32 v90, v94, v94
	v_lshlrev_b32_e32 v80, 16, v87
	v_fmac_f32_e32 v79, v78, v78
	v_fmac_f32_e32 v90, v91, v91
	v_and_b32_e32 v81, 0xffff0000, v87
	v_fmac_f32_e32 v79, v80, v80
	v_add_f32_e32 v90, v92, v90
	v_fmac_f32_e32 v79, v81, v81
	v_add_f32_e32 v78, v90, v79
	ds_bpermute_b32 v79, v0, v78
	v_mov_b32_e32 v210, v86
	v_mov_b32_e32 v211, v87
	v_mov_b32_e32 v208, v200
	v_mov_b32_e32 v209, v201
	v_lshl_add_u64 v[212:213], v[102:103], 0, v[254:255]
	s_nop 0
	v_permlane16_swap_b32_e32 v208, v210
	v_permlane16_swap_b32_e32 v209, v211
	s_nop 1
	global_store_dwordx4 v[212:213], v[208:211], off offset:64
	s_waitcnt lgkmcnt(0)
	v_add_f32_e32 v78, v78, v79
	ds_bpermute_b32 v79, v122, v78
	s_and_saveexec_b64 s[36:37], s[38:39]
	s_cbranch_execz .LBB0_299
	s_waitcnt lgkmcnt(0)
	v_add_f32_e32 v78, v78, v79
	ds_write_b32 v183, v78 offset:512

; DEVI float lo2f(unsigned u) { return __uint_as_float(u << 16); }
; DEVI float hi2f(unsigned u) { return __uint_as_float(u & 0xffff0000u); }
; DEVI void phase_resid_gemm(const Params& p, const bfu* A, int lda, int nkt, const bfu* wT, int ldb, const float* resid32,
;                            float* ssq_out, float* out32, char* lds) {
;     ...
;       for (int ni = 0; ni < 4; ++ni) {
;         const int n = n0 + wn * 64 + ni * 16 + fq * 4;
;         float4 r;
;         if (resid32) r = *(const float4*)(resid32 + (long)m * 1024 + n);
;         else { const uint2 u = *(const uint2*)(xs + (long)m * LDX + n); r = make_float4(lo2f(u.x), hi2f(u.x), lo2f(u.y), hi2f(u.y)); }
;         float4 o;
;         o.x = r.x + acc[ni][mi][0]; o.y = r.y + acc[ni][mi][1]; o.z = r.z + acc[ni][mi][2]; o.w = r.w + acc[ni][mi][3];
;         if (out32) *(float4*)(out32 + (long)m * 1024 + n) = o;
;         else {
;           uint2 ob; ob.x = pack2(o.x, o.y); ob.y = pack2(o.z, o.w);
;           *(uint2*)(xs + (long)m * LDX + n) = ob;
.LBB0_307:
	s_waitcnt vmcnt(0)
	v_pk_add_f32 v[78:79], v[82:83], v[78:79]
	v_pk_add_f32 v[80:81], v[84:85], v[80:81]
	v_cvt_pk_bf16_f32 v82, v78, v79
	v_cvt_pk_bf16_f32 v83, v80, v81
	s_and_b64 vcc, exec, s[40:41]
	v_mov_b32_e32 v200, v82
	v_mov_b32_e32 v201, v83
	s_cbranch_vccnz .LBB0_320
	global_load_dwordx4 v[78:81], v[88:89], off offset:64
	s_cbranch_execnz .LBB0_310

; DEVI float lo2f(unsigned u) { return __uint_as_float(u << 16); }
; DEVI float hi2f(unsigned u) { return __uint_as_float(u & 0xffff0000u); }
; DEVI void phase_resid_gemm(const Params& p, const bfu* A, int lda, int nkt, const bfu* wT, int ldb, const float* resid32,
;                            float* ssq_out, float* out32, char* lds) {
;     ...
;       for (int ni = 0; ni < 4; ++ni) {
;         const int n = n0 + wn * 64 + ni * 16 + fq * 4;
;         float4 r;
;         if (resid32) r = *(const float4*)(resid32 + (long)m * 1024 + n);
;         else { const uint2 u = *(const uint2*)(xs + (long)m * LDX + n); r = make_float4(lo2f(u.x), hi2f(u.x), lo2f(u.y), hi2f(u.y)); }
;         float4 o;
;         o.x = r.x + acc[ni][mi][0]; o.y = r.y + acc[ni][mi][1]; o.z = r.z + acc[ni][mi][2]; o.w = r.w + acc[ni][mi][3];
;         if (out32) *(float4*)(out32 + (long)m * 1024 + n) = o;
;         else {
;           uint2 ob; ob.x = pack2(o.x, o.y); ob.y = pack2(o.z, o.w);
;           *(uint2*)(xs + (long)m * LDX + n) = ob;
.LBB0_310:
	s_waitcnt vmcnt(0)
	v_pk_add_f32 v[74:75], v[74:75], v[78:79]
	v_pk_add_f32 v[76:77], v[76:77], v[80:81]
	v_cvt_pk_bf16_f32 v78, v74, v75
	v_cvt_pk_bf16_f32 v79, v76, v77
	s_and_b64 vcc, exec, s[40:41]
	v_mov_b32_e32 v206, v78
	v_mov_b32_e32 v207, v79
	v_mov_b32_e32 v204, v200
	v_mov_b32_e32 v205, v201
	v_lshl_add_u64 v[212:213], v[86:87], 0, v[254:255]
	s_nop 0
	v_permlane16_swap_b32_e32 v204, v206
	v_permlane16_swap_b32_e32 v205, v207
	s_nop 1
	global_store_dwordx4 v[212:213], v[204:207], off
	s_cbranch_vccnz .LBB0_321
	global_load_dwordx4 v[74:77], v[88:89], off offset:128
	s_cbranch_execnz .LBB0_313

; DEVI float lo2f(unsigned u) { return __uint_as_float(u << 16); }
; DEVI float hi2f(unsigned u) { return __uint_as_float(u & 0xffff0000u); }
; DEVI void phase_resid_gemm(const Params& p, const bfu* A, int lda, int nkt, const bfu* wT, int ldb, const float* resid32,
;                            float* ssq_out, float* out32, char* lds) {
;     ...
;       for (int ni = 0; ni < 4; ++ni) {
;         const int n = n0 + wn * 64 + ni * 16 + fq * 4;
;         float4 r;
;         if (resid32) r = *(const float4*)(resid32 + (long)m * 1024 + n);
;         else { const uint2 u = *(const uint2*)(xs + (long)m * LDX + n); r = make_float4(lo2f(u.x), hi2f(u.x), lo2f(u.y), hi2f(u.y)); }
;         float4 o;
;         o.x = r.x + acc[ni][mi][0]; o.y = r.y + acc[ni][mi][1]; o.z = r.z + acc[ni][mi][2]; o.w = r.w + acc[ni][mi][3];
;         if (out32) *(float4*)(out32 + (long)m * 1024 + n) = o;
;         else {
;           uint2 ob; ob.x = pack2(o.x, o.y); ob.y = pack2(o.z, o.w);
;           *(uint2*)(xs + (long)m * LDX + n) = ob;
.LBB0_313:
	s_waitcnt vmcnt(0)
	v_pk_add_f32 v[70:71], v[70:71], v[74:75]
	v_pk_add_f32 v[72:73], v[72:73], v[76:77]
	v_cvt_pk_bf16_f32 v74, v70, v71
	v_cvt_pk_bf16_f32 v75, v72, v73
	s_and_b64 vcc, exec, s[40:41]
	v_mov_b32_e32 v200, v74
	v_mov_b32_e32 v201, v75
	s_cbranch_vccnz .LBB0_322
	global_load_dwordx4 v[70:73], v[88:89], off offset:192
	s_cbranch_execnz .LBB0_316

; DEVI float lo2f(unsigned u) { return __uint_as_float(u << 16); }
; DEVI float hi2f(unsigned u) { return __uint_as_float(u & 0xffff0000u); }
; DEVI void phase_resid_gemm(const Params& p, const bfu* A, int lda, int nkt, const bfu* wT, int ldb, const float* resid32,
;                            float* ssq_out, float* out32, char* lds) {
;     ...
; #pragma unroll
;       for (int ni = 0; ni < 4; ++ni) {
;         const int n = n0 + wn * 64 + ni * 16 + fq * 4;
;         float4 r;
;         if (resid32) r = *(const float4*)(resid32 + (long)m * 1024 + n);
;         else { const uint2 u = *(const uint2*)(xs + (long)m * LDX + n); r = make_float4(lo2f(u.x), hi2f(u.x), lo2f(u.y), hi2f(u.y)); }
;         float4 o;
;         o.x = r.x + acc[ni][mi][0]; o.y = r.y + acc[ni][mi][1]; o.z = r.z + acc[ni][mi][2]; o.w = r.w + acc[ni][mi][3];
;         if (out32) *(float4*)(out32 + (long)m * 1024 + n) = o;
;         else {
;           uint2 ob; ob.x = pack2(o.x, o.y); ob.y = pack2(o.z, o.w);
;           *(uint2*)(xs + (long)m * LDX + n) = ob;
;           const float q0 = lo2f(ob.x), q1 = hi2f(ob.x), q2 = lo2f(ob.y), q3 = hi2f(ob.y);
;           ss += q0 * q0 + q1 * q1 + q2 * q2 + q3 * q3;
;         }
;       }
;       if (!out32) {
;         ss += __shfl_xor(ss, 16);
;         ss += __shfl_xor(ss, 32);
;         if (fq == 0) part[(wm * 128 + mi * 16 + fr) * 4 + wn] = ss;
;       }
.LBB0_316:
	v_and_b32_e32 v77, 0xffff0000, v82
	v_lshlrev_b32_e32 v76, 16, v82
	v_mul_f32_e32 v77, v77, v77
	v_fmac_f32_e32 v77, v76, v76
	v_lshlrev_b32_e32 v76, 16, v78
	v_and_b32_e32 v78, 0xffff0000, v78
	v_lshlrev_b32_e32 v80, 16, v83
	v_mul_f32_e32 v78, v78, v78
	v_fmac_f32_e32 v77, v80, v80
	v_lshlrev_b32_e32 v80, 16, v79
	v_fmac_f32_e32 v78, v76, v76
	v_and_b32_e32 v81, 0xffff0000, v83
	v_and_b32_e32 v79, 0xffff0000, v79
	v_fmac_f32_e32 v78, v80, v80
	v_fmac_f32_e32 v77, v81, v81
	v_fmac_f32_e32 v78, v79, v79
	s_waitcnt vmcnt(0)
	v_pk_add_f32 v[62:63], v[62:63], v[70:71]
	v_add_f32_e32 v76, v77, v78
	v_lshlrev_b32_e32 v77, 16, v74
	v_and_b32_e32 v74, 0xffff0000, v74
	v_cvt_pk_bf16_f32 v70, v62, v63
	v_mul_f32_e32 v74, v74, v74
	v_pk_add_f32 v[64:65], v[64:65], v[72:73]
	v_and_b32_e32 v63, 0xffff0000, v70
	v_lshlrev_b32_e32 v78, 16, v75
	v_fmac_f32_e32 v74, v77, v77
	v_cvt_pk_bf16_f32 v71, v64, v65
	v_lshlrev_b32_e32 v62, 16, v70
	v_mul_f32_e32 v63, v63, v63
	v_and_b32_e32 v75, 0xffff0000, v75
	v_fmac_f32_e32 v74, v78, v78
	v_lshlrev_b32_e32 v64, 16, v71
	v_fmac_f32_e32 v63, v62, v62
	v_fmac_f32_e32 v74, v75, v75
	v_and_b32_e32 v65, 0xffff0000, v71
	v_fmac_f32_e32 v63, v64, v64
	v_add_f32_e32 v74, v76, v74
	v_fmac_f32_e32 v63, v65, v65
	v_add_f32_e32 v62, v74, v63
	ds_bpermute_b32 v63, v0, v62
	v_mov_b32_e32 v210, v70
	v_mov_b32_e32 v211, v71
	v_mov_b32_e32 v208, v200
	v_mov_b32_e32 v209, v201
	v_lshl_add_u64 v[212:213], v[86:87], 0, v[254:255]
	s_nop 0
	v_permlane16_swap_b32_e32 v208, v210
	v_permlane16_swap_b32_e32 v209, v211
	s_nop 1
	global_store_dwordx4 v[212:213], v[208:211], off offset:64
	s_waitcnt lgkmcnt(0)
	v_add_f32_e32 v62, v62, v63
	ds_bpermute_b32 v63, v122, v62
	s_and_saveexec_b64 s[36:37], s[38:39]
	s_cbranch_execz .LBB0_318
	s_waitcnt lgkmcnt(0)
	v_add_f32_e32 v62, v62, v63
	ds_write_b32 v183, v62 offset:768

; DEVI float lo2f(unsigned u) { return __uint_as_float(u << 16); }
; DEVI float hi2f(unsigned u) { return __uint_as_float(u & 0xffff0000u); }
; DEVI void phase_resid_gemm(const Params& p, const bfu* A, int lda, int nkt, const bfu* wT, int ldb, const float* resid32,
;                            float* ssq_out, float* out32, char* lds) {
;     ...
;       for (int ni = 0; ni < 4; ++ni) {
;         const int n = n0 + wn * 64 + ni * 16 + fq * 4;
;         float4 r;
;         if (resid32) r = *(const float4*)(resid32 + (long)m * 1024 + n);
;         else { const uint2 u = *(const uint2*)(xs + (long)m * LDX + n); r = make_float4(lo2f(u.x), hi2f(u.x), lo2f(u.y), hi2f(u.y)); }
;         float4 o;
;         o.x = r.x + acc[ni][mi][0]; o.y = r.y + acc[ni][mi][1]; o.z = r.z + acc[ni][mi][2]; o.w = r.w + acc[ni][mi][3];
;         if (out32) *(float4*)(out32 + (long)m * 1024 + n) = o;
;         else {
;           uint2 ob; ob.x = pack2(o.x, o.y); ob.y = pack2(o.z, o.w);
;           *(uint2*)(xs + (long)m * LDX + n) = ob;
.LBB0_326:
	s_waitcnt vmcnt(0)
	v_pk_add_f32 v[62:63], v[66:67], v[62:63]
	v_pk_add_f32 v[64:65], v[68:69], v[64:65]
	v_cvt_pk_bf16_f32 v66, v62, v63
	v_cvt_pk_bf16_f32 v67, v64, v65
	s_and_b64 vcc, exec, s[40:41]
	v_mov_b32_e32 v200, v66
	v_mov_b32_e32 v201, v67
	s_cbranch_vccnz .LBB0_339
	global_load_dwordx4 v[62:65], v[72:73], off offset:64
	s_cbranch_execnz .LBB0_329

; DEVI float lo2f(unsigned u) { return __uint_as_float(u << 16); }
; DEVI float hi2f(unsigned u) { return __uint_as_float(u & 0xffff0000u); }
; DEVI void phase_resid_gemm(const Params& p, const bfu* A, int lda, int nkt, const bfu* wT, int ldb, const float* resid32,
;                            float* ssq_out, float* out32, char* lds) {
;     ...
;       for (int ni = 0; ni < 4; ++ni) {
;         const int n = n0 + wn * 64 + ni * 16 + fq * 4;
;         float4 r;
;         if (resid32) r = *(const float4*)(resid32 + (long)m * 1024 + n);
;         else { const uint2 u = *(const uint2*)(xs + (long)m * LDX + n); r = make_float4(lo2f(u.x), hi2f(u.x), lo2f(u.y), hi2f(u.y)); }
;         float4 o;
;         o.x = r.x + acc[ni][mi][0]; o.y = r.y + acc[ni][mi][1]; o.z = r.z + acc[ni][mi][2]; o.w = r.w + acc[ni][mi][3];
;         if (out32) *(float4*)(out32 + (long)m * 1024 + n) = o;
;         else {
;           uint2 ob; ob.x = pack2(o.x, o.y); ob.y = pack2(o.z, o.w);
;           *(uint2*)(xs + (long)m * LDX + n) = ob;
.LBB0_329:
	s_waitcnt vmcnt(0)
	v_pk_add_f32 v[58:59], v[58:59], v[62:63]
	v_pk_add_f32 v[60:61], v[60:61], v[64:65]
	v_cvt_pk_bf16_f32 v62, v58, v59
	v_cvt_pk_bf16_f32 v63, v60, v61
	s_and_b64 vcc, exec, s[40:41]
	v_mov_b32_e32 v206, v62
	v_mov_b32_e32 v207, v63
	v_mov_b32_e32 v204, v200
	v_mov_b32_e32 v205, v201
	v_lshl_add_u64 v[212:213], v[70:71], 0, v[254:255]
	s_nop 0
	v_permlane16_swap_b32_e32 v204, v206
	v_permlane16_swap_b32_e32 v205, v207
	s_nop 1
	global_store_dwordx4 v[212:213], v[204:207], off
	s_cbranch_vccnz .LBB0_340
	global_load_dwordx4 v[58:61], v[72:73], off offset:128
	s_cbranch_execnz .LBB0_332

; DEVI float lo2f(unsigned u) { return __uint_as_float(u << 16); }
; DEVI float hi2f(unsigned u) { return __uint_as_float(u & 0xffff0000u); }
; DEVI void phase_resid_gemm(const Params& p, const bfu* A, int lda, int nkt, const bfu* wT, int ldb, const float* resid32,
;                            float* ssq_out, float* out32, char* lds) {
;     ...
;       for (int ni = 0; ni < 4; ++ni) {
;         const int n = n0 + wn * 64 + ni * 16 + fq * 4;
;         float4 r;
;         if (resid32) r = *(const float4*)(resid32 + (long)m * 1024 + n);
;         else { const uint2 u = *(const uint2*)(xs + (long)m * LDX + n); r = make_float4(lo2f(u.x), hi2f(u.x), lo2f(u.y), hi2f(u.y)); }
;         float4 o;
;         o.x = r.x + acc[ni][mi][0]; o.y = r.y + acc[ni][mi][1]; o.z = r.z + acc[ni][mi][2]; o.w = r.w + acc[ni][mi][3];
;         if (out32) *(float4*)(out32 + (long)m * 1024 + n) = o;
;         else {
;           uint2 ob; ob.x = pack2(o.x, o.y); ob.y = pack2(o.z, o.w);
;           *(uint2*)(xs + (long)m * LDX + n) = ob;
.LBB0_332:
	s_waitcnt vmcnt(0)
	v_pk_add_f32 v[54:55], v[54:55], v[58:59]
	v_pk_add_f32 v[56:57], v[56:57], v[60:61]
	v_cvt_pk_bf16_f32 v58, v54, v55
	v_cvt_pk_bf16_f32 v59, v56, v57
	s_and_b64 vcc, exec, s[40:41]
	v_mov_b32_e32 v200, v58
	v_mov_b32_e32 v201, v59
	s_cbranch_vccnz .LBB0_341
	global_load_dwordx4 v[54:57], v[72:73], off offset:192
	s_cbranch_execnz .LBB0_335

; DEVI float lo2f(unsigned u) { return __uint_as_float(u << 16); }
; DEVI float hi2f(unsigned u) { return __uint_as_float(u & 0xffff0000u); }
; DEVI void phase_resid_gemm(const Params& p, const bfu* A, int lda, int nkt, const bfu* wT, int ldb, const float* resid32,
;                            float* ssq_out, float* out32, char* lds) {
;     ...
; #pragma unroll
;       for (int ni = 0; ni < 4; ++ni) {
;         const int n = n0 + wn * 64 + ni * 16 + fq * 4;
;         float4 r;
;         if (resid32) r = *(const float4*)(resid32 + (long)m * 1024 + n);
;         else { const uint2 u = *(const uint2*)(xs + (long)m * LDX + n); r = make_float4(lo2f(u.x), hi2f(u.x), lo2f(u.y), hi2f(u.y)); }
;         float4 o;
;         o.x = r.x + acc[ni][mi][0]; o.y = r.y + acc[ni][mi][1]; o.z = r.z + acc[ni][mi][2]; o.w = r.w + acc[ni][mi][3];
;         if (out32) *(float4*)(out32 + (long)m * 1024 + n) = o;
;         else {
;           uint2 ob; ob.x = pack2(o.x, o.y); ob.y = pack2(o.z, o.w);
;           *(uint2*)(xs + (long)m * LDX + n) = ob;
;           const float q0 = lo2f(ob.x), q1 = hi2f(ob.x), q2 = lo2f(ob.y), q3 = hi2f(ob.y);
;           ss += q0 * q0 + q1 * q1 + q2 * q2 + q3 * q3;
;         }
;       }
;       if (!out32) {
;         ss += __shfl_xor(ss, 16);
;         ss += __shfl_xor(ss, 32);
;         if (fq == 0) part[(wm * 128 + mi * 16 + fr) * 4 + wn] = ss;
;       }
.LBB0_335:
	v_and_b32_e32 v61, 0xffff0000, v66
	v_lshlrev_b32_e32 v60, 16, v66
	v_mul_f32_e32 v61, v61, v61
	v_fmac_f32_e32 v61, v60, v60
	v_lshlrev_b32_e32 v60, 16, v62
	v_and_b32_e32 v62, 0xffff0000, v62
	v_lshlrev_b32_e32 v64, 16, v67
	v_mul_f32_e32 v62, v62, v62
	v_fmac_f32_e32 v61, v64, v64
	v_lshlrev_b32_e32 v64, 16, v63
	v_fmac_f32_e32 v62, v60, v60
	v_and_b32_e32 v65, 0xffff0000, v67
	v_and_b32_e32 v63, 0xffff0000, v63
	v_fmac_f32_e32 v62, v64, v64
	v_fmac_f32_e32 v61, v65, v65
	v_fmac_f32_e32 v62, v63, v63
	s_waitcnt vmcnt(0)
	v_pk_add_f32 v[46:47], v[46:47], v[54:55]
	v_add_f32_e32 v60, v61, v62
	v_lshlrev_b32_e32 v61, 16, v58
	v_and_b32_e32 v58, 0xffff0000, v58
	v_cvt_pk_bf16_f32 v54, v46, v47
	v_mul_f32_e32 v58, v58, v58
	v_pk_add_f32 v[48:49], v[48:49], v[56:57]
	v_and_b32_e32 v47, 0xffff0000, v54
	v_lshlrev_b32_e32 v62, 16, v59
	v_fmac_f32_e32 v58, v61, v61
	v_cvt_pk_bf16_f32 v55, v48, v49
	v_lshlrev_b32_e32 v46, 16, v54
	v_mul_f32_e32 v47, v47, v47
	v_and_b32_e32 v59, 0xffff0000, v59
	v_fmac_f32_e32 v58, v62, v62
	v_lshlrev_b32_e32 v48, 16, v55
	v_fmac_f32_e32 v47, v46, v46
	v_fmac_f32_e32 v58, v59, v59
	v_and_b32_e32 v49, 0xffff0000, v55
	v_fmac_f32_e32 v47, v48, v48
	v_add_f32_e32 v58, v60, v58
	v_fmac_f32_e32 v47, v49, v49
	v_add_f32_e32 v46, v58, v47
	ds_bpermute_b32 v47, v0, v46
	v_mov_b32_e32 v210, v54
	v_mov_b32_e32 v211, v55
	v_mov_b32_e32 v208, v200
	v_mov_b32_e32 v209, v201
	v_lshl_add_u64 v[212:213], v[70:71], 0, v[254:255]
	s_nop 0
	v_permlane16_swap_b32_e32 v208, v210
	v_permlane16_swap_b32_e32 v209, v211
	s_nop 1
	global_store_dwordx4 v[212:213], v[208:211], off offset:64
	s_waitcnt lgkmcnt(0)
	v_add_f32_e32 v46, v46, v47
	ds_bpermute_b32 v47, v122, v46
	s_and_saveexec_b64 s[36:37], s[38:39]
	s_cbranch_execz .LBB0_337
	s_waitcnt lgkmcnt(0)
	v_add_f32_e32 v46, v46, v47
	ds_write_b32 v183, v46 offset:1024

; DEVI float lo2f(unsigned u) { return __uint_as_float(u << 16); }
; DEVI float hi2f(unsigned u) { return __uint_as_float(u & 0xffff0000u); }
; DEVI void phase_resid_gemm(const Params& p, const bfu* A, int lda, int nkt, const bfu* wT, int ldb, const float* resid32,
;                            float* ssq_out, float* out32, char* lds) {
;     ...
;       for (int ni = 0; ni < 4; ++ni) {
;         const int n = n0 + wn * 64 + ni * 16 + fq * 4;
;         float4 r;
;         if (resid32) r = *(const float4*)(resid32 + (long)m * 1024 + n);
;         else { const uint2 u = *(const uint2*)(xs + (long)m * LDX + n); r = make_float4(lo2f(u.x), hi2f(u.x), lo2f(u.y), hi2f(u.y)); }
;         float4 o;
;         o.x = r.x + acc[ni][mi][0]; o.y = r.y + acc[ni][mi][1]; o.z = r.z + acc[ni][mi][2]; o.w = r.w + acc[ni][mi][3];
;         if (out32) *(float4*)(out32 + (long)m * 1024 + n) = o;
;         else {
;           uint2 ob; ob.x = pack2(o.x, o.y); ob.y = pack2(o.z, o.w);
;           *(uint2*)(xs + (long)m * LDX + n) = ob;
.LBB0_345:
	s_waitcnt vmcnt(0)
	v_pk_add_f32 v[46:47], v[50:51], v[46:47]
	v_pk_add_f32 v[48:49], v[52:53], v[48:49]
	v_cvt_pk_bf16_f32 v50, v46, v47
	v_cvt_pk_bf16_f32 v51, v48, v49
	s_and_b64 vcc, exec, s[40:41]
	v_mov_b32_e32 v200, v50
	v_mov_b32_e32 v201, v51
	s_cbranch_vccnz .LBB0_358
	global_load_dwordx4 v[46:49], v[56:57], off offset:64
	s_cbranch_execnz .LBB0_348

; DEVI float lo2f(unsigned u) { return __uint_as_float(u << 16); }
; DEVI float hi2f(unsigned u) { return __uint_as_float(u & 0xffff0000u); }
; DEVI void phase_resid_gemm(const Params& p, const bfu* A, int lda, int nkt, const bfu* wT, int ldb, const float* resid32,
;                            float* ssq_out, float* out32, char* lds) {
;     ...
;       for (int ni = 0; ni < 4; ++ni) {
;         const int n = n0 + wn * 64 + ni * 16 + fq * 4;
;         float4 r;
;         if (resid32) r = *(const float4*)(resid32 + (long)m * 1024 + n);
;         else { const uint2 u = *(const uint2*)(xs + (long)m * LDX + n); r = make_float4(lo2f(u.x), hi2f(u.x), lo2f(u.y), hi2f(u.y)); }
;         float4 o;
;         o.x = r.x + acc[ni][mi][0]; o.y = r.y + acc[ni][mi][1]; o.z = r.z + acc[ni][mi][2]; o.w = r.w + acc[ni][mi][3];
;         if (out32) *(float4*)(out32 + (long)m * 1024 + n) = o;
;         else {
;           uint2 ob; ob.x = pack2(o.x, o.y); ob.y = pack2(o.z, o.w);
;           *(uint2*)(xs + (long)m * LDX + n) = ob;
.LBB0_348:
	s_waitcnt vmcnt(0)
	v_pk_add_f32 v[42:43], v[42:43], v[46:47]
	v_pk_add_f32 v[44:45], v[44:45], v[48:49]
	v_cvt_pk_bf16_f32 v46, v42, v43
	v_cvt_pk_bf16_f32 v47, v44, v45
	s_and_b64 vcc, exec, s[40:41]
	v_mov_b32_e32 v206, v46
	v_mov_b32_e32 v207, v47
	v_mov_b32_e32 v204, v200
	v_mov_b32_e32 v205, v201
	v_lshl_add_u64 v[212:213], v[54:55], 0, v[254:255]
	s_nop 0
	v_permlane16_swap_b32_e32 v204, v206
	v_permlane16_swap_b32_e32 v205, v207
	s_nop 1
	global_store_dwordx4 v[212:213], v[204:207], off
	s_cbranch_vccnz .LBB0_359
	global_load_dwordx4 v[42:45], v[56:57], off offset:128
	s_cbranch_execnz .LBB0_351

; DEVI float lo2f(unsigned u) { return __uint_as_float(u << 16); }
; DEVI float hi2f(unsigned u) { return __uint_as_float(u & 0xffff0000u); }
; DEVI void phase_resid_gemm(const Params& p, const bfu* A, int lda, int nkt, const bfu* wT, int ldb, const float* resid32,
;                            float* ssq_out, float* out32, char* lds) {
;     ...
;       for (int ni = 0; ni < 4; ++ni) {
;         const int n = n0 + wn * 64 + ni * 16 + fq * 4;
;         float4 r;
;         if (resid32) r = *(const float4*)(resid32 + (long)m * 1024 + n);
;         else { const uint2 u = *(const uint2*)(xs + (long)m * LDX + n); r = make_float4(lo2f(u.x), hi2f(u.x), lo2f(u.y), hi2f(u.y)); }
;         float4 o;
;         o.x = r.x + acc[ni][mi][0]; o.y = r.y + acc[ni][mi][1]; o.z = r.z + acc[ni][mi][2]; o.w = r.w + acc[ni][mi][3];
;         if (out32) *(float4*)(out32 + (long)m * 1024 + n) = o;
;         else {
;           uint2 ob; ob.x = pack2(o.x, o.y); ob.y = pack2(o.z, o.w);
;           *(uint2*)(xs + (long)m * LDX + n) = ob;
.LBB0_351:
	s_waitcnt vmcnt(0)
	v_pk_add_f32 v[38:39], v[38:39], v[42:43]
	v_pk_add_f32 v[40:41], v[40:41], v[44:45]
	v_cvt_pk_bf16_f32 v42, v38, v39
	v_cvt_pk_bf16_f32 v43, v40, v41
	s_and_b64 vcc, exec, s[40:41]
	v_mov_b32_e32 v200, v42
	v_mov_b32_e32 v201, v43
	s_cbranch_vccnz .LBB0_360
	global_load_dwordx4 v[38:41], v[56:57], off offset:192
	s_cbranch_execnz .LBB0_354

; DEVI float lo2f(unsigned u) { return __uint_as_float(u << 16); }
; DEVI float hi2f(unsigned u) { return __uint_as_float(u & 0xffff0000u); }
; DEVI void phase_resid_gemm(const Params& p, const bfu* A, int lda, int nkt, const bfu* wT, int ldb, const float* resid32,
;                            float* ssq_out, float* out32, char* lds) {
;     ...
; #pragma unroll
;       for (int ni = 0; ni < 4; ++ni) {
;         const int n = n0 + wn * 64 + ni * 16 + fq * 4;
;         float4 r;
;         if (resid32) r = *(const float4*)(resid32 + (long)m * 1024 + n);
;         else { const uint2 u = *(const uint2*)(xs + (long)m * LDX + n); r = make_float4(lo2f(u.x), hi2f(u.x), lo2f(u.y), hi2f(u.y)); }
;         float4 o;
;         o.x = r.x + acc[ni][mi][0]; o.y = r.y + acc[ni][mi][1]; o.z = r.z + acc[ni][mi][2]; o.w = r.w + acc[ni][mi][3];
;         if (out32) *(float4*)(out32 + (long)m * 1024 + n) = o;
;         else {
;           uint2 ob; ob.x = pack2(o.x, o.y); ob.y = pack2(o.z, o.w);
;           *(uint2*)(xs + (long)m * LDX + n) = ob;
;           const float q0 = lo2f(ob.x), q1 = hi2f(ob.x), q2 = lo2f(ob.y), q3 = hi2f(ob.y);
;           ss += q0 * q0 + q1 * q1 + q2 * q2 + q3 * q3;
;         }
;       }
;       if (!out32) {
;         ss += __shfl_xor(ss, 16);
;         ss += __shfl_xor(ss, 32);
;         if (fq == 0) part[(wm * 128 + mi * 16 + fr) * 4 + wn] = ss;
;       }
.LBB0_354:
	v_and_b32_e32 v45, 0xffff0000, v50
	v_lshlrev_b32_e32 v44, 16, v50
	v_mul_f32_e32 v45, v45, v45
	v_fmac_f32_e32 v45, v44, v44
	v_lshlrev_b32_e32 v44, 16, v46
	v_and_b32_e32 v46, 0xffff0000, v46
	v_lshlrev_b32_e32 v48, 16, v51
	v_mul_f32_e32 v46, v46, v46
	v_fmac_f32_e32 v45, v48, v48
	v_lshlrev_b32_e32 v48, 16, v47
	v_fmac_f32_e32 v46, v44, v44
	v_and_b32_e32 v49, 0xffff0000, v51
	v_and_b32_e32 v47, 0xffff0000, v47
	v_fmac_f32_e32 v46, v48, v48
	v_fmac_f32_e32 v45, v49, v49
	v_fmac_f32_e32 v46, v47, v47
	s_waitcnt vmcnt(0)
	v_pk_add_f32 v[30:31], v[30:31], v[38:39]
	v_add_f32_e32 v44, v45, v46
	v_lshlrev_b32_e32 v45, 16, v42
	v_and_b32_e32 v42, 0xffff0000, v42
	v_cvt_pk_bf16_f32 v38, v30, v31
	v_mul_f32_e32 v42, v42, v42
	v_pk_add_f32 v[32:33], v[32:33], v[40:41]
	v_and_b32_e32 v31, 0xffff0000, v38
	v_lshlrev_b32_e32 v46, 16, v43
	v_fmac_f32_e32 v42, v45, v45
	v_cvt_pk_bf16_f32 v39, v32, v33
	v_lshlrev_b32_e32 v30, 16, v38
	v_mul_f32_e32 v31, v31, v31
	v_and_b32_e32 v43, 0xffff0000, v43
	v_fmac_f32_e32 v42, v46, v46
	v_lshlrev_b32_e32 v32, 16, v39
	v_fmac_f32_e32 v31, v30, v30
	v_fmac_f32_e32 v42, v43, v43
	v_and_b32_e32 v33, 0xffff0000, v39
	v_fmac_f32_e32 v31, v32, v32
	v_add_f32_e32 v42, v44, v42
	v_fmac_f32_e32 v31, v33, v33
	v_add_f32_e32 v30, v42, v31
	ds_bpermute_b32 v31, v0, v30
	v_mov_b32_e32 v210, v38
	v_mov_b32_e32 v211, v39
	v_mov_b32_e32 v208, v200
	v_mov_b32_e32 v209, v201
	v_lshl_add_u64 v[212:213], v[54:55], 0, v[254:255]
	s_nop 0
	v_permlane16_swap_b32_e32 v208, v210
	v_permlane16_swap_b32_e32 v209, v211
	s_nop 1
	global_store_dwordx4 v[212:213], v[208:211], off offset:64
	s_waitcnt lgkmcnt(0)
	v_add_f32_e32 v30, v30, v31
	ds_bpermute_b32 v31, v122, v30
	s_and_saveexec_b64 s[36:37], s[38:39]
	s_cbranch_execz .LBB0_356
	s_waitcnt lgkmcnt(0)
	v_add_f32_e32 v30, v30, v31
	ds_write_b32 v183, v30 offset:1280

; DEVI float lo2f(unsigned u) { return __uint_as_float(u << 16); }
; DEVI float hi2f(unsigned u) { return __uint_as_float(u & 0xffff0000u); }
; DEVI void phase_resid_gemm(const Params& p, const bfu* A, int lda, int nkt, const bfu* wT, int ldb, const float* resid32,
;                            float* ssq_out, float* out32, char* lds) {
;     ...
;       for (int ni = 0; ni < 4; ++ni) {
;         const int n = n0 + wn * 64 + ni * 16 + fq * 4;
;         float4 r;
;         if (resid32) r = *(const float4*)(resid32 + (long)m * 1024 + n);
;         else { const uint2 u = *(const uint2*)(xs + (long)m * LDX + n); r = make_float4(lo2f(u.x), hi2f(u.x), lo2f(u.y), hi2f(u.y)); }
;         float4 o;
;         o.x = r.x + acc[ni][mi][0]; o.y = r.y + acc[ni][mi][1]; o.z = r.z + acc[ni][mi][2]; o.w = r.w + acc[ni][mi][3];
;         if (out32) *(float4*)(out32 + (long)m * 1024 + n) = o;
;         else {
;           uint2 ob; ob.x = pack2(o.x, o.y); ob.y = pack2(o.z, o.w);
;           *(uint2*)(xs + (long)m * LDX + n) = ob;
.LBB0_364:
	s_waitcnt vmcnt(0)
	v_pk_add_f32 v[30:31], v[34:35], v[30:31]
	v_pk_add_f32 v[32:33], v[36:37], v[32:33]
	v_cvt_pk_bf16_f32 v34, v30, v31
	v_cvt_pk_bf16_f32 v35, v32, v33
	s_and_b64 vcc, exec, s[40:41]
	v_mov_b32_e32 v200, v34
	v_mov_b32_e32 v201, v35
	s_cbranch_vccnz .LBB0_377
	global_load_dwordx4 v[30:33], v[40:41], off offset:64
	s_cbranch_execnz .LBB0_367

; DEVI float lo2f(unsigned u) { return __uint_as_float(u << 16); }
; DEVI float hi2f(unsigned u) { return __uint_as_float(u & 0xffff0000u); }
; DEVI void phase_resid_gemm(const Params& p, const bfu* A, int lda, int nkt, const bfu* wT, int ldb, const float* resid32,
;                            float* ssq_out, float* out32, char* lds) {
;     ...
;       for (int ni = 0; ni < 4; ++ni) {
;         const int n = n0 + wn * 64 + ni * 16 + fq * 4;
;         float4 r;
;         if (resid32) r = *(const float4*)(resid32 + (long)m * 1024 + n);
;         else { const uint2 u = *(const uint2*)(xs + (long)m * LDX + n); r = make_float4(lo2f(u.x), hi2f(u.x), lo2f(u.y), hi2f(u.y)); }
;         float4 o;
;         o.x = r.x + acc[ni][mi][0]; o.y = r.y + acc[ni][mi][1]; o.z = r.z + acc[ni][mi][2]; o.w = r.w + acc[ni][mi][3];
;         if (out32) *(float4*)(out32 + (long)m * 1024 + n) = o;
;         else {
;           uint2 ob; ob.x = pack2(o.x, o.y); ob.y = pack2(o.z, o.w);
;           *(uint2*)(xs + (long)m * LDX + n) = ob;
.LBB0_367:
	s_waitcnt vmcnt(0)
	v_pk_add_f32 v[26:27], v[26:27], v[30:31]
	v_pk_add_f32 v[28:29], v[28:29], v[32:33]
	v_cvt_pk_bf16_f32 v30, v26, v27
	v_cvt_pk_bf16_f32 v31, v28, v29
	s_and_b64 vcc, exec, s[40:41]
	v_mov_b32_e32 v206, v30
	v_mov_b32_e32 v207, v31
	v_mov_b32_e32 v204, v200
	v_mov_b32_e32 v205, v201
	v_lshl_add_u64 v[212:213], v[38:39], 0, v[254:255]
	s_nop 0
	v_permlane16_swap_b32_e32 v204, v206
	v_permlane16_swap_b32_e32 v205, v207
	s_nop 1
	global_store_dwordx4 v[212:213], v[204:207], off
	s_cbranch_vccnz .LBB0_378
	global_load_dwordx4 v[26:29], v[40:41], off offset:128
	s_cbranch_execnz .LBB0_370

; DEVI float lo2f(unsigned u) { return __uint_as_float(u << 16); }
; DEVI float hi2f(unsigned u) { return __uint_as_float(u & 0xffff0000u); }
; DEVI void phase_resid_gemm(const Params& p, const bfu* A, int lda, int nkt, const bfu* wT, int ldb, const float* resid32,
;                            float* ssq_out, float* out32, char* lds) {
;     ...
;       for (int ni = 0; ni < 4; ++ni) {
;         const int n = n0 + wn * 64 + ni * 16 + fq * 4;
;         float4 r;
;         if (resid32) r = *(const float4*)(resid32 + (long)m * 1024 + n);
;         else { const uint2 u = *(const uint2*)(xs + (long)m * LDX + n); r = make_float4(lo2f(u.x), hi2f(u.x), lo2f(u.y), hi2f(u.y)); }
;         float4 o;
;         o.x = r.x + acc[ni][mi][0]; o.y = r.y + acc[ni][mi][1]; o.z = r.z + acc[ni][mi][2]; o.w = r.w + acc[ni][mi][3];
;         if (out32) *(float4*)(out32 + (long)m * 1024 + n) = o;
;         else {
;           uint2 ob; ob.x = pack2(o.x, o.y); ob.y = pack2(o.z, o.w);
;           *(uint2*)(xs + (long)m * LDX + n) = ob;
.LBB0_370:
	s_waitcnt vmcnt(0)
	v_pk_add_f32 v[22:23], v[22:23], v[26:27]
	v_pk_add_f32 v[24:25], v[24:25], v[28:29]
	v_cvt_pk_bf16_f32 v26, v22, v23
	v_cvt_pk_bf16_f32 v27, v24, v25
	s_and_b64 vcc, exec, s[40:41]
	v_mov_b32_e32 v200, v26
	v_mov_b32_e32 v201, v27
	s_cbranch_vccnz .LBB0_379
	global_load_dwordx4 v[22:25], v[40:41], off offset:192
	s_cbranch_execnz .LBB0_373

; DEVI float lo2f(unsigned u) { return __uint_as_float(u << 16); }
; DEVI float hi2f(unsigned u) { return __uint_as_float(u & 0xffff0000u); }
; DEVI void phase_resid_gemm(const Params& p, const bfu* A, int lda, int nkt, const bfu* wT, int ldb, const float* resid32,
;                            float* ssq_out, float* out32, char* lds) {
;     ...
; #pragma unroll
;       for (int ni = 0; ni < 4; ++ni) {
;         const int n = n0 + wn * 64 + ni * 16 + fq * 4;
;         float4 r;
;         if (resid32) r = *(const float4*)(resid32 + (long)m * 1024 + n);
;         else { const uint2 u = *(const uint2*)(xs + (long)m * LDX + n); r = make_float4(lo2f(u.x), hi2f(u.x), lo2f(u.y), hi2f(u.y)); }
;         float4 o;
;         o.x = r.x + acc[ni][mi][0]; o.y = r.y + acc[ni][mi][1]; o.z = r.z + acc[ni][mi][2]; o.w = r.w + acc[ni][mi][3];
;         if (out32) *(float4*)(out32 + (long)m * 1024 + n) = o;
;         else {
;           uint2 ob; ob.x = pack2(o.x, o.y); ob.y = pack2(o.z, o.w);
;           *(uint2*)(xs + (long)m * LDX + n) = ob;
;           const float q0 = lo2f(ob.x), q1 = hi2f(ob.x), q2 = lo2f(ob.y), q3 = hi2f(ob.y);
;           ss += q0 * q0 + q1 * q1 + q2 * q2 + q3 * q3;
;         }
;       }
;       if (!out32) {
;         ss += __shfl_xor(ss, 16);
;         ss += __shfl_xor(ss, 32);
;         if (fq == 0) part[(wm * 128 + mi * 16 + fr) * 4 + wn] = ss;
;       }
.LBB0_373:
	v_and_b32_e32 v29, 0xffff0000, v34
	v_lshlrev_b32_e32 v28, 16, v34
	v_mul_f32_e32 v29, v29, v29
	v_fmac_f32_e32 v29, v28, v28
	v_lshlrev_b32_e32 v28, 16, v30
	v_and_b32_e32 v30, 0xffff0000, v30
	v_lshlrev_b32_e32 v32, 16, v35
	v_mul_f32_e32 v30, v30, v30
	v_fmac_f32_e32 v29, v32, v32
	v_lshlrev_b32_e32 v32, 16, v31
	v_fmac_f32_e32 v30, v28, v28
	v_and_b32_e32 v33, 0xffff0000, v35
	v_and_b32_e32 v31, 0xffff0000, v31
	v_fmac_f32_e32 v30, v32, v32
	v_fmac_f32_e32 v29, v33, v33
	v_fmac_f32_e32 v30, v31, v31
	s_waitcnt vmcnt(0)
	v_pk_add_f32 v[14:15], v[14:15], v[22:23]
	v_add_f32_e32 v28, v29, v30
	v_lshlrev_b32_e32 v29, 16, v26
	v_and_b32_e32 v26, 0xffff0000, v26
	v_cvt_pk_bf16_f32 v22, v14, v15
	v_mul_f32_e32 v26, v26, v26
	v_pk_add_f32 v[16:17], v[16:17], v[24:25]
	v_and_b32_e32 v15, 0xffff0000, v22
	v_lshlrev_b32_e32 v30, 16, v27
	v_fmac_f32_e32 v26, v29, v29
	v_cvt_pk_bf16_f32 v23, v16, v17
	v_lshlrev_b32_e32 v14, 16, v22
	v_mul_f32_e32 v15, v15, v15
	v_and_b32_e32 v27, 0xffff0000, v27
	v_fmac_f32_e32 v26, v30, v30
	v_lshlrev_b32_e32 v16, 16, v23
	v_fmac_f32_e32 v15, v14, v14
	v_fmac_f32_e32 v26, v27, v27
	v_and_b32_e32 v17, 0xffff0000, v23
	v_fmac_f32_e32 v15, v16, v16
	v_add_f32_e32 v26, v28, v26
	v_fmac_f32_e32 v15, v17, v17
	v_add_f32_e32 v14, v26, v15
	ds_bpermute_b32 v15, v0, v14
	v_mov_b32_e32 v210, v22
	v_mov_b32_e32 v211, v23
	v_mov_b32_e32 v208, v200
	v_mov_b32_e32 v209, v201
	v_lshl_add_u64 v[212:213], v[38:39], 0, v[254:255]
	s_nop 0
	v_permlane16_swap_b32_e32 v208, v210
	v_permlane16_swap_b32_e32 v209, v211
	s_nop 1
	global_store_dwordx4 v[212:213], v[208:211], off offset:64
	s_waitcnt lgkmcnt(0)
	v_add_f32_e32 v14, v14, v15
	ds_bpermute_b32 v15, v122, v14
	s_and_saveexec_b64 s[36:37], s[38:39]
	s_cbranch_execz .LBB0_375
	s_waitcnt lgkmcnt(0)
	v_add_f32_e32 v14, v14, v15
	ds_write_b32 v183, v14 offset:1536

; DEVI float lo2f(unsigned u) { return __uint_as_float(u << 16); }
; DEVI float hi2f(unsigned u) { return __uint_as_float(u & 0xffff0000u); }
; DEVI void phase_resid_gemm(const Params& p, const bfu* A, int lda, int nkt, const bfu* wT, int ldb, const float* resid32,
;                            float* ssq_out, float* out32, char* lds) {
;     ...
;       for (int ni = 0; ni < 4; ++ni) {
;         const int n = n0 + wn * 64 + ni * 16 + fq * 4;
;         float4 r;
;         if (resid32) r = *(const float4*)(resid32 + (long)m * 1024 + n);
;         else { const uint2 u = *(const uint2*)(xs + (long)m * LDX + n); r = make_float4(lo2f(u.x), hi2f(u.x), lo2f(u.y), hi2f(u.y)); }
;         float4 o;
;         o.x = r.x + acc[ni][mi][0]; o.y = r.y + acc[ni][mi][1]; o.z = r.z + acc[ni][mi][2]; o.w = r.w + acc[ni][mi][3];
;         if (out32) *(float4*)(out32 + (long)m * 1024 + n) = o;
;         else {
;           uint2 ob; ob.x = pack2(o.x, o.y); ob.y = pack2(o.z, o.w);
;           *(uint2*)(xs + (long)m * LDX + n) = ob;
.LBB0_383:
	s_waitcnt vmcnt(0)
	v_pk_add_f32 v[14:15], v[18:19], v[14:15]
	v_pk_add_f32 v[16:17], v[20:21], v[16:17]
	v_cvt_pk_bf16_f32 v18, v14, v15
	v_cvt_pk_bf16_f32 v19, v16, v17
	s_and_b64 vcc, exec, s[40:41]
	v_mov_b32_e32 v200, v18
	v_mov_b32_e32 v201, v19
	s_cbranch_vccnz .LBB0_396
	global_load_dwordx4 v[14:17], v[24:25], off offset:64
	s_cbranch_execnz .LBB0_386

; DEVI float lo2f(unsigned u) { return __uint_as_float(u << 16); }
; DEVI float hi2f(unsigned u) { return __uint_as_float(u & 0xffff0000u); }
; DEVI void phase_resid_gemm(const Params& p, const bfu* A, int lda, int nkt, const bfu* wT, int ldb, const float* resid32,
;                            float* ssq_out, float* out32, char* lds) {
;     ...
;       for (int ni = 0; ni < 4; ++ni) {
;         const int n = n0 + wn * 64 + ni * 16 + fq * 4;
;         float4 r;
;         if (resid32) r = *(const float4*)(resid32 + (long)m * 1024 + n);
;         else { const uint2 u = *(const uint2*)(xs + (long)m * LDX + n); r = make_float4(lo2f(u.x), hi2f(u.x), lo2f(u.y), hi2f(u.y)); }
;         float4 o;
;         o.x = r.x + acc[ni][mi][0]; o.y = r.y + acc[ni][mi][1]; o.z = r.z + acc[ni][mi][2]; o.w = r.w + acc[ni][mi][3];
;         if (out32) *(float4*)(out32 + (long)m * 1024 + n) = o;
;         else {
;           uint2 ob; ob.x = pack2(o.x, o.y); ob.y = pack2(o.z, o.w);
;           *(uint2*)(xs + (long)m * LDX + n) = ob;
.LBB0_386:
	s_waitcnt vmcnt(0)
	v_pk_add_f32 v[10:11], v[10:11], v[14:15]
	v_pk_add_f32 v[12:13], v[12:13], v[16:17]
	v_cvt_pk_bf16_f32 v14, v10, v11
	v_cvt_pk_bf16_f32 v15, v12, v13
	s_and_b64 vcc, exec, s[40:41]
	v_mov_b32_e32 v206, v14
	v_mov_b32_e32 v207, v15
	v_mov_b32_e32 v204, v200
	v_mov_b32_e32 v205, v201
	v_lshl_add_u64 v[212:213], v[22:23], 0, v[254:255]
	s_nop 0
	v_permlane16_swap_b32_e32 v204, v206
	v_permlane16_swap_b32_e32 v205, v207
	s_nop 1
	global_store_dwordx4 v[212:213], v[204:207], off
	s_cbranch_vccnz .LBB0_397
	global_load_dwordx4 v[10:13], v[24:25], off offset:128
	s_cbranch_execnz .LBB0_389

; DEVI float lo2f(unsigned u) { return __uint_as_float(u << 16); }
; DEVI float hi2f(unsigned u) { return __uint_as_float(u & 0xffff0000u); }
; DEVI void phase_resid_gemm(const Params& p, const bfu* A, int lda, int nkt, const bfu* wT, int ldb, const float* resid32,
;                            float* ssq_out, float* out32, char* lds) {
;     ...
;       for (int ni = 0; ni < 4; ++ni) {
;         const int n = n0 + wn * 64 + ni * 16 + fq * 4;
;         float4 r;
;         if (resid32) r = *(const float4*)(resid32 + (long)m * 1024 + n);
;         else { const uint2 u = *(const uint2*)(xs + (long)m * LDX + n); r = make_float4(lo2f(u.x), hi2f(u.x), lo2f(u.y), hi2f(u.y)); }
;         float4 o;
;         o.x = r.x + acc[ni][mi][0]; o.y = r.y + acc[ni][mi][1]; o.z = r.z + acc[ni][mi][2]; o.w = r.w + acc[ni][mi][3];
;         if (out32) *(float4*)(out32 + (long)m * 1024 + n) = o;
;         else {
;           uint2 ob; ob.x = pack2(o.x, o.y); ob.y = pack2(o.z, o.w);
;           *(uint2*)(xs + (long)m * LDX + n) = ob;
.LBB0_389:
	s_waitcnt vmcnt(0)
	v_pk_add_f32 v[6:7], v[6:7], v[10:11]
	v_pk_add_f32 v[8:9], v[8:9], v[12:13]
	v_cvt_pk_bf16_f32 v10, v6, v7
	v_cvt_pk_bf16_f32 v11, v8, v9
	s_and_b64 vcc, exec, s[40:41]
	v_mov_b32_e32 v200, v10
	v_mov_b32_e32 v201, v11
	s_cbranch_vccnz .LBB0_398
	global_load_dwordx4 v[6:9], v[24:25], off offset:192
	s_cbranch_execnz .LBB0_392

; DEVI float lo2f(unsigned u) { return __uint_as_float(u << 16); }
; DEVI float hi2f(unsigned u) { return __uint_as_float(u & 0xffff0000u); }
; DEVI void phase_resid_gemm(const Params& p, const bfu* A, int lda, int nkt, const bfu* wT, int ldb, const float* resid32,
;                            float* ssq_out, float* out32, char* lds) {
;     ...
; #pragma unroll
;       for (int ni = 0; ni < 4; ++ni) {
;         const int n = n0 + wn * 64 + ni * 16 + fq * 4;
;         float4 r;
;         if (resid32) r = *(const float4*)(resid32 + (long)m * 1024 + n);
;         else { const uint2 u = *(const uint2*)(xs + (long)m * LDX + n); r = make_float4(lo2f(u.x), hi2f(u.x), lo2f(u.y), hi2f(u.y)); }
;         float4 o;
;         o.x = r.x + acc[ni][mi][0]; o.y = r.y + acc[ni][mi][1]; o.z = r.z + acc[ni][mi][2]; o.w = r.w + acc[ni][mi][3];
;         if (out32) *(float4*)(out32 + (long)m * 1024 + n) = o;
;         else {
;           uint2 ob; ob.x = pack2(o.x, o.y); ob.y = pack2(o.z, o.w);
;           *(uint2*)(xs + (long)m * LDX + n) = ob;
;           const float q0 = lo2f(ob.x), q1 = hi2f(ob.x), q2 = lo2f(ob.y), q3 = hi2f(ob.y);
;           ss += q0 * q0 + q1 * q1 + q2 * q2 + q3 * q3;
;         }
;       }
;       if (!out32) {
;         ss += __shfl_xor(ss, 16);
;         ss += __shfl_xor(ss, 32);
;         if (fq == 0) part[(wm * 128 + mi * 16 + fr) * 4 + wn] = ss;
;       }
.LBB0_392:
	v_and_b32_e32 v13, 0xffff0000, v18
	v_lshlrev_b32_e32 v12, 16, v18
	v_mul_f32_e32 v13, v13, v13
	v_fmac_f32_e32 v13, v12, v12
	v_lshlrev_b32_e32 v12, 16, v14
	v_and_b32_e32 v14, 0xffff0000, v14
	v_lshlrev_b32_e32 v16, 16, v19
	v_mul_f32_e32 v14, v14, v14
	v_fmac_f32_e32 v13, v16, v16
	v_lshlrev_b32_e32 v16, 16, v15
	v_fmac_f32_e32 v14, v12, v12
	v_and_b32_e32 v17, 0xffff0000, v19
	v_and_b32_e32 v15, 0xffff0000, v15
	v_fmac_f32_e32 v14, v16, v16
	v_fmac_f32_e32 v13, v17, v17
	v_fmac_f32_e32 v14, v15, v15
	s_waitcnt vmcnt(0)
	v_pk_add_f32 v[2:3], v[2:3], v[6:7]
	v_add_f32_e32 v12, v13, v14
	v_lshlrev_b32_e32 v13, 16, v10
	v_and_b32_e32 v10, 0xffff0000, v10
	v_cvt_pk_bf16_f32 v6, v2, v3
	v_mul_f32_e32 v10, v10, v10
	v_pk_add_f32 v[4:5], v[4:5], v[8:9]
	v_and_b32_e32 v3, 0xffff0000, v6
	v_lshlrev_b32_e32 v14, 16, v11
	v_fmac_f32_e32 v10, v13, v13
	v_cvt_pk_bf16_f32 v7, v4, v5
	v_lshlrev_b32_e32 v2, 16, v6
	v_mul_f32_e32 v3, v3, v3
	v_and_b32_e32 v11, 0xffff0000, v11
	v_fmac_f32_e32 v10, v14, v14
	v_lshlrev_b32_e32 v4, 16, v7
	v_fmac_f32_e32 v3, v2, v2
	v_fmac_f32_e32 v10, v11, v11
	v_and_b32_e32 v5, 0xffff0000, v7
	v_fmac_f32_e32 v3, v4, v4
	v_add_f32_e32 v10, v12, v10
	v_fmac_f32_e32 v3, v5, v5
	v_add_f32_e32 v2, v10, v3
	ds_bpermute_b32 v0, v0, v2
	v_mov_b32_e32 v210, v6
	v_mov_b32_e32 v211, v7
	v_mov_b32_e32 v208, v200
	v_mov_b32_e32 v209, v201
	v_lshl_add_u64 v[212:213], v[22:23], 0, v[254:255]
	s_nop 0
	v_permlane16_swap_b32_e32 v208, v210
	v_permlane16_swap_b32_e32 v209, v211
	s_nop 1
	global_store_dwordx4 v[212:213], v[208:211], off offset:64
	s_waitcnt lgkmcnt(0)
	v_add_f32_e32 v0, v2, v0
	ds_bpermute_b32 v2, v122, v0
	s_and_saveexec_b64 s[36:37], s[38:39]
	s_cbranch_execz .LBB0_394
	s_waitcnt lgkmcnt(0)
	v_add_f32_e32 v0, v0, v2
	ds_write_b32 v183, v0 offset:1792

; DEVI void phase2(const Params& p, int l, char* lds) {
;     ...
; #pragma unroll
;     for (int ni = 0; ni < 4; ++ni)
; #pragma unroll
;       for (int mi = 0; mi < 8; ++mi) {
;         f32x4 v = acc[ni][mi];
;         if (do_gelu) { v[0] = gelu_f(v[0]); v[1] = gelu_f(v[1]); v[2] = gelu_f(v[2]); v[3] = gelu_f(v[3]); }
;         int n = n0 + wn * 64 + ni * 16 + fq * 4;
;         int m = m0 + wm * 128 + mi * 16 + fr;
;         store_bf4(proj + (long)m * LDP + n, v);
;       }
.LBB0_675:
	v_cvt_pk_bf16_f32 v4, v8, v9
	v_cvt_pk_bf16_f32 v5, v6, v7
	s_and_b64 vcc, exec, s[42:43]
	s_mov_b32 s20, s47
	s_mov_b32 s23, s49
	s_mov_b32 s52, s48
	v_mov_b32_e32 v214, v4
	v_mov_b32_e32 v215, v5
	v_mov_b32_e32 v212, v210
	v_mov_b32_e32 v213, v211
	v_lshl_add_u64 v[234:235], v[2:3], 0, v[254:255]
	s_nop 0
	v_permlane16_swap_b32_e32 v212, v214
	v_permlane16_swap_b32_e32 v213, v215
	s_nop 1
	global_store_dwordx4 v[234:235], v[212:215], off offset:64
	s_cbranch_vccnz .LBB0_775

; DEVI void phase2(const Params& p, int l, char* lds) {
;     ...
; #pragma unroll
;     for (int mi = 0; mi < 8; ++mi) {
;       const float rs = rsS[wm * 128 + mi * 16 + fr];
; #pragma unroll
;       for (int ni = 0; ni < 4; ++ni) acc[ni][mi] *= rs;
;     }
;     const bool do_gelu = (n0 < 512);
;     const int kind = (nt_cur == 2) ? 1 : ((nt_cur == 4 && wn < 2) ? 2 : ((nt_cur == 5 && wn < 2) ? 3 : 0));
;     if (kind) {
;       const float* gain = (kind == 1) ? (p.in[7] + l * 64) : (p.in[8] + (l * 3 + (kind == 2 ? 1 : 2)) * 64);
;       const float mul = (kind == 1) ? 0.125f * 1.4426950408889634f : 1.f;
.LBB0_689:
	v_bfe_u32 v254, v225, 4, 1
	v_mov_b32_e32 v255, 0
	v_mul_u32_u24_e32 v254, 24, v254
	v_lshlrev_b32_e32 v114, 2, v179
	v_add3_u32 v138, s25, v181, v114
	ds_read2_b32 v[116:117], v138 offset1:16
	s_cmp_lg_u32 s52, 2
	s_cselect_b64 vcc, -1, 0
	s_cmp_eq_u32 s52, 4
	s_cselect_b64 s[0:1], -1, 0
	s_waitcnt lgkmcnt(0)
	v_pk_mul_f32 v[134:135], v[164:165], v[116:117] op_sel_hi:[1,0]
	v_pk_mul_f32 v[136:137], v[162:163], v[116:117] op_sel_hi:[1,0]
	v_pk_mul_f32 v[104:105], v[104:105], v[116:117] op_sel_hi:[1,0]
	v_pk_mul_f32 v[114:115], v[102:103], v[116:117] op_sel_hi:[1,0]
	v_pk_mul_f32 v[76:77], v[76:77], v[116:117] op_sel_hi:[1,0]
	v_pk_mul_f32 v[74:75], v[74:75], v[116:117] op_sel_hi:[1,0]
	v_pk_mul_f32 v[44:45], v[44:45], v[116:117] op_sel_hi:[1,0]
	v_pk_mul_f32 v[42:43], v[42:43], v[116:117] op_sel_hi:[1,0]
	v_mov_b32_e32 v102, v117
	ds_read2_b32 v[116:117], v138 offset0:32 offset1:48
	v_pk_mul_f32 v[126:127], v[160:161], v[102:103] op_sel_hi:[1,0]
	v_pk_mul_f32 v[128:129], v[158:159], v[102:103] op_sel_hi:[1,0]
	v_pk_mul_f32 v[100:101], v[100:101], v[102:103] op_sel_hi:[1,0]
	v_pk_mul_f32 v[98:99], v[98:99], v[102:103] op_sel_hi:[1,0]
	v_pk_mul_f32 v[72:73], v[72:73], v[102:103] op_sel_hi:[1,0]
	v_pk_mul_f32 v[70:71], v[70:71], v[102:103] op_sel_hi:[1,0]
	v_pk_mul_f32 v[40:41], v[40:41], v[102:103] op_sel_hi:[1,0]
	v_pk_mul_f32 v[38:39], v[38:39], v[102:103] op_sel_hi:[1,0]
	s_waitcnt lgkmcnt(0)
	v_pk_mul_f32 v[102:103], v[94:95], v[116:117] op_sel_hi:[1,0]
	v_mov_b32_e32 v94, v117
	v_pk_mul_f32 v[120:121], v[130:131], v[94:95] op_sel_hi:[1,0]
	ds_read2_b32 v[130:131], v138 offset0:64 offset1:80
	v_pk_mul_f32 v[122:123], v[152:153], v[116:117] op_sel_hi:[1,0]
	v_pk_mul_f32 v[124:125], v[150:151], v[116:117] op_sel_hi:[1,0]
	v_pk_mul_f32 v[96:97], v[96:97], v[116:117] op_sel_hi:[1,0]
	v_pk_mul_f32 v[68:69], v[68:69], v[116:117] op_sel_hi:[1,0]
	v_pk_mul_f32 v[66:67], v[66:67], v[116:117] op_sel_hi:[1,0]
	v_pk_mul_f32 v[36:37], v[36:37], v[116:117] op_sel_hi:[1,0]
	v_pk_mul_f32 v[34:35], v[34:35], v[116:117] op_sel_hi:[1,0]
	v_pk_mul_f32 v[118:119], v[132:133], v[94:95] op_sel_hi:[1,0]
	v_pk_mul_f32 v[92:93], v[92:93], v[94:95] op_sel_hi:[1,0]
	v_pk_mul_f32 v[90:91], v[90:91], v[94:95] op_sel_hi:[1,0]
	v_pk_mul_f32 v[64:65], v[64:65], v[94:95] op_sel_hi:[1,0]
	v_pk_mul_f32 v[62:63], v[62:63], v[94:95] op_sel_hi:[1,0]
	v_pk_mul_f32 v[32:33], v[32:33], v[94:95] op_sel_hi:[1,0]
	v_pk_mul_f32 v[30:31], v[30:31], v[94:95] op_sel_hi:[1,0]
	s_waitcnt lgkmcnt(0)
	v_pk_mul_f32 v[112:113], v[112:113], v[130:131] op_sel_hi:[1,0]
	v_pk_mul_f32 v[116:117], v[110:111], v[130:131] op_sel_hi:[1,0]
	v_pk_mul_f32 v[88:89], v[88:89], v[130:131] op_sel_hi:[1,0]
	v_pk_mul_f32 v[94:95], v[86:87], v[130:131] op_sel_hi:[1,0]
	v_pk_mul_f32 v[56:57], v[56:57], v[130:131] op_sel_hi:[1,0]
	v_pk_mul_f32 v[54:55], v[54:55], v[130:131] op_sel_hi:[1,0]
	v_pk_mul_f32 v[28:29], v[28:29], v[130:131] op_sel_hi:[1,0]
	v_pk_mul_f32 v[26:27], v[26:27], v[130:131] op_sel_hi:[1,0]
	v_mov_b32_e32 v130, v131
	v_pk_mul_f32 v[108:109], v[108:109], v[130:131] op_sel_hi:[1,0]
	v_pk_mul_f32 v[110:111], v[106:107], v[130:131] op_sel_hi:[1,0]
	v_pk_mul_f32 v[80:81], v[80:81], v[130:131] op_sel_hi:[1,0]
	v_pk_mul_f32 v[86:87], v[78:79], v[130:131] op_sel_hi:[1,0]
	v_pk_mul_f32 v[52:53], v[52:53], v[130:131] op_sel_hi:[1,0]
	v_pk_mul_f32 v[50:51], v[50:51], v[130:131] op_sel_hi:[1,0]
	v_pk_mul_f32 v[20:21], v[20:21], v[130:131] op_sel_hi:[1,0]
	v_pk_mul_f32 v[18:19], v[18:19], v[130:131] op_sel_hi:[1,0]
	ds_read2_b32 v[130:131], v138 offset0:96 offset1:112
	s_and_b64 s[36:37], s[0:1], s[38:39]
	s_cmp_eq_u32 s52, 5
	s_cselect_b64 s[0:1], -1, 0
	s_and_b64 s[0:1], s[0:1], s[38:39]
	s_waitcnt lgkmcnt(0)
	v_pk_mul_f32 v[84:85], v[84:85], v[130:131] op_sel_hi:[1,0]
	v_pk_mul_f32 v[106:107], v[82:83], v[130:131] op_sel_hi:[1,0]
	v_pk_mul_f32 v[78:79], v[48:49], v[130:131] op_sel_hi:[1,0]
	v_pk_mul_f32 v[82:83], v[46:47], v[130:131] op_sel_hi:[1,0]
	v_pk_mul_f32 v[24:25], v[24:25], v[130:131] op_sel_hi:[1,0]
	v_pk_mul_f32 v[22:23], v[22:23], v[130:131] op_sel_hi:[1,0]
	v_pk_mul_f32 v[12:13], v[12:13], v[130:131] op_sel_hi:[1,0]
	v_pk_mul_f32 v[10:11], v[10:11], v[130:131] op_sel_hi:[1,0]
	v_mov_b32_e32 v130, v131
	v_pk_mul_f32 v[48:49], v[14:15], v[130:131] op_sel_hi:[1,0]
	v_pk_mul_f32 v[14:15], v[8:9], v[130:131] op_sel_hi:[1,0]
	v_pk_mul_f32 v[8:9], v[2:3], v[130:131] op_sel_hi:[1,0]
	v_cndmask_b32_e64 v2, 0, 3, s[0:1]
	v_cndmask_b32_e64 v2, v2, 2, s[36:37]
	v_cndmask_b32_e32 v2, 1, v2, vcc
	v_pk_mul_f32 v[60:61], v[60:61], v[130:131] op_sel_hi:[1,0]
	v_pk_mul_f32 v[58:59], v[58:59], v[130:131] op_sel_hi:[1,0]
	v_pk_mul_f32 v[46:47], v[16:17], v[130:131] op_sel_hi:[1,0]
	v_pk_mul_f32 v[16:17], v[6:7], v[130:131] op_sel_hi:[1,0]
	v_pk_mul_f32 v[6:7], v[4:5], v[130:131] op_sel_hi:[1,0]
	v_cmp_lt_i32_e64 s[0:1], 0, v2
	s_and_saveexec_b64 s[40:41], s[0:1]
	s_cbranch_execz .LBB0_693
	v_cmp_ne_u32_e64 s[0:1], 1, v2
	v_mov_b32_e32 v131, 0x3e38aa3b
	v_mov_b64_e32 v[2:3], s[4:5]
	s_and_saveexec_b64 s[44:45], s[0:1]
	s_cbranch_execz .LBB0_692
	s_and_b64 s[0:1], vcc, s[36:37]
	v_cndmask_b32_e64 v2, 2, 1, s[0:1]
	v_readlane_b32 s0, v242, 43
	s_mul_i32 s0, s0, 3
	v_readlane_b32 s56, v244, 19
	v_add_lshl_u32 v2, v2, s0, 6
	v_ashrrev_i32_e32 v3, 31, v2
	v_readlane_b32 s57, v244, 20
	v_mov_b32_e32 v131, 1.0
	v_readlane_b32 s1, v242, 44
	v_lshl_add_u64 v[2:3], v[2:3], 2, s[56:57]
	v_readlane_b32 s58, v244, 21
	v_readlane_b32 s59, v244, 22
	v_readlane_b32 s60, v244, 23
	v_readlane_b32 s61, v244, 24
	v_readlane_b32 s62, v244, 25
	v_readlane_b32 s63, v244, 26
	v_readlane_b32 s64, v244, 27
	v_readlane_b32 s65, v244, 28
	v_readlane_b32 s66, v244, 29
	v_readlane_b32 s67, v244, 30
	v_readlane_b32 s68, v244, 31
	v_readlane_b32 s69, v244, 32
	v_readlane_b32 s70, v244, 33
	v_readlane_b32 s71, v244, 34

; DEVI float gelu_f(float x) {
;   float u = 0.7978845608028654f * (x + 0.044715f * x * x * x);
;   return x * __builtin_amdgcn_rcpf(1.f + __expf(-2.f * u));
; }
; DEVI void phase2(const Params& p, int l, char* lds) {
;     ...
; #pragma unroll
;     for (int ni = 0; ni < 4; ++ni)
; #pragma unroll
;       for (int mi = 0; mi < 8; ++mi) {
;         f32x4 v = acc[ni][mi];
;         if (do_gelu) { v[0] = gelu_f(v[0]); v[1] = gelu_f(v[1]); v[2] = gelu_f(v[2]); v[3] = gelu_f(v[3]); }
;         int n = n0 + wn * 64 + ni * 16 + fq * 4;
;         int m = m0 + wm * 128 + mi * 16 + fr;
;         store_bf4(proj + (long)m * LDP + n, v);
;       }
.LBB0_695:
	v_or_b32_e32 v2, s53, v183
	v_ashrrev_i32_e32 v3, 31, v2
	v_add_u32_e32 v138, s51, v186
	v_lshl_add_u64 v[2:3], v[2:3], 1, s[6:7]
	v_cndmask_b32_e64 v130, 0, 1, s[36:37]
	v_mad_i64_i32 v[132:133], s[28:29], v138, s72, v[2:3]
	v_cvt_pk_bf16_f32 v4, v136, v137
	v_cvt_pk_bf16_f32 v5, v134, v135
	v_cmp_ne_u32_e64 s[40:41], 1, v130
	s_andn2_b64 vcc, exec, s[36:37]
	v_mov_b32_e32 v196, v4
	v_mov_b32_e32 v197, v5
	s_cbranch_vccnz .LBB0_697
	v_mul_f32_e32 v4, 0x3d372713, v128
	v_mul_f32_e32 v5, 0x3d372713, v129
	v_mul_f32_e32 v130, 0x3d372713, v126
	v_mul_f32_e32 v131, 0x3d372713, v127
	v_mul_f32_e32 v4, v128, v4
	v_mul_f32_e32 v5, v129, v5
	v_mul_f32_e32 v130, v126, v130
	v_mul_f32_e32 v131, v127, v131
	v_fma_f32 v4, v128, v4, v128
	v_fma_f32 v5, v129, v5, v129
	v_fma_f32 v130, v126, v130, v126
	v_fma_f32 v131, v127, v131, v127
	v_mul_f32_e32 v4, 0x3f4c422a, v4
	v_mul_f32_e32 v5, 0x3f4c422a, v5
	v_mul_f32_e32 v130, 0x3f4c422a, v130
	v_mul_f32_e32 v131, 0x3f4c422a, v131
	v_mul_f32_e32 v4, -2.0, v4
	v_mul_f32_e32 v5, -2.0, v5
	v_mul_f32_e32 v130, -2.0, v130
	v_mul_f32_e32 v131, -2.0, v131
	v_mul_f32_e32 v4, 0x3fb8aa3b, v4
	v_mul_f32_e32 v5, 0x3fb8aa3b, v5
	v_mul_f32_e32 v130, 0x3fb8aa3b, v130
	v_mul_f32_e32 v131, 0x3fb8aa3b, v131
	v_exp_f32_e32 v4, v4
	v_exp_f32_e32 v5, v5
	v_exp_f32_e32 v130, v130
	v_exp_f32_e32 v131, v131
	v_add_f32_e32 v4, 1.0, v4
	v_add_f32_e32 v5, 1.0, v5
	v_add_f32_e32 v130, 1.0, v130
	v_add_f32_e32 v131, 1.0, v131
	v_rcp_f32_e32 v4, v4
	v_rcp_f32_e32 v130, v130
	v_rcp_f32_e32 v131, v131
	v_rcp_f32_e32 v5, v5
	v_pk_mul_f32 v[126:127], v[126:127], v[130:131]
	v_pk_mul_f32 v[128:129], v[128:129], v[4:5]
.LBB0_697:
	v_or_b32_e32 v4, 16, v138
	v_mad_i64_i32 v[130:131], s[28:29], v4, s72, v[2:3]
	v_cvt_pk_bf16_f32 v4, v128, v129
	v_cvt_pk_bf16_f32 v5, v126, v127
	s_and_b64 vcc, exec, s[40:41]
	v_mov_b32_e32 v198, v4
	v_mov_b32_e32 v199, v5
	s_cbranch_vccnz .LBB0_699
	v_mul_f32_e32 v4, 0x3d372713, v124
	v_mul_f32_e32 v5, 0x3d372713, v125
	v_mul_f32_e32 v126, 0x3d372713, v122
	v_mul_f32_e32 v127, 0x3d372713, v123
	v_mul_f32_e32 v4, v124, v4
	v_mul_f32_e32 v5, v125, v5
	v_mul_f32_e32 v126, v122, v126
	v_mul_f32_e32 v127, v123, v127
	v_fma_f32 v4, v124, v4, v124
	v_fma_f32 v5, v125, v5, v125
	v_fma_f32 v126, v122, v126, v122
	v_fma_f32 v127, v123, v127, v123
	v_mul_f32_e32 v4, 0x3f4c422a, v4
	v_mul_f32_e32 v5, 0x3f4c422a, v5
	v_mul_f32_e32 v126, 0x3f4c422a, v126
	v_mul_f32_e32 v127, 0x3f4c422a, v127
	v_mul_f32_e32 v4, -2.0, v4
	v_mul_f32_e32 v5, -2.0, v5
	v_mul_f32_e32 v126, -2.0, v126
	v_mul_f32_e32 v127, -2.0, v127
	v_mul_f32_e32 v4, 0x3fb8aa3b, v4
	v_mul_f32_e32 v5, 0x3fb8aa3b, v5
	v_mul_f32_e32 v126, 0x3fb8aa3b, v126
	v_mul_f32_e32 v127, 0x3fb8aa3b, v127
	v_exp_f32_e32 v4, v4
	v_exp_f32_e32 v5, v5
	v_exp_f32_e32 v126, v126
	v_exp_f32_e32 v127, v127
	v_add_f32_e32 v4, 1.0, v4
	v_add_f32_e32 v5, 1.0, v5
	v_add_f32_e32 v126, 1.0, v126
	v_add_f32_e32 v127, 1.0, v127
	v_rcp_f32_e32 v4, v4
	v_rcp_f32_e32 v126, v126
	v_rcp_f32_e32 v127, v127
	v_rcp_f32_e32 v5, v5
	v_pk_mul_f32 v[122:123], v[122:123], v[126:127]
	v_pk_mul_f32 v[124:125], v[124:125], v[4:5]
.LBB0_699:
	v_or_b32_e32 v4, 32, v138
	v_mad_i64_i32 v[126:127], s[28:29], v4, s72, v[2:3]
	v_cvt_pk_bf16_f32 v4, v124, v125
	v_cvt_pk_bf16_f32 v5, v122, v123
	s_and_b64 vcc, exec, s[40:41]
	v_mov_b32_e32 v200, v4
	v_mov_b32_e32 v201, v5
	s_cbranch_vccnz .LBB0_701
	v_mul_f32_e32 v4, 0x3d372713, v120
	v_mul_f32_e32 v5, 0x3d372713, v121
	v_mul_f32_e32 v122, 0x3d372713, v118
	v_mul_f32_e32 v123, 0x3d372713, v119
	v_mul_f32_e32 v4, v120, v4
	v_mul_f32_e32 v5, v121, v5
	v_mul_f32_e32 v122, v118, v122
	v_mul_f32_e32 v123, v119, v123
	v_fma_f32 v4, v120, v4, v120
	v_fma_f32 v5, v121, v5, v121
	v_fma_f32 v122, v118, v122, v118
	v_fma_f32 v123, v119, v123, v119
	v_mul_f32_e32 v4, 0x3f4c422a, v4
	v_mul_f32_e32 v5, 0x3f4c422a, v5
	v_mul_f32_e32 v122, 0x3f4c422a, v122
	v_mul_f32_e32 v123, 0x3f4c422a, v123
	v_mul_f32_e32 v4, -2.0, v4
	v_mul_f32_e32 v5, -2.0, v5
	v_mul_f32_e32 v122, -2.0, v122
	v_mul_f32_e32 v123, -2.0, v123
	v_mul_f32_e32 v4, 0x3fb8aa3b, v4
	v_mul_f32_e32 v5, 0x3fb8aa3b, v5
	v_mul_f32_e32 v122, 0x3fb8aa3b, v122
	v_mul_f32_e32 v123, 0x3fb8aa3b, v123
	v_exp_f32_e32 v4, v4
	v_exp_f32_e32 v5, v5
	v_exp_f32_e32 v122, v122
	v_exp_f32_e32 v123, v123
	v_add_f32_e32 v4, 1.0, v4
	v_add_f32_e32 v5, 1.0, v5
	v_add_f32_e32 v122, 1.0, v122
	v_add_f32_e32 v123, 1.0, v123
	v_rcp_f32_e32 v4, v4
	v_rcp_f32_e32 v122, v122
	v_rcp_f32_e32 v123, v123
	v_rcp_f32_e32 v5, v5
	v_pk_mul_f32 v[118:119], v[118:119], v[122:123]
	v_pk_mul_f32 v[120:121], v[120:121], v[4:5]
.LBB0_701:
	v_or_b32_e32 v4, 48, v138
	v_mad_i64_i32 v[122:123], s[28:29], v4, s72, v[2:3]
	v_cvt_pk_bf16_f32 v4, v120, v121
	v_cvt_pk_bf16_f32 v5, v118, v119
	s_and_b64 vcc, exec, s[40:41]
	v_mov_b32_e32 v202, v4
	v_mov_b32_e32 v203, v5
	s_cbranch_vccnz .LBB0_703
	v_mul_f32_e32 v4, 0x3d372713, v116
	v_mul_f32_e32 v5, 0x3d372713, v117
	v_mul_f32_e32 v118, 0x3d372713, v112
	v_mul_f32_e32 v119, 0x3d372713, v113
	v_mul_f32_e32 v4, v116, v4
	v_mul_f32_e32 v5, v117, v5
	v_mul_f32_e32 v118, v112, v118
	v_mul_f32_e32 v119, v113, v119
	v_fma_f32 v4, v116, v4, v116
	v_fma_f32 v5, v117, v5, v117
	v_fma_f32 v118, v112, v118, v112
	v_fma_f32 v119, v113, v119, v113
	v_mul_f32_e32 v4, 0x3f4c422a, v4
	v_mul_f32_e32 v5, 0x3f4c422a, v5
	v_mul_f32_e32 v118, 0x3f4c422a, v118
	v_mul_f32_e32 v119, 0x3f4c422a, v119
	v_mul_f32_e32 v4, -2.0, v4
	v_mul_f32_e32 v5, -2.0, v5
	v_mul_f32_e32 v118, -2.0, v118
	v_mul_f32_e32 v119, -2.0, v119
	v_mul_f32_e32 v4, 0x3fb8aa3b, v4
	v_mul_f32_e32 v5, 0x3fb8aa3b, v5
	v_mul_f32_e32 v118, 0x3fb8aa3b, v118
	v_mul_f32_e32 v119, 0x3fb8aa3b, v119
	v_exp_f32_e32 v4, v4
	v_exp_f32_e32 v5, v5
	v_exp_f32_e32 v118, v118
	v_exp_f32_e32 v119, v119
	v_add_f32_e32 v4, 1.0, v4
	v_add_f32_e32 v5, 1.0, v5
	v_add_f32_e32 v118, 1.0, v118
	v_add_f32_e32 v119, 1.0, v119
	v_rcp_f32_e32 v4, v4
	v_rcp_f32_e32 v118, v118
	v_rcp_f32_e32 v119, v119
	v_rcp_f32_e32 v5, v5
	v_pk_mul_f32 v[112:113], v[112:113], v[118:119]
	v_pk_mul_f32 v[116:117], v[116:117], v[4:5]
; DEVI float gelu_f(float x) {
;   float u = 0.7978845608028654f * (x + 0.044715f * x * x * x);
;   return x * __builtin_amdgcn_rcpf(1.f + __expf(-2.f * u));
; }
; DEVI void phase2(const Params& p, int l, char* lds) {
;     ...
; #pragma unroll
;     for (int ni = 0; ni < 4; ++ni)
; #pragma unroll
;       for (int mi = 0; mi < 8; ++mi) {
;         f32x4 v = acc[ni][mi];
;         if (do_gelu) { v[0] = gelu_f(v[0]); v[1] = gelu_f(v[1]); v[2] = gelu_f(v[2]); v[3] = gelu_f(v[3]); }
;         int n = n0 + wn * 64 + ni * 16 + fq * 4;
;         int m = m0 + wm * 128 + mi * 16 + fr;
;         store_bf4(proj + (long)m * LDP + n, v);
;       }
.LBB0_703:
	v_or_b32_e32 v4, 64, v138
	v_mad_i64_i32 v[118:119], s[28:29], v4, s72, v[2:3]
	v_cvt_pk_bf16_f32 v4, v116, v117
	v_cvt_pk_bf16_f32 v5, v112, v113
	s_and_b64 vcc, exec, s[40:41]
	v_mov_b32_e32 v204, v4
	v_mov_b32_e32 v205, v5
	s_cbranch_vccnz .LBB0_705
	v_mul_f32_e32 v4, 0x3d372713, v110
	v_mul_f32_e32 v5, 0x3d372713, v111
	v_mul_f32_e32 v112, 0x3d372713, v108
	v_mul_f32_e32 v113, 0x3d372713, v109
	v_mul_f32_e32 v4, v110, v4
	v_mul_f32_e32 v5, v111, v5
	v_mul_f32_e32 v112, v108, v112
	v_mul_f32_e32 v113, v109, v113
	v_fma_f32 v4, v110, v4, v110
	v_fma_f32 v5, v111, v5, v111
	v_fma_f32 v112, v108, v112, v108
	v_fma_f32 v113, v109, v113, v109
	v_mul_f32_e32 v4, 0x3f4c422a, v4
	v_mul_f32_e32 v5, 0x3f4c422a, v5
	v_mul_f32_e32 v112, 0x3f4c422a, v112
	v_mul_f32_e32 v113, 0x3f4c422a, v113
	v_mul_f32_e32 v4, -2.0, v4
	v_mul_f32_e32 v5, -2.0, v5
	v_mul_f32_e32 v112, -2.0, v112
	v_mul_f32_e32 v113, -2.0, v113
	v_mul_f32_e32 v4, 0x3fb8aa3b, v4
	v_mul_f32_e32 v5, 0x3fb8aa3b, v5
	v_mul_f32_e32 v112, 0x3fb8aa3b, v112
	v_mul_f32_e32 v113, 0x3fb8aa3b, v113
	v_exp_f32_e32 v4, v4
	v_exp_f32_e32 v5, v5
	v_exp_f32_e32 v112, v112
	v_exp_f32_e32 v113, v113
	v_add_f32_e32 v4, 1.0, v4
	v_add_f32_e32 v5, 1.0, v5
	v_add_f32_e32 v112, 1.0, v112
	v_add_f32_e32 v113, 1.0, v113
	v_rcp_f32_e32 v4, v4
	v_rcp_f32_e32 v112, v112
	v_rcp_f32_e32 v113, v113
	v_rcp_f32_e32 v5, v5
	v_pk_mul_f32 v[108:109], v[108:109], v[112:113]
	v_pk_mul_f32 v[110:111], v[110:111], v[4:5]
.LBB0_705:
	v_or_b32_e32 v4, 0x50, v138
	v_mad_i64_i32 v[112:113], s[28:29], v4, s72, v[2:3]
	v_cvt_pk_bf16_f32 v4, v110, v111
	v_cvt_pk_bf16_f32 v5, v108, v109
	s_and_b64 vcc, exec, s[40:41]
	v_mov_b32_e32 v206, v4
	v_mov_b32_e32 v207, v5
	s_cbranch_vccnz .LBB0_707
	v_mul_f32_e32 v4, 0x3d372713, v106
	v_mul_f32_e32 v5, 0x3d372713, v107
	v_mul_f32_e32 v108, 0x3d372713, v84
	v_mul_f32_e32 v109, 0x3d372713, v85
	v_mul_f32_e32 v4, v106, v4
	v_mul_f32_e32 v5, v107, v5
	v_mul_f32_e32 v108, v84, v108
	v_mul_f32_e32 v109, v85, v109
	v_fma_f32 v4, v106, v4, v106
	v_fma_f32 v5, v107, v5, v107
	v_fma_f32 v108, v84, v108, v84
	v_fma_f32 v109, v85, v109, v85
	v_mul_f32_e32 v4, 0x3f4c422a, v4
	v_mul_f32_e32 v5, 0x3f4c422a, v5
	v_mul_f32_e32 v108, 0x3f4c422a, v108
	v_mul_f32_e32 v109, 0x3f4c422a, v109
	v_mul_f32_e32 v4, -2.0, v4
	v_mul_f32_e32 v5, -2.0, v5
	v_mul_f32_e32 v108, -2.0, v108
	v_mul_f32_e32 v109, -2.0, v109
	v_mul_f32_e32 v4, 0x3fb8aa3b, v4
	v_mul_f32_e32 v5, 0x3fb8aa3b, v5
	v_mul_f32_e32 v108, 0x3fb8aa3b, v108
	v_mul_f32_e32 v109, 0x3fb8aa3b, v109
	v_exp_f32_e32 v4, v4
	v_exp_f32_e32 v5, v5
	v_exp_f32_e32 v108, v108
	v_exp_f32_e32 v109, v109
	v_add_f32_e32 v4, 1.0, v4
	v_add_f32_e32 v5, 1.0, v5
	v_add_f32_e32 v108, 1.0, v108
	v_add_f32_e32 v109, 1.0, v109
	v_rcp_f32_e32 v4, v4
	v_rcp_f32_e32 v108, v108
	v_rcp_f32_e32 v109, v109
	v_rcp_f32_e32 v5, v5
	v_pk_mul_f32 v[84:85], v[84:85], v[108:109]
	v_pk_mul_f32 v[106:107], v[106:107], v[4:5]
.LBB0_707:
	v_or_b32_e32 v4, 0x60, v138
	v_mad_i64_i32 v[4:5], s[28:29], v4, s72, v[2:3]
	v_cvt_pk_bf16_f32 v106, v106, v107
	v_cvt_pk_bf16_f32 v107, v84, v85
	s_and_b64 vcc, exec, s[40:41]
	v_mov_b32_e32 v208, v106
	v_mov_b32_e32 v209, v107
	s_cbranch_vccnz .LBB0_709
	v_mul_f32_e32 v84, 0x3d372713, v58
	v_mul_f32_e32 v85, 0x3d372713, v59
	v_mul_f32_e32 v106, 0x3d372713, v60
	v_mul_f32_e32 v107, 0x3d372713, v61
	v_mul_f32_e32 v84, v58, v84
	v_mul_f32_e32 v85, v59, v85
	v_mul_f32_e32 v106, v60, v106
	v_mul_f32_e32 v107, v61, v107
	v_fma_f32 v84, v58, v84, v58
	v_fma_f32 v85, v59, v85, v59
	v_fma_f32 v106, v60, v106, v60
	v_fma_f32 v107, v61, v107, v61
	v_mul_f32_e32 v84, 0x3f4c422a, v84
	v_mul_f32_e32 v85, 0x3f4c422a, v85
	v_mul_f32_e32 v106, 0x3f4c422a, v106
	v_mul_f32_e32 v107, 0x3f4c422a, v107
	v_mul_f32_e32 v84, -2.0, v84
	v_mul_f32_e32 v85, -2.0, v85
	v_mul_f32_e32 v106, -2.0, v106
	v_mul_f32_e32 v107, -2.0, v107
	v_mul_f32_e32 v84, 0x3fb8aa3b, v84
	v_mul_f32_e32 v85, 0x3fb8aa3b, v85
	v_mul_f32_e32 v106, 0x3fb8aa3b, v106
	v_mul_f32_e32 v107, 0x3fb8aa3b, v107
	v_exp_f32_e32 v84, v84
	v_exp_f32_e32 v85, v85
	v_exp_f32_e32 v106, v106
	v_exp_f32_e32 v107, v107
	v_add_f32_e32 v84, 1.0, v84
	v_add_f32_e32 v85, 1.0, v85
	v_add_f32_e32 v106, 1.0, v106
	v_add_f32_e32 v107, 1.0, v107
	v_rcp_f32_e32 v84, v84
	v_rcp_f32_e32 v106, v106
	v_rcp_f32_e32 v107, v107
	v_rcp_f32_e32 v85, v85
	v_pk_mul_f32 v[60:61], v[60:61], v[106:107]
	v_pk_mul_f32 v[58:59], v[58:59], v[84:85]
.LBB0_709:
	v_or_b32_e32 v84, 0x70, v138
	v_mad_i64_i32 v[2:3], s[28:29], v84, s72, v[2:3]
	v_cvt_pk_bf16_f32 v58, v58, v59
	v_cvt_pk_bf16_f32 v59, v60, v61
	s_mov_b64 s[36:37], -1
	s_and_b64 vcc, exec, s[0:1]
	v_mov_b32_e32 v210, v58
	v_mov_b32_e32 v211, v59
	s_cbranch_vccz .LBB0_711
	v_cvt_pk_bf16_f32 v58, v114, v115
	v_cvt_pk_bf16_f32 v59, v104, v105
	v_mov_b32_e32 v218, v58
	v_mov_b32_e32 v219, v59
	v_mov_b32_e32 v216, v196
	v_mov_b32_e32 v217, v197
	v_lshl_add_u64 v[234:235], v[132:133], 0, v[254:255]
	s_nop 0
	v_permlane16_swap_b32_e32 v216, v218
	v_permlane16_swap_b32_e32 v217, v219
	s_nop 1
	global_store_dwordx4 v[234:235], v[216:219], off
	s_mov_b64 s[36:37], 0
; DEVI float gelu_f(float x) {
;   float u = 0.7978845608028654f * (x + 0.044715f * x * x * x);
;   return x * __builtin_amdgcn_rcpf(1.f + __expf(-2.f * u));
; }
; DEVI void phase2(const Params& p, int l, char* lds) {
;     ...
; #pragma unroll
;     for (int ni = 0; ni < 4; ++ni)
; #pragma unroll
;       for (int mi = 0; mi < 8; ++mi) {
;         f32x4 v = acc[ni][mi];
;         if (do_gelu) { v[0] = gelu_f(v[0]); v[1] = gelu_f(v[1]); v[2] = gelu_f(v[2]); v[3] = gelu_f(v[3]); }
;         int n = n0 + wn * 64 + ni * 16 + fq * 4;
;         int m = m0 + wm * 128 + mi * 16 + fr;
;         store_bf4(proj + (long)m * LDP + n, v);
;       }
.LBB0_711:
	s_andn2_b64 vcc, exec, s[36:37]
	s_cbranch_vccnz .LBB0_713
	v_mul_f32_e32 v58, 0x3d372713, v114
	v_mul_f32_e32 v59, 0x3d372713, v115
	v_mul_f32_e32 v60, 0x3d372713, v104
	v_mul_f32_e32 v61, 0x3d372713, v105
	v_mul_f32_e32 v58, v114, v58
	v_mul_f32_e32 v59, v115, v59
	v_mul_f32_e32 v60, v104, v60
	v_mul_f32_e32 v61, v105, v61
	v_fma_f32 v58, v114, v58, v114
	v_fma_f32 v59, v115, v59, v115
	v_fma_f32 v60, v104, v60, v104
	v_fma_f32 v61, v105, v61, v105
	v_mul_f32_e32 v58, 0x3f4c422a, v58
	v_mul_f32_e32 v59, 0x3f4c422a, v59
	v_mul_f32_e32 v60, 0x3f4c422a, v60
	v_mul_f32_e32 v61, 0x3f4c422a, v61
	v_mul_f32_e32 v58, -2.0, v58
	v_mul_f32_e32 v59, -2.0, v59
	v_mul_f32_e32 v60, -2.0, v60
	v_mul_f32_e32 v61, -2.0, v61
	v_mul_f32_e32 v58, 0x3fb8aa3b, v58
	v_mul_f32_e32 v59, 0x3fb8aa3b, v59
	v_mul_f32_e32 v60, 0x3fb8aa3b, v60
	v_mul_f32_e32 v61, 0x3fb8aa3b, v61
	v_exp_f32_e32 v58, v58
	v_exp_f32_e32 v59, v59
	v_exp_f32_e32 v60, v60
	v_exp_f32_e32 v61, v61
	v_add_f32_e32 v58, 1.0, v58
	v_add_f32_e32 v59, 1.0, v59
	v_add_f32_e32 v60, 1.0, v60
	v_add_f32_e32 v61, 1.0, v61
	v_rcp_f32_e32 v58, v58
	v_rcp_f32_e32 v59, v59
	v_rcp_f32_e32 v60, v60
	v_rcp_f32_e32 v61, v61
	v_pk_mul_f32 v[58:59], v[114:115], v[58:59]
	s_nop 0
	v_cvt_pk_bf16_f32 v58, v58, v59
	v_pk_mul_f32 v[60:61], v[104:105], v[60:61]
	s_nop 0
	v_cvt_pk_bf16_f32 v59, v60, v61
	v_mov_b32_e32 v214, v58
	v_mov_b32_e32 v215, v59
	v_mov_b32_e32 v212, v196
	v_mov_b32_e32 v213, v197
	v_lshl_add_u64 v[234:235], v[132:133], 0, v[254:255]
	s_nop 0
	v_permlane16_swap_b32_e32 v212, v214
	v_permlane16_swap_b32_e32 v213, v215
	s_nop 1
	global_store_dwordx4 v[234:235], v[212:215], off
	v_mul_f32_e32 v58, 0x3d372713, v98
	v_mul_f32_e32 v59, 0x3d372713, v99
	v_mul_f32_e32 v60, 0x3d372713, v100
	v_mul_f32_e32 v61, 0x3d372713, v101
	v_mul_f32_e32 v58, v98, v58
	v_mul_f32_e32 v59, v99, v59
	v_mul_f32_e32 v60, v100, v60
	v_mul_f32_e32 v61, v101, v61
	v_fma_f32 v58, v98, v58, v98
	v_fma_f32 v59, v99, v59, v99
	v_fma_f32 v60, v100, v60, v100
	v_fma_f32 v61, v101, v61, v101
	v_mul_f32_e32 v58, 0x3f4c422a, v58
	v_mul_f32_e32 v59, 0x3f4c422a, v59
	v_mul_f32_e32 v60, 0x3f4c422a, v60
	v_mul_f32_e32 v61, 0x3f4c422a, v61
	v_mul_f32_e32 v58, -2.0, v58
	v_mul_f32_e32 v59, -2.0, v59
	v_mul_f32_e32 v60, -2.0, v60
	v_mul_f32_e32 v61, -2.0, v61
	v_mul_f32_e32 v58, 0x3fb8aa3b, v58
	v_mul_f32_e32 v59, 0x3fb8aa3b, v59
	v_mul_f32_e32 v60, 0x3fb8aa3b, v60
	v_mul_f32_e32 v61, 0x3fb8aa3b, v61
	v_exp_f32_e32 v58, v58
	v_exp_f32_e32 v59, v59
	v_exp_f32_e32 v60, v60
	v_exp_f32_e32 v61, v61
	v_add_f32_e32 v58, 1.0, v58
	v_add_f32_e32 v59, 1.0, v59
	v_add_f32_e32 v60, 1.0, v60
	v_add_f32_e32 v61, 1.0, v61
	v_rcp_f32_e32 v58, v58
	v_rcp_f32_e32 v59, v59
	v_rcp_f32_e32 v60, v60
	v_rcp_f32_e32 v61, v61
	v_pk_mul_f32 v[98:99], v[98:99], v[58:59]
	v_pk_mul_f32 v[100:101], v[100:101], v[60:61]
.LBB0_713:
	v_cvt_pk_bf16_f32 v58, v98, v99
	v_cvt_pk_bf16_f32 v59, v100, v101
	s_mov_b64 s[36:37], -1
	s_and_b64 vcc, exec, s[0:1]
	v_mov_b32_e32 v218, v58
	v_mov_b32_e32 v219, v59
	v_mov_b32_e32 v216, v198
	v_mov_b32_e32 v217, v199
	v_lshl_add_u64 v[234:235], v[130:131], 0, v[254:255]
	s_nop 0
	v_permlane16_swap_b32_e32 v216, v218
	v_permlane16_swap_b32_e32 v217, v219
	s_nop 1
	global_store_dwordx4 v[234:235], v[216:219], off
	s_cbranch_vccz .LBB0_715
	v_cvt_pk_bf16_f32 v58, v102, v103
	v_cvt_pk_bf16_f32 v59, v96, v97
	v_mov_b32_e32 v214, v58
	v_mov_b32_e32 v215, v59
	v_mov_b32_e32 v212, v200
	v_mov_b32_e32 v213, v201
	v_lshl_add_u64 v[234:235], v[126:127], 0, v[254:255]
	s_nop 0
	v_permlane16_swap_b32_e32 v212, v214
	v_permlane16_swap_b32_e32 v213, v215
	s_nop 1
	global_store_dwordx4 v[234:235], v[212:215], off
	s_mov_b64 s[36:37], 0
.LBB0_715:
	s_andn2_b64 vcc, exec, s[36:37]
	s_cbranch_vccnz .LBB0_717
	v_mul_f32_e32 v58, 0x3d372713, v102
	v_mul_f32_e32 v59, 0x3d372713, v103
	v_mul_f32_e32 v60, 0x3d372713, v96
	v_mul_f32_e32 v61, 0x3d372713, v97
	v_mul_f32_e32 v58, v102, v58
	v_mul_f32_e32 v59, v103, v59
	v_mul_f32_e32 v60, v96, v60
	v_mul_f32_e32 v61, v97, v61
	v_fma_f32 v58, v102, v58, v102
	v_fma_f32 v59, v103, v59, v103
	v_fma_f32 v60, v96, v60, v96
	v_fma_f32 v61, v97, v61, v97
	v_mul_f32_e32 v58, 0x3f4c422a, v58
	v_mul_f32_e32 v59, 0x3f4c422a, v59
	v_mul_f32_e32 v60, 0x3f4c422a, v60
	v_mul_f32_e32 v61, 0x3f4c422a, v61
	v_mul_f32_e32 v58, -2.0, v58
	v_mul_f32_e32 v59, -2.0, v59
	v_mul_f32_e32 v60, -2.0, v60
	v_mul_f32_e32 v61, -2.0, v61
	v_mul_f32_e32 v58, 0x3fb8aa3b, v58
	v_mul_f32_e32 v59, 0x3fb8aa3b, v59
	v_mul_f32_e32 v60, 0x3fb8aa3b, v60
	v_mul_f32_e32 v61, 0x3fb8aa3b, v61
	v_exp_f32_e32 v58, v58
	v_exp_f32_e32 v59, v59
	v_exp_f32_e32 v60, v60
	v_exp_f32_e32 v61, v61
	v_add_f32_e32 v58, 1.0, v58
	v_add_f32_e32 v59, 1.0, v59
	v_add_f32_e32 v60, 1.0, v60
	v_add_f32_e32 v61, 1.0, v61
	v_rcp_f32_e32 v58, v58
	v_rcp_f32_e32 v59, v59
	v_rcp_f32_e32 v60, v60
	v_rcp_f32_e32 v61, v61
	v_pk_mul_f32 v[58:59], v[102:103], v[58:59]
	s_nop 0
	v_cvt_pk_bf16_f32 v58, v58, v59
	v_pk_mul_f32 v[60:61], v[96:97], v[60:61]
	s_nop 0
	v_cvt_pk_bf16_f32 v59, v60, v61
	v_mov_b32_e32 v218, v58
	v_mov_b32_e32 v219, v59
	v_mov_b32_e32 v216, v200
	v_mov_b32_e32 v217, v201
	v_lshl_add_u64 v[234:235], v[126:127], 0, v[254:255]
	s_nop 0
	v_permlane16_swap_b32_e32 v216, v218
	v_permlane16_swap_b32_e32 v217, v219
	s_nop 1
	global_store_dwordx4 v[234:235], v[216:219], off
	v_mul_f32_e32 v58, 0x3d372713, v90
	v_mul_f32_e32 v59, 0x3d372713, v91
	v_mul_f32_e32 v60, 0x3d372713, v92
	v_mul_f32_e32 v61, 0x3d372713, v93
	v_mul_f32_e32 v58, v90, v58
	v_mul_f32_e32 v59, v91, v59
	v_mul_f32_e32 v60, v92, v60
	v_mul_f32_e32 v61, v93, v61
	v_fma_f32 v58, v90, v58, v90
	v_fma_f32 v59, v91, v59, v91
	v_fma_f32 v60, v92, v60, v92
	v_fma_f32 v61, v93, v61, v93
	v_mul_f32_e32 v58, 0x3f4c422a, v58
	v_mul_f32_e32 v59, 0x3f4c422a, v59
	v_mul_f32_e32 v60, 0x3f4c422a, v60
	v_mul_f32_e32 v61, 0x3f4c422a, v61
	v_mul_f32_e32 v58, -2.0, v58
	v_mul_f32_e32 v59, -2.0, v59
	v_mul_f32_e32 v60, -2.0, v60
	v_mul_f32_e32 v61, -2.0, v61
	v_mul_f32_e32 v58, 0x3fb8aa3b, v58
	v_mul_f32_e32 v59, 0x3fb8aa3b, v59
	v_mul_f32_e32 v60, 0x3fb8aa3b, v60
	v_mul_f32_e32 v61, 0x3fb8aa3b, v61
	v_exp_f32_e32 v58, v58
	v_exp_f32_e32 v59, v59
	v_exp_f32_e32 v60, v60
	v_exp_f32_e32 v61, v61
	v_add_f32_e32 v58, 1.0, v58
	v_add_f32_e32 v59, 1.0, v59
	v_add_f32_e32 v60, 1.0, v60
	v_add_f32_e32 v61, 1.0, v61
	v_rcp_f32_e32 v58, v58
	v_rcp_f32_e32 v59, v59
	v_rcp_f32_e32 v60, v60
	v_rcp_f32_e32 v61, v61
	v_pk_mul_f32 v[90:91], v[90:91], v[58:59]
	v_pk_mul_f32 v[92:93], v[92:93], v[60:61]
; DEVI float gelu_f(float x) {
;   float u = 0.7978845608028654f * (x + 0.044715f * x * x * x);
;   return x * __builtin_amdgcn_rcpf(1.f + __expf(-2.f * u));
; }
; DEVI void phase2(const Params& p, int l, char* lds) {
;     ...
; #pragma unroll
;     for (int ni = 0; ni < 4; ++ni)
; #pragma unroll
;       for (int mi = 0; mi < 8; ++mi) {
;         f32x4 v = acc[ni][mi];
;         if (do_gelu) { v[0] = gelu_f(v[0]); v[1] = gelu_f(v[1]); v[2] = gelu_f(v[2]); v[3] = gelu_f(v[3]); }
;         int n = n0 + wn * 64 + ni * 16 + fq * 4;
;         int m = m0 + wm * 128 + mi * 16 + fr;
;         store_bf4(proj + (long)m * LDP + n, v);
;       }
.LBB0_717:
	v_cvt_pk_bf16_f32 v58, v90, v91
	v_cvt_pk_bf16_f32 v59, v92, v93
	s_mov_b64 s[36:37], -1
	s_and_b64 vcc, exec, s[0:1]
	v_mov_b32_e32 v214, v58
	v_mov_b32_e32 v215, v59
	v_mov_b32_e32 v212, v202
	v_mov_b32_e32 v213, v203
	v_lshl_add_u64 v[234:235], v[122:123], 0, v[254:255]
	s_nop 0
	v_permlane16_swap_b32_e32 v212, v214
	v_permlane16_swap_b32_e32 v213, v215
	s_nop 1
	global_store_dwordx4 v[234:235], v[212:215], off
	s_cbranch_vccz .LBB0_719
	v_cvt_pk_bf16_f32 v58, v94, v95
	v_cvt_pk_bf16_f32 v59, v88, v89
	v_mov_b32_e32 v218, v58
	v_mov_b32_e32 v219, v59
	v_mov_b32_e32 v216, v204
	v_mov_b32_e32 v217, v205
	v_lshl_add_u64 v[234:235], v[118:119], 0, v[254:255]
	s_nop 0
	v_permlane16_swap_b32_e32 v216, v218
	v_permlane16_swap_b32_e32 v217, v219
	s_nop 1
	global_store_dwordx4 v[234:235], v[216:219], off
	s_mov_b64 s[36:37], 0
.LBB0_719:
	s_andn2_b64 vcc, exec, s[36:37]
	s_cbranch_vccnz .LBB0_721
	v_mul_f32_e32 v58, 0x3d372713, v94
	v_mul_f32_e32 v59, 0x3d372713, v95
	v_mul_f32_e32 v60, 0x3d372713, v88
	v_mul_f32_e32 v61, 0x3d372713, v89
	v_mul_f32_e32 v58, v94, v58
	v_mul_f32_e32 v59, v95, v59
	v_mul_f32_e32 v60, v88, v60
	v_mul_f32_e32 v61, v89, v61
	v_fma_f32 v58, v94, v58, v94
	v_fma_f32 v59, v95, v59, v95
	v_fma_f32 v60, v88, v60, v88
	v_fma_f32 v61, v89, v61, v89
	v_mul_f32_e32 v58, 0x3f4c422a, v58
	v_mul_f32_e32 v59, 0x3f4c422a, v59
	v_mul_f32_e32 v60, 0x3f4c422a, v60
	v_mul_f32_e32 v61, 0x3f4c422a, v61
	v_mul_f32_e32 v58, -2.0, v58
	v_mul_f32_e32 v59, -2.0, v59
	v_mul_f32_e32 v60, -2.0, v60
	v_mul_f32_e32 v61, -2.0, v61
	v_mul_f32_e32 v58, 0x3fb8aa3b, v58
	v_mul_f32_e32 v59, 0x3fb8aa3b, v59
	v_mul_f32_e32 v60, 0x3fb8aa3b, v60
	v_mul_f32_e32 v61, 0x3fb8aa3b, v61
	v_exp_f32_e32 v58, v58
	v_exp_f32_e32 v59, v59
	v_exp_f32_e32 v60, v60
	v_exp_f32_e32 v61, v61
	v_add_f32_e32 v58, 1.0, v58
	v_add_f32_e32 v59, 1.0, v59
	v_add_f32_e32 v60, 1.0, v60
	v_add_f32_e32 v61, 1.0, v61
	v_rcp_f32_e32 v58, v58
	v_rcp_f32_e32 v59, v59
	v_rcp_f32_e32 v60, v60
	v_rcp_f32_e32 v61, v61
	v_pk_mul_f32 v[58:59], v[94:95], v[58:59]
	s_nop 0
	v_cvt_pk_bf16_f32 v58, v58, v59
	v_pk_mul_f32 v[60:61], v[88:89], v[60:61]
	s_nop 0
	v_cvt_pk_bf16_f32 v59, v60, v61
	v_mov_b32_e32 v214, v58
	v_mov_b32_e32 v215, v59
	v_mov_b32_e32 v212, v204
	v_mov_b32_e32 v213, v205
	v_lshl_add_u64 v[234:235], v[118:119], 0, v[254:255]
	s_nop 0
	v_permlane16_swap_b32_e32 v212, v214
	v_permlane16_swap_b32_e32 v213, v215
	s_nop 1
	global_store_dwordx4 v[234:235], v[212:215], off
	v_mul_f32_e32 v58, 0x3d372713, v86
	v_mul_f32_e32 v59, 0x3d372713, v87
	v_mul_f32_e32 v60, 0x3d372713, v80
	v_mul_f32_e32 v61, 0x3d372713, v81
	v_mul_f32_e32 v58, v86, v58
	v_mul_f32_e32 v59, v87, v59
	v_mul_f32_e32 v60, v80, v60
	v_mul_f32_e32 v61, v81, v61
	v_fma_f32 v58, v86, v58, v86
	v_fma_f32 v59, v87, v59, v87
	v_fma_f32 v60, v80, v60, v80
	v_fma_f32 v61, v81, v61, v81
	v_mul_f32_e32 v58, 0x3f4c422a, v58
	v_mul_f32_e32 v59, 0x3f4c422a, v59
	v_mul_f32_e32 v60, 0x3f4c422a, v60
	v_mul_f32_e32 v61, 0x3f4c422a, v61
	v_mul_f32_e32 v58, -2.0, v58
	v_mul_f32_e32 v59, -2.0, v59
	v_mul_f32_e32 v60, -2.0, v60
	v_mul_f32_e32 v61, -2.0, v61
	v_mul_f32_e32 v58, 0x3fb8aa3b, v58
	v_mul_f32_e32 v59, 0x3fb8aa3b, v59
	v_mul_f32_e32 v60, 0x3fb8aa3b, v60
	v_mul_f32_e32 v61, 0x3fb8aa3b, v61
	v_exp_f32_e32 v58, v58
	v_exp_f32_e32 v59, v59
	v_exp_f32_e32 v60, v60
	v_exp_f32_e32 v61, v61
	v_add_f32_e32 v58, 1.0, v58
	v_add_f32_e32 v59, 1.0, v59
	v_add_f32_e32 v60, 1.0, v60
	v_add_f32_e32 v61, 1.0, v61
	v_rcp_f32_e32 v58, v58
	v_rcp_f32_e32 v59, v59
	v_rcp_f32_e32 v60, v60
	v_rcp_f32_e32 v61, v61
	v_pk_mul_f32 v[86:87], v[86:87], v[58:59]
	v_pk_mul_f32 v[80:81], v[80:81], v[60:61]
.LBB0_721:
	v_cvt_pk_bf16_f32 v58, v86, v87
	v_cvt_pk_bf16_f32 v59, v80, v81
	s_mov_b64 s[36:37], -1
	s_and_b64 vcc, exec, s[0:1]
	v_mov_b32_e32 v218, v58
	v_mov_b32_e32 v219, v59
	v_mov_b32_e32 v216, v206
	v_mov_b32_e32 v217, v207
	v_lshl_add_u64 v[234:235], v[112:113], 0, v[254:255]
	s_nop 0
	v_permlane16_swap_b32_e32 v216, v218
	v_permlane16_swap_b32_e32 v217, v219
	s_nop 1
	global_store_dwordx4 v[234:235], v[216:219], off
	s_cbranch_vccz .LBB0_723
	v_cvt_pk_bf16_f32 v58, v82, v83
	v_cvt_pk_bf16_f32 v59, v78, v79
	v_mov_b32_e32 v214, v58
	v_mov_b32_e32 v215, v59
	v_mov_b32_e32 v212, v208
	v_mov_b32_e32 v213, v209
	v_lshl_add_u64 v[234:235], v[4:5], 0, v[254:255]
	s_nop 0
	v_permlane16_swap_b32_e32 v212, v214
	v_permlane16_swap_b32_e32 v213, v215
	s_nop 1
	global_store_dwordx4 v[234:235], v[212:215], off
	s_mov_b64 s[36:37], 0
; DEVI float gelu_f(float x) {
;   float u = 0.7978845608028654f * (x + 0.044715f * x * x * x);
;   return x * __builtin_amdgcn_rcpf(1.f + __expf(-2.f * u));
; }
; DEVI void phase2(const Params& p, int l, char* lds) {
;     ...
; #pragma unroll
;     for (int ni = 0; ni < 4; ++ni)
; #pragma unroll
;       for (int mi = 0; mi < 8; ++mi) {
;         f32x4 v = acc[ni][mi];
;         if (do_gelu) { v[0] = gelu_f(v[0]); v[1] = gelu_f(v[1]); v[2] = gelu_f(v[2]); v[3] = gelu_f(v[3]); }
;         int n = n0 + wn * 64 + ni * 16 + fq * 4;
;         int m = m0 + wm * 128 + mi * 16 + fr;
;         store_bf4(proj + (long)m * LDP + n, v);
;       }
.LBB0_723:
	s_andn2_b64 vcc, exec, s[36:37]
	s_cbranch_vccnz .LBB0_725
	v_mul_f32_e32 v58, 0x3d372713, v82
	v_mul_f32_e32 v59, 0x3d372713, v83
	v_mul_f32_e32 v60, 0x3d372713, v78
	v_mul_f32_e32 v61, 0x3d372713, v79
	v_mul_f32_e32 v58, v82, v58
	v_mul_f32_e32 v59, v83, v59
	v_mul_f32_e32 v60, v78, v60
	v_mul_f32_e32 v61, v79, v61
	v_fma_f32 v58, v82, v58, v82
	v_fma_f32 v59, v83, v59, v83
	v_fma_f32 v60, v78, v60, v78
	v_fma_f32 v61, v79, v61, v79
	v_mul_f32_e32 v58, 0x3f4c422a, v58
	v_mul_f32_e32 v59, 0x3f4c422a, v59
	v_mul_f32_e32 v60, 0x3f4c422a, v60
	v_mul_f32_e32 v61, 0x3f4c422a, v61
	v_mul_f32_e32 v58, -2.0, v58
	v_mul_f32_e32 v59, -2.0, v59
	v_mul_f32_e32 v60, -2.0, v60
	v_mul_f32_e32 v61, -2.0, v61
	v_mul_f32_e32 v58, 0x3fb8aa3b, v58
	v_mul_f32_e32 v59, 0x3fb8aa3b, v59
	v_mul_f32_e32 v60, 0x3fb8aa3b, v60
	v_mul_f32_e32 v61, 0x3fb8aa3b, v61
	v_exp_f32_e32 v58, v58
	v_exp_f32_e32 v59, v59
	v_exp_f32_e32 v60, v60
	v_exp_f32_e32 v61, v61
	v_add_f32_e32 v58, 1.0, v58
	v_add_f32_e32 v59, 1.0, v59
	v_add_f32_e32 v60, 1.0, v60
	v_add_f32_e32 v61, 1.0, v61
	v_rcp_f32_e32 v58, v58
	v_rcp_f32_e32 v59, v59
	v_rcp_f32_e32 v60, v60
	v_rcp_f32_e32 v61, v61
	v_pk_mul_f32 v[58:59], v[82:83], v[58:59]
	s_nop 0
	v_cvt_pk_bf16_f32 v58, v58, v59
	v_pk_mul_f32 v[60:61], v[78:79], v[60:61]
	s_nop 0
	v_cvt_pk_bf16_f32 v59, v60, v61
	v_mov_b32_e32 v218, v58
	v_mov_b32_e32 v219, v59
	v_mov_b32_e32 v216, v208
	v_mov_b32_e32 v217, v209
	v_lshl_add_u64 v[234:235], v[4:5], 0, v[254:255]
	s_nop 0
	v_permlane16_swap_b32_e32 v216, v218
	v_permlane16_swap_b32_e32 v217, v219
	s_nop 1
	global_store_dwordx4 v[234:235], v[216:219], off
	v_mul_f32_e32 v58, 0x3d372713, v48
	v_mul_f32_e32 v59, 0x3d372713, v49
	v_mul_f32_e32 v60, 0x3d372713, v46
	v_mul_f32_e32 v61, 0x3d372713, v47
	v_mul_f32_e32 v58, v48, v58
	v_mul_f32_e32 v59, v49, v59
	v_mul_f32_e32 v60, v46, v60
	v_mul_f32_e32 v61, v47, v61
	v_fma_f32 v58, v48, v58, v48
	v_fma_f32 v59, v49, v59, v49
	v_fma_f32 v60, v46, v60, v46
	v_fma_f32 v61, v47, v61, v47
	v_mul_f32_e32 v58, 0x3f4c422a, v58
	v_mul_f32_e32 v59, 0x3f4c422a, v59
	v_mul_f32_e32 v60, 0x3f4c422a, v60
	v_mul_f32_e32 v61, 0x3f4c422a, v61
	v_mul_f32_e32 v58, -2.0, v58
	v_mul_f32_e32 v59, -2.0, v59
	v_mul_f32_e32 v60, -2.0, v60
	v_mul_f32_e32 v61, -2.0, v61
	v_mul_f32_e32 v58, 0x3fb8aa3b, v58
	v_mul_f32_e32 v59, 0x3fb8aa3b, v59
	v_mul_f32_e32 v60, 0x3fb8aa3b, v60
	v_mul_f32_e32 v61, 0x3fb8aa3b, v61
	v_exp_f32_e32 v58, v58
	v_exp_f32_e32 v59, v59
	v_exp_f32_e32 v60, v60
	v_exp_f32_e32 v61, v61
	v_add_f32_e32 v58, 1.0, v58
	v_add_f32_e32 v59, 1.0, v59
	v_add_f32_e32 v60, 1.0, v60
	v_add_f32_e32 v61, 1.0, v61
	v_rcp_f32_e32 v58, v58
	v_rcp_f32_e32 v59, v59
	v_rcp_f32_e32 v60, v60
	v_rcp_f32_e32 v61, v61
	v_pk_mul_f32 v[48:49], v[48:49], v[58:59]
	v_pk_mul_f32 v[46:47], v[46:47], v[60:61]
.LBB0_725:
	v_cvt_pk_bf16_f32 v48, v48, v49
	v_cvt_pk_bf16_f32 v49, v46, v47
	s_mov_b64 s[36:37], -1
	s_and_b64 vcc, exec, s[0:1]
	v_mov_b32_e32 v214, v48
	v_mov_b32_e32 v215, v49
	v_mov_b32_e32 v212, v210
	v_mov_b32_e32 v213, v211
	v_lshl_add_u64 v[234:235], v[2:3], 0, v[254:255]
	s_nop 0
	v_permlane16_swap_b32_e32 v212, v214
	v_permlane16_swap_b32_e32 v213, v215
	s_nop 1
	global_store_dwordx4 v[234:235], v[212:215], off
	s_cbranch_vccz .LBB0_727
	v_cvt_pk_bf16_f32 v46, v74, v75
	v_cvt_pk_bf16_f32 v47, v76, v77
	v_mov_b32_e32 v196, v46
	v_mov_b32_e32 v197, v47
	s_mov_b64 s[36:37], 0
.LBB0_727:
	s_andn2_b64 vcc, exec, s[36:37]
	s_cbranch_vccnz .LBB0_729
	v_mul_f32_e32 v46, 0x3d372713, v74
	v_mul_f32_e32 v46, v74, v46
	v_mov_b32_e32 v47, v74
	v_fmac_f32_e32 v47, v47, v46
	v_mul_f32_e32 v46, 0x3f4c422a, v47
	v_mul_f32_e32 v47, 0x3d372713, v75
	v_mul_f32_e32 v47, v75, v47
	v_mov_b32_e32 v48, v75
	v_fmac_f32_e32 v48, v48, v47
	v_mul_f32_e32 v47, 0x3f4c422a, v48
	v_mul_f32_e32 v48, 0x3d372713, v76
	v_mul_f32_e32 v49, 0x3d372713, v77
	v_mul_f32_e32 v48, v76, v48
	v_mul_f32_e32 v49, v77, v49
	v_fma_f32 v48, v76, v48, v76
	v_fma_f32 v49, v77, v49, v77
	v_mul_f32_e32 v48, 0x3f4c422a, v48
	v_mul_f32_e32 v49, 0x3f4c422a, v49
	v_mul_f32_e32 v46, -2.0, v46
	v_mul_f32_e32 v47, -2.0, v47
	v_mul_f32_e32 v48, -2.0, v48
	v_mul_f32_e32 v49, -2.0, v49
	v_mul_f32_e32 v46, 0x3fb8aa3b, v46
	v_mul_f32_e32 v47, 0x3fb8aa3b, v47
	v_mul_f32_e32 v48, 0x3fb8aa3b, v48
	v_mul_f32_e32 v49, 0x3fb8aa3b, v49
	v_exp_f32_e32 v46, v46
	v_exp_f32_e32 v47, v47
	v_exp_f32_e32 v48, v48
	v_exp_f32_e32 v49, v49
	v_add_f32_e32 v46, 1.0, v46
	v_add_f32_e32 v47, 1.0, v47
	v_add_f32_e32 v48, 1.0, v48
	v_add_f32_e32 v49, 1.0, v49
	v_rcp_f32_e32 v46, v46
	v_rcp_f32_e32 v47, v47
	v_rcp_f32_e32 v48, v48
	v_rcp_f32_e32 v49, v49
	v_pk_mul_f32 v[46:47], v[74:75], v[46:47]
	s_nop 0
	v_cvt_pk_bf16_f32 v46, v46, v47
	v_pk_mul_f32 v[48:49], v[76:77], v[48:49]
	s_nop 0
	v_cvt_pk_bf16_f32 v47, v48, v49
	v_mov_b32_e32 v196, v46
	v_mov_b32_e32 v197, v47
	v_mul_f32_e32 v46, 0x3d372713, v70
	v_mul_f32_e32 v47, 0x3d372713, v71
	v_mul_f32_e32 v48, 0x3d372713, v72
	v_mul_f32_e32 v49, 0x3d372713, v73
	v_mul_f32_e32 v46, v70, v46
	v_mul_f32_e32 v47, v71, v47
	v_mul_f32_e32 v48, v72, v48
	v_mul_f32_e32 v49, v73, v49
	v_fma_f32 v46, v70, v46, v70
	v_fma_f32 v47, v71, v47, v71
	v_fma_f32 v48, v72, v48, v72
	v_fma_f32 v49, v73, v49, v73
	v_mul_f32_e32 v46, 0x3f4c422a, v46
	v_mul_f32_e32 v47, 0x3f4c422a, v47
	v_mul_f32_e32 v48, 0x3f4c422a, v48
	v_mul_f32_e32 v49, 0x3f4c422a, v49
	v_mul_f32_e32 v46, -2.0, v46
	v_mul_f32_e32 v47, -2.0, v47
	v_mul_f32_e32 v48, -2.0, v48
	v_mul_f32_e32 v49, -2.0, v49
	v_mul_f32_e32 v46, 0x3fb8aa3b, v46
	v_mul_f32_e32 v47, 0x3fb8aa3b, v47
	v_mul_f32_e32 v48, 0x3fb8aa3b, v48
	v_mul_f32_e32 v49, 0x3fb8aa3b, v49
	v_exp_f32_e32 v46, v46
	v_exp_f32_e32 v47, v47
	v_exp_f32_e32 v48, v48
	v_exp_f32_e32 v49, v49
	v_add_f32_e32 v46, 1.0, v46
	v_add_f32_e32 v47, 1.0, v47
	v_add_f32_e32 v48, 1.0, v48
	v_add_f32_e32 v49, 1.0, v49
	v_rcp_f32_e32 v46, v46
	v_rcp_f32_e32 v47, v47
	v_rcp_f32_e32 v48, v48
	v_rcp_f32_e32 v49, v49
	v_pk_mul_f32 v[70:71], v[70:71], v[46:47]
	v_pk_mul_f32 v[72:73], v[72:73], v[48:49]
; DEVI float gelu_f(float x) {
;   float u = 0.7978845608028654f * (x + 0.044715f * x * x * x);
;   return x * __builtin_amdgcn_rcpf(1.f + __expf(-2.f * u));
; }
; DEVI void phase2(const Params& p, int l, char* lds) {
;     ...
; #pragma unroll
;     for (int ni = 0; ni < 4; ++ni)
; #pragma unroll
;       for (int mi = 0; mi < 8; ++mi) {
;         f32x4 v = acc[ni][mi];
;         if (do_gelu) { v[0] = gelu_f(v[0]); v[1] = gelu_f(v[1]); v[2] = gelu_f(v[2]); v[3] = gelu_f(v[3]); }
;         int n = n0 + wn * 64 + ni * 16 + fq * 4;
;         int m = m0 + wm * 128 + mi * 16 + fr;
;         store_bf4(proj + (long)m * LDP + n, v);
;       }
.LBB0_729:
	v_cvt_pk_bf16_f32 v46, v70, v71
	v_cvt_pk_bf16_f32 v47, v72, v73
	s_mov_b64 s[36:37], -1
	s_and_b64 vcc, exec, s[0:1]
	v_mov_b32_e32 v198, v46
	v_mov_b32_e32 v199, v47
	s_cbranch_vccz .LBB0_731
	v_cvt_pk_bf16_f32 v46, v66, v67
	v_cvt_pk_bf16_f32 v47, v68, v69
	v_mov_b32_e32 v200, v46
	v_mov_b32_e32 v201, v47
	s_mov_b64 s[36:37], 0
.LBB0_731:
	s_andn2_b64 vcc, exec, s[36:37]
	s_cbranch_vccnz .LBB0_733
	v_mul_f32_e32 v46, 0x3d372713, v66
	v_mul_f32_e32 v47, 0x3d372713, v67
	v_mul_f32_e32 v48, 0x3d372713, v68
	v_mul_f32_e32 v49, 0x3d372713, v69
	v_mul_f32_e32 v46, v66, v46
	v_mul_f32_e32 v47, v67, v47
	v_mul_f32_e32 v48, v68, v48
	v_mul_f32_e32 v49, v69, v49
	v_fma_f32 v46, v66, v46, v66
	v_fma_f32 v47, v67, v47, v67
	v_fma_f32 v48, v68, v48, v68
	v_fma_f32 v49, v69, v49, v69
	v_mul_f32_e32 v46, 0x3f4c422a, v46
	v_mul_f32_e32 v47, 0x3f4c422a, v47
	v_mul_f32_e32 v48, 0x3f4c422a, v48
	v_mul_f32_e32 v49, 0x3f4c422a, v49
	v_mul_f32_e32 v46, -2.0, v46
	v_mul_f32_e32 v47, -2.0, v47
	v_mul_f32_e32 v48, -2.0, v48
	v_mul_f32_e32 v49, -2.0, v49
	v_mul_f32_e32 v46, 0x3fb8aa3b, v46
	v_mul_f32_e32 v47, 0x3fb8aa3b, v47
	v_mul_f32_e32 v48, 0x3fb8aa3b, v48
	v_mul_f32_e32 v49, 0x3fb8aa3b, v49
	v_exp_f32_e32 v46, v46
	v_exp_f32_e32 v47, v47
	v_exp_f32_e32 v48, v48
	v_exp_f32_e32 v49, v49
	v_add_f32_e32 v46, 1.0, v46
	v_add_f32_e32 v47, 1.0, v47
	v_add_f32_e32 v48, 1.0, v48
	v_add_f32_e32 v49, 1.0, v49
	v_rcp_f32_e32 v46, v46
	v_rcp_f32_e32 v47, v47
	v_rcp_f32_e32 v48, v48
	v_rcp_f32_e32 v49, v49
	v_pk_mul_f32 v[46:47], v[66:67], v[46:47]
	s_nop 0
	v_cvt_pk_bf16_f32 v46, v46, v47
	v_pk_mul_f32 v[48:49], v[68:69], v[48:49]
	s_nop 0
	v_cvt_pk_bf16_f32 v47, v48, v49
	v_mov_b32_e32 v200, v46
	v_mov_b32_e32 v201, v47
	v_mul_f32_e32 v46, 0x3d372713, v62
	v_mul_f32_e32 v47, 0x3d372713, v63
	v_mul_f32_e32 v48, 0x3d372713, v64
	v_mul_f32_e32 v49, 0x3d372713, v65
	v_mul_f32_e32 v46, v62, v46
	v_mul_f32_e32 v47, v63, v47
	v_mul_f32_e32 v48, v64, v48
	v_mul_f32_e32 v49, v65, v49
	v_fma_f32 v46, v62, v46, v62
	v_fma_f32 v47, v63, v47, v63
	v_fma_f32 v48, v64, v48, v64
	v_fma_f32 v49, v65, v49, v65
	v_mul_f32_e32 v46, 0x3f4c422a, v46
	v_mul_f32_e32 v47, 0x3f4c422a, v47
	v_mul_f32_e32 v48, 0x3f4c422a, v48
	v_mul_f32_e32 v49, 0x3f4c422a, v49
	v_mul_f32_e32 v46, -2.0, v46
	v_mul_f32_e32 v47, -2.0, v47
	v_mul_f32_e32 v48, -2.0, v48
	v_mul_f32_e32 v49, -2.0, v49
	v_mul_f32_e32 v46, 0x3fb8aa3b, v46
	v_mul_f32_e32 v47, 0x3fb8aa3b, v47
	v_mul_f32_e32 v48, 0x3fb8aa3b, v48
	v_mul_f32_e32 v49, 0x3fb8aa3b, v49
	v_exp_f32_e32 v46, v46
	v_exp_f32_e32 v47, v47
	v_exp_f32_e32 v48, v48
	v_exp_f32_e32 v49, v49
	v_add_f32_e32 v46, 1.0, v46
	v_add_f32_e32 v47, 1.0, v47
	v_add_f32_e32 v48, 1.0, v48
	v_add_f32_e32 v49, 1.0, v49
	v_rcp_f32_e32 v46, v46
	v_rcp_f32_e32 v47, v47
	v_rcp_f32_e32 v48, v48
	v_rcp_f32_e32 v49, v49
	v_pk_mul_f32 v[62:63], v[62:63], v[46:47]
	v_pk_mul_f32 v[64:65], v[64:65], v[48:49]
.LBB0_733:
	v_cvt_pk_bf16_f32 v46, v62, v63
	v_cvt_pk_bf16_f32 v47, v64, v65
	s_mov_b64 s[36:37], -1
	s_and_b64 vcc, exec, s[0:1]
	v_mov_b32_e32 v202, v46
	v_mov_b32_e32 v203, v47
	s_cbranch_vccz .LBB0_735
	v_cvt_pk_bf16_f32 v46, v54, v55
	v_cvt_pk_bf16_f32 v47, v56, v57
	v_mov_b32_e32 v204, v46
	v_mov_b32_e32 v205, v47
	s_mov_b64 s[36:37], 0
.LBB0_735:
	s_andn2_b64 vcc, exec, s[36:37]
	s_cbranch_vccnz .LBB0_737
	v_mul_f32_e32 v46, 0x3d372713, v54
	v_mul_f32_e32 v47, 0x3d372713, v55
	v_mul_f32_e32 v48, 0x3d372713, v56
	v_mul_f32_e32 v49, 0x3d372713, v57
	v_mul_f32_e32 v46, v54, v46
	v_mul_f32_e32 v47, v55, v47
	v_mul_f32_e32 v48, v56, v48
	v_mul_f32_e32 v49, v57, v49
	v_fma_f32 v46, v54, v46, v54
	v_fma_f32 v47, v55, v47, v55
	v_fma_f32 v48, v56, v48, v56
	v_fma_f32 v49, v57, v49, v57
	v_mul_f32_e32 v46, 0x3f4c422a, v46
	v_mul_f32_e32 v47, 0x3f4c422a, v47
	v_mul_f32_e32 v48, 0x3f4c422a, v48
	v_mul_f32_e32 v49, 0x3f4c422a, v49
	v_mul_f32_e32 v46, -2.0, v46
	v_mul_f32_e32 v47, -2.0, v47
	v_mul_f32_e32 v48, -2.0, v48
	v_mul_f32_e32 v49, -2.0, v49
	v_mul_f32_e32 v46, 0x3fb8aa3b, v46
	v_mul_f32_e32 v47, 0x3fb8aa3b, v47
	v_mul_f32_e32 v48, 0x3fb8aa3b, v48
	v_mul_f32_e32 v49, 0x3fb8aa3b, v49
	v_exp_f32_e32 v46, v46
	v_exp_f32_e32 v47, v47
	v_exp_f32_e32 v48, v48
	v_exp_f32_e32 v49, v49
	v_add_f32_e32 v46, 1.0, v46
	v_add_f32_e32 v47, 1.0, v47
	v_add_f32_e32 v48, 1.0, v48
	v_add_f32_e32 v49, 1.0, v49
	v_rcp_f32_e32 v46, v46
	v_rcp_f32_e32 v47, v47
	v_rcp_f32_e32 v48, v48
	v_rcp_f32_e32 v49, v49
	v_pk_mul_f32 v[46:47], v[54:55], v[46:47]
	s_nop 0
	v_cvt_pk_bf16_f32 v46, v46, v47
	v_pk_mul_f32 v[48:49], v[56:57], v[48:49]
	s_nop 0
	v_cvt_pk_bf16_f32 v47, v48, v49
	v_mov_b32_e32 v204, v46
	v_mov_b32_e32 v205, v47
	v_mul_f32_e32 v46, 0x3d372713, v50
	v_mul_f32_e32 v47, 0x3d372713, v51
	v_mul_f32_e32 v48, 0x3d372713, v52
	v_mul_f32_e32 v49, 0x3d372713, v53
	v_mul_f32_e32 v46, v50, v46
	v_mul_f32_e32 v47, v51, v47
	v_mul_f32_e32 v48, v52, v48
	v_mul_f32_e32 v49, v53, v49
	v_fma_f32 v46, v50, v46, v50
	v_fma_f32 v47, v51, v47, v51
	v_fma_f32 v48, v52, v48, v52
	v_fma_f32 v49, v53, v49, v53
	v_mul_f32_e32 v46, 0x3f4c422a, v46
	v_mul_f32_e32 v47, 0x3f4c422a, v47
	v_mul_f32_e32 v48, 0x3f4c422a, v48
	v_mul_f32_e32 v49, 0x3f4c422a, v49
	v_mul_f32_e32 v46, -2.0, v46
	v_mul_f32_e32 v47, -2.0, v47
	v_mul_f32_e32 v48, -2.0, v48
	v_mul_f32_e32 v49, -2.0, v49
	v_mul_f32_e32 v46, 0x3fb8aa3b, v46
	v_mul_f32_e32 v47, 0x3fb8aa3b, v47
	v_mul_f32_e32 v48, 0x3fb8aa3b, v48
	v_mul_f32_e32 v49, 0x3fb8aa3b, v49
	v_exp_f32_e32 v46, v46
	v_exp_f32_e32 v47, v47
	v_exp_f32_e32 v48, v48
	v_exp_f32_e32 v49, v49
	v_add_f32_e32 v46, 1.0, v46
	v_add_f32_e32 v47, 1.0, v47
	v_add_f32_e32 v48, 1.0, v48
	v_add_f32_e32 v49, 1.0, v49
	v_rcp_f32_e32 v46, v46
	v_rcp_f32_e32 v47, v47
	v_rcp_f32_e32 v48, v48
	v_rcp_f32_e32 v49, v49
	v_pk_mul_f32 v[50:51], v[50:51], v[46:47]
	v_pk_mul_f32 v[52:53], v[52:53], v[48:49]
; DEVI float gelu_f(float x) {
;   float u = 0.7978845608028654f * (x + 0.044715f * x * x * x);
;   return x * __builtin_amdgcn_rcpf(1.f + __expf(-2.f * u));
; }
; DEVI void phase2(const Params& p, int l, char* lds) {
;     ...
; #pragma unroll
;     for (int ni = 0; ni < 4; ++ni)
; #pragma unroll
;       for (int mi = 0; mi < 8; ++mi) {
;         f32x4 v = acc[ni][mi];
;         if (do_gelu) { v[0] = gelu_f(v[0]); v[1] = gelu_f(v[1]); v[2] = gelu_f(v[2]); v[3] = gelu_f(v[3]); }
;         int n = n0 + wn * 64 + ni * 16 + fq * 4;
;         int m = m0 + wm * 128 + mi * 16 + fr;
;         store_bf4(proj + (long)m * LDP + n, v);
;       }
.LBB0_737:
	v_cvt_pk_bf16_f32 v46, v50, v51
	v_cvt_pk_bf16_f32 v47, v52, v53
	s_mov_b64 s[36:37], -1
	s_and_b64 vcc, exec, s[0:1]
	v_mov_b32_e32 v206, v46
	v_mov_b32_e32 v207, v47
	s_cbranch_vccz .LBB0_739
	v_cvt_pk_bf16_f32 v46, v22, v23
	v_cvt_pk_bf16_f32 v47, v24, v25
	v_mov_b32_e32 v208, v46
	v_mov_b32_e32 v209, v47
	s_mov_b64 s[36:37], 0
.LBB0_739:
	s_andn2_b64 vcc, exec, s[36:37]
	s_cbranch_vccnz .LBB0_741
	v_mul_f32_e32 v46, 0x3d372713, v22
	v_mul_f32_e32 v47, 0x3d372713, v23
	v_mul_f32_e32 v46, v22, v46
	v_mul_f32_e32 v47, v23, v47
	v_fma_f32 v46, v22, v46, v22
	v_fma_f32 v47, v23, v47, v23
	v_mul_f32_e32 v46, 0x3f4c422a, v46
	v_mul_f32_e32 v47, 0x3f4c422a, v47
	v_mul_f32_e32 v46, -2.0, v46
	v_mul_f32_e32 v47, -2.0, v47
	v_mul_f32_e32 v46, 0x3fb8aa3b, v46
	v_mul_f32_e32 v47, 0x3fb8aa3b, v47
	v_exp_f32_e32 v46, v46
	v_exp_f32_e32 v47, v47
	v_add_f32_e32 v46, 1.0, v46
	v_add_f32_e32 v47, 1.0, v47
	v_rcp_f32_e32 v46, v46
	v_rcp_f32_e32 v47, v47
	s_nop 0
	v_pk_mul_f32 v[22:23], v[22:23], v[46:47]
	v_mul_f32_e32 v46, 0x3d372713, v24
	v_mul_f32_e32 v47, 0x3d372713, v25
	v_mul_f32_e32 v46, v24, v46
	v_mul_f32_e32 v47, v25, v47
	v_fma_f32 v46, v24, v46, v24
	v_fma_f32 v47, v25, v47, v25
	v_mul_f32_e32 v46, 0x3f4c422a, v46
	v_mul_f32_e32 v47, 0x3f4c422a, v47
	v_mul_f32_e32 v46, -2.0, v46
	v_mul_f32_e32 v47, -2.0, v47
	v_mul_f32_e32 v46, 0x3fb8aa3b, v46
	v_mul_f32_e32 v47, 0x3fb8aa3b, v47
	v_exp_f32_e32 v46, v46
	v_exp_f32_e32 v47, v47
	v_cvt_pk_bf16_f32 v22, v22, v23
	v_add_f32_e32 v46, 1.0, v46
	v_add_f32_e32 v47, 1.0, v47
	v_rcp_f32_e32 v46, v46
	v_rcp_f32_e32 v47, v47
	s_nop 0
	v_pk_mul_f32 v[24:25], v[24:25], v[46:47]
	s_nop 0
	v_cvt_pk_bf16_f32 v23, v24, v25
	v_mov_b32_e32 v208, v22
	v_mov_b32_e32 v209, v23
	v_mul_f32_e32 v22, 0x3d372713, v16
	v_mul_f32_e32 v23, 0x3d372713, v17
	v_mul_f32_e32 v24, 0x3d372713, v14
	v_mul_f32_e32 v25, 0x3d372713, v15
	v_mul_f32_e32 v22, v16, v22
	v_mul_f32_e32 v23, v17, v23
	v_mul_f32_e32 v24, v14, v24
	v_mul_f32_e32 v25, v15, v25
	v_fma_f32 v22, v16, v22, v16
	v_fma_f32 v23, v17, v23, v17
	v_fma_f32 v24, v14, v24, v14
	v_fma_f32 v25, v15, v25, v15
	v_mul_f32_e32 v22, 0x3f4c422a, v22
	v_mul_f32_e32 v23, 0x3f4c422a, v23
	v_mul_f32_e32 v24, 0x3f4c422a, v24
	v_mul_f32_e32 v25, 0x3f4c422a, v25
	v_mul_f32_e32 v22, -2.0, v22
	v_mul_f32_e32 v23, -2.0, v23
	v_mul_f32_e32 v24, -2.0, v24
	v_mul_f32_e32 v25, -2.0, v25
	v_mul_f32_e32 v22, 0x3fb8aa3b, v22
	v_mul_f32_e32 v23, 0x3fb8aa3b, v23
	v_mul_f32_e32 v24, 0x3fb8aa3b, v24
	v_mul_f32_e32 v25, 0x3fb8aa3b, v25
	v_exp_f32_e32 v22, v22
	v_exp_f32_e32 v23, v23
	v_exp_f32_e32 v24, v24
	v_exp_f32_e32 v25, v25
	v_add_f32_e32 v22, 1.0, v22
	v_add_f32_e32 v23, 1.0, v23
	v_add_f32_e32 v24, 1.0, v24
	v_add_f32_e32 v25, 1.0, v25
	v_rcp_f32_e32 v22, v22
	v_rcp_f32_e32 v23, v23
	v_rcp_f32_e32 v24, v24
	v_rcp_f32_e32 v25, v25
	v_pk_mul_f32 v[16:17], v[16:17], v[22:23]
	v_pk_mul_f32 v[14:15], v[14:15], v[24:25]
.LBB0_741:
	v_cvt_pk_bf16_f32 v16, v16, v17
	v_cvt_pk_bf16_f32 v17, v14, v15
	s_mov_b64 s[36:37], -1
	s_and_b64 vcc, exec, s[0:1]
	v_mov_b32_e32 v210, v16
	v_mov_b32_e32 v211, v17
	s_cbranch_vccz .LBB0_743
	v_cvt_pk_bf16_f32 v14, v42, v43
	v_cvt_pk_bf16_f32 v15, v44, v45
	v_mov_b32_e32 v218, v14
	v_mov_b32_e32 v219, v15
	v_mov_b32_e32 v216, v196
	v_mov_b32_e32 v217, v197
	v_lshl_add_u64 v[234:235], v[132:133], 0, v[254:255]
	s_nop 0
	v_permlane16_swap_b32_e32 v216, v218
	v_permlane16_swap_b32_e32 v217, v219
	s_nop 1
	global_store_dwordx4 v[234:235], v[216:219], off offset:64
	s_mov_b64 s[36:37], 0
.LBB0_743:
	s_andn2_b64 vcc, exec, s[36:37]
	s_cbranch_vccnz .LBB0_745
	v_mul_f32_e32 v14, 0x3d372713, v42
	v_mul_f32_e32 v15, 0x3d372713, v43
	v_mul_f32_e32 v16, 0x3d372713, v44
	v_mul_f32_e32 v17, 0x3d372713, v45
	v_mul_f32_e32 v14, v42, v14
	v_mul_f32_e32 v15, v43, v15
	v_mul_f32_e32 v16, v44, v16
	v_mul_f32_e32 v17, v45, v17
	v_fma_f32 v14, v42, v14, v42
	v_fma_f32 v15, v43, v15, v43
	v_fma_f32 v16, v44, v16, v44
	v_fma_f32 v17, v45, v17, v45
	v_mul_f32_e32 v14, 0x3f4c422a, v14
	v_mul_f32_e32 v15, 0x3f4c422a, v15
	v_mul_f32_e32 v16, 0x3f4c422a, v16
	v_mul_f32_e32 v17, 0x3f4c422a, v17
	v_mul_f32_e32 v14, -2.0, v14
	v_mul_f32_e32 v15, -2.0, v15
	v_mul_f32_e32 v16, -2.0, v16
	v_mul_f32_e32 v17, -2.0, v17
	v_mul_f32_e32 v14, 0x3fb8aa3b, v14
	v_mul_f32_e32 v15, 0x3fb8aa3b, v15
	v_mul_f32_e32 v16, 0x3fb8aa3b, v16
	v_mul_f32_e32 v17, 0x3fb8aa3b, v17
	v_exp_f32_e32 v14, v14
	v_exp_f32_e32 v15, v15
	v_exp_f32_e32 v16, v16
	v_exp_f32_e32 v17, v17
	v_add_f32_e32 v14, 1.0, v14
	v_add_f32_e32 v15, 1.0, v15
	v_add_f32_e32 v16, 1.0, v16
	v_add_f32_e32 v17, 1.0, v17
	v_rcp_f32_e32 v14, v14
	v_rcp_f32_e32 v15, v15
	v_rcp_f32_e32 v16, v16
	v_rcp_f32_e32 v17, v17
	v_pk_mul_f32 v[14:15], v[42:43], v[14:15]
	s_nop 0
	v_cvt_pk_bf16_f32 v14, v14, v15
	v_pk_mul_f32 v[16:17], v[44:45], v[16:17]
	s_nop 0
	v_cvt_pk_bf16_f32 v15, v16, v17
	v_mov_b32_e32 v214, v14
	v_mov_b32_e32 v215, v15
	v_mov_b32_e32 v212, v196
	v_mov_b32_e32 v213, v197
	v_lshl_add_u64 v[234:235], v[132:133], 0, v[254:255]
	s_nop 0
	v_permlane16_swap_b32_e32 v212, v214
	v_permlane16_swap_b32_e32 v213, v215
	s_nop 1
	global_store_dwordx4 v[234:235], v[212:215], off offset:64
	v_mul_f32_e32 v14, 0x3d372713, v38
	v_mul_f32_e32 v15, 0x3d372713, v39
	v_mul_f32_e32 v16, 0x3d372713, v40
	v_mul_f32_e32 v17, 0x3d372713, v41
	v_mul_f32_e32 v14, v38, v14
	v_mul_f32_e32 v15, v39, v15
	v_mul_f32_e32 v16, v40, v16
	v_mul_f32_e32 v17, v41, v17
	v_fma_f32 v14, v38, v14, v38
	v_fma_f32 v15, v39, v15, v39
	v_fma_f32 v16, v40, v16, v40
	v_fma_f32 v17, v41, v17, v41
	v_mul_f32_e32 v14, 0x3f4c422a, v14
	v_mul_f32_e32 v15, 0x3f4c422a, v15
	v_mul_f32_e32 v16, 0x3f4c422a, v16
	v_mul_f32_e32 v17, 0x3f4c422a, v17
	v_mul_f32_e32 v14, -2.0, v14
	v_mul_f32_e32 v15, -2.0, v15
	v_mul_f32_e32 v16, -2.0, v16
	v_mul_f32_e32 v17, -2.0, v17
	v_mul_f32_e32 v14, 0x3fb8aa3b, v14
	v_mul_f32_e32 v15, 0x3fb8aa3b, v15
	v_mul_f32_e32 v16, 0x3fb8aa3b, v16
	v_mul_f32_e32 v17, 0x3fb8aa3b, v17
	v_exp_f32_e32 v14, v14
	v_exp_f32_e32 v15, v15
	v_exp_f32_e32 v16, v16
	v_exp_f32_e32 v17, v17
	v_add_f32_e32 v14, 1.0, v14
	v_add_f32_e32 v15, 1.0, v15
	v_add_f32_e32 v16, 1.0, v16
	v_add_f32_e32 v17, 1.0, v17
	v_rcp_f32_e32 v14, v14
	v_rcp_f32_e32 v15, v15
	v_rcp_f32_e32 v16, v16
	v_rcp_f32_e32 v17, v17
	v_pk_mul_f32 v[38:39], v[38:39], v[14:15]
	v_pk_mul_f32 v[40:41], v[40:41], v[16:17]
; DEVI float gelu_f(float x) {
;   float u = 0.7978845608028654f * (x + 0.044715f * x * x * x);
;   return x * __builtin_amdgcn_rcpf(1.f + __expf(-2.f * u));
; }
; DEVI void phase2(const Params& p, int l, char* lds) {
;     ...
; #pragma unroll
;     for (int ni = 0; ni < 4; ++ni)
; #pragma unroll
;       for (int mi = 0; mi < 8; ++mi) {
;         f32x4 v = acc[ni][mi];
;         if (do_gelu) { v[0] = gelu_f(v[0]); v[1] = gelu_f(v[1]); v[2] = gelu_f(v[2]); v[3] = gelu_f(v[3]); }
;         int n = n0 + wn * 64 + ni * 16 + fq * 4;
;         int m = m0 + wm * 128 + mi * 16 + fr;
;         store_bf4(proj + (long)m * LDP + n, v);
;       }
.LBB0_745:
	v_cvt_pk_bf16_f32 v14, v38, v39
	v_cvt_pk_bf16_f32 v15, v40, v41
	s_mov_b64 s[36:37], -1
	s_and_b64 vcc, exec, s[0:1]
	v_mov_b32_e32 v218, v14
	v_mov_b32_e32 v219, v15
	v_mov_b32_e32 v216, v198
	v_mov_b32_e32 v217, v199
	v_lshl_add_u64 v[234:235], v[130:131], 0, v[254:255]
	s_nop 0
	v_permlane16_swap_b32_e32 v216, v218
	v_permlane16_swap_b32_e32 v217, v219
	s_nop 1
	global_store_dwordx4 v[234:235], v[216:219], off offset:64
	s_cbranch_vccz .LBB0_747
	v_cvt_pk_bf16_f32 v14, v34, v35
	v_cvt_pk_bf16_f32 v15, v36, v37
	v_mov_b32_e32 v214, v14
	v_mov_b32_e32 v215, v15
	v_mov_b32_e32 v212, v200
	v_mov_b32_e32 v213, v201
	v_lshl_add_u64 v[234:235], v[126:127], 0, v[254:255]
	s_nop 0
	v_permlane16_swap_b32_e32 v212, v214
	v_permlane16_swap_b32_e32 v213, v215
	s_nop 1
	global_store_dwordx4 v[234:235], v[212:215], off offset:64
	s_mov_b64 s[36:37], 0
.LBB0_747:
	s_andn2_b64 vcc, exec, s[36:37]
	s_cbranch_vccnz .LBB0_749
	v_mul_f32_e32 v14, 0x3d372713, v34
	v_mul_f32_e32 v15, 0x3d372713, v35
	v_mul_f32_e32 v16, 0x3d372713, v36
	v_mul_f32_e32 v17, 0x3d372713, v37
	v_mul_f32_e32 v14, v34, v14
	v_mul_f32_e32 v15, v35, v15
	v_mul_f32_e32 v16, v36, v16
	v_mul_f32_e32 v17, v37, v17
	v_fma_f32 v14, v34, v14, v34
	v_fma_f32 v15, v35, v15, v35
	v_fma_f32 v16, v36, v16, v36
	v_fma_f32 v17, v37, v17, v37
	v_mul_f32_e32 v14, 0x3f4c422a, v14
	v_mul_f32_e32 v15, 0x3f4c422a, v15
	v_mul_f32_e32 v16, 0x3f4c422a, v16
	v_mul_f32_e32 v17, 0x3f4c422a, v17
	v_mul_f32_e32 v14, -2.0, v14
	v_mul_f32_e32 v15, -2.0, v15
	v_mul_f32_e32 v16, -2.0, v16
	v_mul_f32_e32 v17, -2.0, v17
	v_mul_f32_e32 v14, 0x3fb8aa3b, v14
	v_mul_f32_e32 v15, 0x3fb8aa3b, v15
	v_mul_f32_e32 v16, 0x3fb8aa3b, v16
	v_mul_f32_e32 v17, 0x3fb8aa3b, v17
	v_exp_f32_e32 v14, v14
	v_exp_f32_e32 v15, v15
	v_exp_f32_e32 v16, v16
	v_exp_f32_e32 v17, v17
	v_add_f32_e32 v14, 1.0, v14
	v_add_f32_e32 v15, 1.0, v15
	v_add_f32_e32 v16, 1.0, v16
	v_add_f32_e32 v17, 1.0, v17
	v_rcp_f32_e32 v14, v14
	v_rcp_f32_e32 v15, v15
	v_rcp_f32_e32 v16, v16
	v_rcp_f32_e32 v17, v17
	v_pk_mul_f32 v[14:15], v[34:35], v[14:15]
	s_nop 0
	v_cvt_pk_bf16_f32 v14, v14, v15
	v_pk_mul_f32 v[16:17], v[36:37], v[16:17]
	s_nop 0
	v_cvt_pk_bf16_f32 v15, v16, v17
	v_mov_b32_e32 v218, v14
	v_mov_b32_e32 v219, v15
	v_mov_b32_e32 v216, v200
	v_mov_b32_e32 v217, v201
	v_lshl_add_u64 v[234:235], v[126:127], 0, v[254:255]
	s_nop 0
	v_permlane16_swap_b32_e32 v216, v218
	v_permlane16_swap_b32_e32 v217, v219
	s_nop 1
	global_store_dwordx4 v[234:235], v[216:219], off offset:64
	v_mul_f32_e32 v14, 0x3d372713, v30
	v_mul_f32_e32 v15, 0x3d372713, v31
	v_mul_f32_e32 v16, 0x3d372713, v32
	v_mul_f32_e32 v17, 0x3d372713, v33
	v_mul_f32_e32 v14, v30, v14
	v_mul_f32_e32 v15, v31, v15
	v_mul_f32_e32 v16, v32, v16
	v_mul_f32_e32 v17, v33, v17
	v_fma_f32 v14, v30, v14, v30
	v_fma_f32 v15, v31, v15, v31
	v_fma_f32 v16, v32, v16, v32
	v_fma_f32 v17, v33, v17, v33
	v_mul_f32_e32 v14, 0x3f4c422a, v14
	v_mul_f32_e32 v15, 0x3f4c422a, v15
	v_mul_f32_e32 v16, 0x3f4c422a, v16
	v_mul_f32_e32 v17, 0x3f4c422a, v17
	v_mul_f32_e32 v14, -2.0, v14
	v_mul_f32_e32 v15, -2.0, v15
	v_mul_f32_e32 v16, -2.0, v16
	v_mul_f32_e32 v17, -2.0, v17
	v_mul_f32_e32 v14, 0x3fb8aa3b, v14
	v_mul_f32_e32 v15, 0x3fb8aa3b, v15
	v_mul_f32_e32 v16, 0x3fb8aa3b, v16
	v_mul_f32_e32 v17, 0x3fb8aa3b, v17
	v_exp_f32_e32 v14, v14
	v_exp_f32_e32 v15, v15
	v_exp_f32_e32 v16, v16
	v_exp_f32_e32 v17, v17
	v_add_f32_e32 v14, 1.0, v14
	v_add_f32_e32 v15, 1.0, v15
	v_add_f32_e32 v16, 1.0, v16
	v_add_f32_e32 v17, 1.0, v17
	v_rcp_f32_e32 v14, v14
	v_rcp_f32_e32 v15, v15
	v_rcp_f32_e32 v16, v16
	v_rcp_f32_e32 v17, v17
	v_pk_mul_f32 v[30:31], v[30:31], v[14:15]
	v_pk_mul_f32 v[32:33], v[32:33], v[16:17]
.LBB0_749:
	v_cvt_pk_bf16_f32 v14, v30, v31
	v_cvt_pk_bf16_f32 v15, v32, v33
	s_mov_b64 s[36:37], -1
	s_and_b64 vcc, exec, s[0:1]
	v_mov_b32_e32 v214, v14
	v_mov_b32_e32 v215, v15
	v_mov_b32_e32 v212, v202
	v_mov_b32_e32 v213, v203
	v_lshl_add_u64 v[234:235], v[122:123], 0, v[254:255]
	s_nop 0
	v_permlane16_swap_b32_e32 v212, v214
	v_permlane16_swap_b32_e32 v213, v215
	s_nop 1
	global_store_dwordx4 v[234:235], v[212:215], off offset:64
	s_cbranch_vccz .LBB0_751
	v_cvt_pk_bf16_f32 v14, v26, v27
	v_cvt_pk_bf16_f32 v15, v28, v29
	v_mov_b32_e32 v218, v14
	v_mov_b32_e32 v219, v15
	v_mov_b32_e32 v216, v204
	v_mov_b32_e32 v217, v205
	v_lshl_add_u64 v[234:235], v[118:119], 0, v[254:255]
	s_nop 0
	v_permlane16_swap_b32_e32 v216, v218
	v_permlane16_swap_b32_e32 v217, v219
	s_nop 1
	global_store_dwordx4 v[234:235], v[216:219], off offset:64
	s_mov_b64 s[36:37], 0
; DEVI float gelu_f(float x) {
;   float u = 0.7978845608028654f * (x + 0.044715f * x * x * x);
;   return x * __builtin_amdgcn_rcpf(1.f + __expf(-2.f * u));
; }
; DEVI void phase2(const Params& p, int l, char* lds) {
;     ...
; #pragma unroll
;     for (int ni = 0; ni < 4; ++ni)
; #pragma unroll
;       for (int mi = 0; mi < 8; ++mi) {
;         f32x4 v = acc[ni][mi];
;         if (do_gelu) { v[0] = gelu_f(v[0]); v[1] = gelu_f(v[1]); v[2] = gelu_f(v[2]); v[3] = gelu_f(v[3]); }
;         int n = n0 + wn * 64 + ni * 16 + fq * 4;
;         int m = m0 + wm * 128 + mi * 16 + fr;
;         store_bf4(proj + (long)m * LDP + n, v);
;       }
.LBB0_751:
	s_andn2_b64 vcc, exec, s[36:37]
	s_cbranch_vccnz .LBB0_753
	v_mul_f32_e32 v14, 0x3d372713, v26
	v_mul_f32_e32 v15, 0x3d372713, v27
	v_mul_f32_e32 v16, 0x3d372713, v28
	v_mul_f32_e32 v17, 0x3d372713, v29
	v_mul_f32_e32 v14, v26, v14
	v_mul_f32_e32 v15, v27, v15
	v_mul_f32_e32 v16, v28, v16
	v_mul_f32_e32 v17, v29, v17
	v_fma_f32 v14, v26, v14, v26
	v_fma_f32 v15, v27, v15, v27
	v_fma_f32 v16, v28, v16, v28
	v_fma_f32 v17, v29, v17, v29
	v_mul_f32_e32 v14, 0x3f4c422a, v14
	v_mul_f32_e32 v15, 0x3f4c422a, v15
	v_mul_f32_e32 v16, 0x3f4c422a, v16
	v_mul_f32_e32 v17, 0x3f4c422a, v17
	v_mul_f32_e32 v14, -2.0, v14
	v_mul_f32_e32 v15, -2.0, v15
	v_mul_f32_e32 v16, -2.0, v16
	v_mul_f32_e32 v17, -2.0, v17
	v_mul_f32_e32 v14, 0x3fb8aa3b, v14
	v_mul_f32_e32 v15, 0x3fb8aa3b, v15
	v_mul_f32_e32 v16, 0x3fb8aa3b, v16
	v_mul_f32_e32 v17, 0x3fb8aa3b, v17
	v_exp_f32_e32 v14, v14
	v_exp_f32_e32 v15, v15
	v_exp_f32_e32 v16, v16
	v_exp_f32_e32 v17, v17
	v_add_f32_e32 v14, 1.0, v14
	v_add_f32_e32 v15, 1.0, v15
	v_add_f32_e32 v16, 1.0, v16
	v_add_f32_e32 v17, 1.0, v17
	v_rcp_f32_e32 v14, v14
	v_rcp_f32_e32 v15, v15
	v_rcp_f32_e32 v16, v16
	v_rcp_f32_e32 v17, v17
	v_pk_mul_f32 v[14:15], v[26:27], v[14:15]
	s_nop 0
	v_cvt_pk_bf16_f32 v14, v14, v15
	v_pk_mul_f32 v[16:17], v[28:29], v[16:17]
	s_nop 0
	v_cvt_pk_bf16_f32 v15, v16, v17
	v_mov_b32_e32 v214, v14
	v_mov_b32_e32 v215, v15
	v_mov_b32_e32 v212, v204
	v_mov_b32_e32 v213, v205
	v_lshl_add_u64 v[234:235], v[118:119], 0, v[254:255]
	s_nop 0
	v_permlane16_swap_b32_e32 v212, v214
	v_permlane16_swap_b32_e32 v213, v215
	s_nop 1
	global_store_dwordx4 v[234:235], v[212:215], off offset:64
	v_mul_f32_e32 v14, 0x3d372713, v18
	v_mul_f32_e32 v15, 0x3d372713, v19
	v_mul_f32_e32 v16, 0x3d372713, v20
	v_mul_f32_e32 v17, 0x3d372713, v21
	v_mul_f32_e32 v14, v18, v14
	v_mul_f32_e32 v15, v19, v15
	v_mul_f32_e32 v16, v20, v16
	v_mul_f32_e32 v17, v21, v17
	v_fma_f32 v14, v18, v14, v18
	v_fma_f32 v15, v19, v15, v19
	v_fma_f32 v16, v20, v16, v20
	v_fma_f32 v17, v21, v17, v21
	v_mul_f32_e32 v14, 0x3f4c422a, v14
	v_mul_f32_e32 v15, 0x3f4c422a, v15
	v_mul_f32_e32 v16, 0x3f4c422a, v16
	v_mul_f32_e32 v17, 0x3f4c422a, v17
	v_mul_f32_e32 v14, -2.0, v14
	v_mul_f32_e32 v15, -2.0, v15
	v_mul_f32_e32 v16, -2.0, v16
	v_mul_f32_e32 v17, -2.0, v17
	v_mul_f32_e32 v14, 0x3fb8aa3b, v14
	v_mul_f32_e32 v15, 0x3fb8aa3b, v15
	v_mul_f32_e32 v16, 0x3fb8aa3b, v16
	v_mul_f32_e32 v17, 0x3fb8aa3b, v17
	v_exp_f32_e32 v14, v14
	v_exp_f32_e32 v15, v15
	v_exp_f32_e32 v16, v16
	v_exp_f32_e32 v17, v17
	v_add_f32_e32 v14, 1.0, v14
	v_add_f32_e32 v15, 1.0, v15
	v_add_f32_e32 v16, 1.0, v16
	v_add_f32_e32 v17, 1.0, v17
	v_rcp_f32_e32 v14, v14
	v_rcp_f32_e32 v15, v15
	v_rcp_f32_e32 v16, v16
	v_rcp_f32_e32 v17, v17
	v_pk_mul_f32 v[18:19], v[18:19], v[14:15]
	v_pk_mul_f32 v[20:21], v[20:21], v[16:17]
.LBB0_753:
	v_cvt_pk_bf16_f32 v14, v18, v19
	v_cvt_pk_bf16_f32 v15, v20, v21
	s_mov_b64 s[36:37], -1
	s_and_b64 vcc, exec, s[0:1]
	v_mov_b32_e32 v218, v14
	v_mov_b32_e32 v219, v15
	v_mov_b32_e32 v216, v206
	v_mov_b32_e32 v217, v207
	v_lshl_add_u64 v[234:235], v[112:113], 0, v[254:255]
	s_nop 0
	v_permlane16_swap_b32_e32 v216, v218
	v_permlane16_swap_b32_e32 v217, v219
	s_nop 1
	global_store_dwordx4 v[234:235], v[216:219], off offset:64
	s_cbranch_vccz .LBB0_755
	v_cvt_pk_bf16_f32 v14, v10, v11
	v_cvt_pk_bf16_f32 v15, v12, v13
	v_mov_b32_e32 v214, v14
	v_mov_b32_e32 v215, v15
	v_mov_b32_e32 v212, v208
	v_mov_b32_e32 v213, v209
	v_lshl_add_u64 v[234:235], v[4:5], 0, v[254:255]
	s_nop 0
	v_permlane16_swap_b32_e32 v212, v214
	v_permlane16_swap_b32_e32 v213, v215
	s_nop 1
	global_store_dwordx4 v[234:235], v[212:215], off offset:64
	s_mov_b64 s[36:37], 0
.LBB0_755:
	s_andn2_b64 vcc, exec, s[36:37]
	s_cbranch_vccnz .LBB0_675
	v_mul_f32_e32 v14, 0x3d372713, v10
	v_mul_f32_e32 v15, 0x3d372713, v11
	v_mul_f32_e32 v14, v10, v14
	v_mul_f32_e32 v15, v11, v15
	v_fma_f32 v14, v10, v14, v10
	v_fma_f32 v15, v11, v15, v11
	v_mul_f32_e32 v14, 0x3f4c422a, v14
	v_mul_f32_e32 v15, 0x3f4c422a, v15
	v_mul_f32_e32 v14, -2.0, v14
	v_mul_f32_e32 v15, -2.0, v15
	v_mul_f32_e32 v14, 0x3fb8aa3b, v14
	v_mul_f32_e32 v15, 0x3fb8aa3b, v15
	v_exp_f32_e32 v14, v14
	v_exp_f32_e32 v15, v15
	v_add_f32_e32 v14, 1.0, v14
	v_add_f32_e32 v15, 1.0, v15
	v_rcp_f32_e32 v14, v14
	v_rcp_f32_e32 v15, v15
	s_nop 0
	v_pk_mul_f32 v[10:11], v[10:11], v[14:15]
	v_mul_f32_e32 v14, 0x3d372713, v12
	v_mul_f32_e32 v15, 0x3d372713, v13
	v_mul_f32_e32 v14, v12, v14
	v_mul_f32_e32 v15, v13, v15
	v_fma_f32 v14, v12, v14, v12
	v_fma_f32 v15, v13, v15, v13
	v_mul_f32_e32 v14, 0x3f4c422a, v14
	v_mul_f32_e32 v15, 0x3f4c422a, v15
	v_mul_f32_e32 v14, -2.0, v14
	v_mul_f32_e32 v15, -2.0, v15
	v_mul_f32_e32 v14, 0x3fb8aa3b, v14
	v_mul_f32_e32 v15, 0x3fb8aa3b, v15
	v_exp_f32_e32 v14, v14
	v_exp_f32_e32 v15, v15
	v_cvt_pk_bf16_f32 v10, v10, v11
	v_add_f32_e32 v14, 1.0, v14
	v_add_f32_e32 v15, 1.0, v15
	v_rcp_f32_e32 v14, v14
	v_rcp_f32_e32 v15, v15
	s_nop 0
	v_pk_mul_f32 v[12:13], v[12:13], v[14:15]
	s_nop 0
	v_cvt_pk_bf16_f32 v11, v12, v13
	v_mov_b32_e32 v218, v10
	v_mov_b32_e32 v219, v11
	v_mov_b32_e32 v216, v208
	v_mov_b32_e32 v217, v209
	v_lshl_add_u64 v[234:235], v[4:5], 0, v[254:255]
	s_nop 0
	v_permlane16_swap_b32_e32 v216, v218
	v_permlane16_swap_b32_e32 v217, v219
	s_nop 1
	global_store_dwordx4 v[234:235], v[216:219], off offset:64
	v_mul_f32_e32 v4, 0x3d372713, v8
	v_mul_f32_e32 v5, 0x3d372713, v9
	v_mul_f32_e32 v10, 0x3d372713, v6
	v_mul_f32_e32 v11, 0x3d372713, v7
	v_mul_f32_e32 v4, v8, v4
	v_mul_f32_e32 v5, v9, v5
	v_mul_f32_e32 v10, v6, v10
	v_mul_f32_e32 v11, v7, v11
	v_fma_f32 v4, v8, v4, v8
	v_fma_f32 v5, v9, v5, v9
	v_fma_f32 v10, v6, v10, v6
	v_fma_f32 v11, v7, v11, v7
	v_mul_f32_e32 v4, 0x3f4c422a, v4
	v_mul_f32_e32 v5, 0x3f4c422a, v5
	v_mul_f32_e32 v10, 0x3f4c422a, v10
	v_mul_f32_e32 v11, 0x3f4c422a, v11
	v_mul_f32_e32 v4, -2.0, v4
	v_mul_f32_e32 v5, -2.0, v5
	v_mul_f32_e32 v10, -2.0, v10
	v_mul_f32_e32 v11, -2.0, v11
	v_mul_f32_e32 v4, 0x3fb8aa3b, v4
	v_mul_f32_e32 v5, 0x3fb8aa3b, v5
	v_mul_f32_e32 v10, 0x3fb8aa3b, v10
	v_mul_f32_e32 v11, 0x3fb8aa3b, v11
	v_exp_f32_e32 v4, v4
	v_exp_f32_e32 v5, v5
	v_exp_f32_e32 v10, v10
	v_exp_f32_e32 v11, v11
	v_add_f32_e32 v4, 1.0, v4
	v_add_f32_e32 v5, 1.0, v5
	v_add_f32_e32 v10, 1.0, v10
	v_add_f32_e32 v11, 1.0, v11
	v_rcp_f32_e32 v4, v4
	v_rcp_f32_e32 v5, v5
	v_rcp_f32_e32 v10, v10
	v_rcp_f32_e32 v11, v11
	v_pk_mul_f32 v[8:9], v[8:9], v[4:5]
	v_pk_mul_f32 v[6:7], v[6:7], v[10:11]
	s_branch .LBB0_675
